# GEMM first K-iteration peeled with srcC=0, no accumulator zeroing (without rsqrt edit)
# speedup vs baseline: 1.0927x; 1.0098x over previous
; #define PG8_STAGE(bufoff, gbase, voff) do { _Pragma("unroll") for (int _i = 0; _i < 2; ++_i) \
;         __builtin_amdgcn_global_load_lds((const unsigned*)((const char*)(gbase) + (voff)[_i]), (LAS unsigned*)(lds + (bufoff) + ldsw + _i * 8192), 16, 0, 0); } while (0)
; #define PG8_LDA(dst, b, h) do { _Pragma("unroll") for (int m = 0; m < 4; ++m) _Pragma("unroll") for (int k = 0; k < 2; ++k) dst[m][k] = *(const LAS bf16x8*)(lds + PG8_SA(b, h) + aoff + m * 2048 + k * 1024); } while (0)
; #define PG8_LDB(dst, b, h) do { _Pragma("unroll") for (int n = 0; n < 2; ++n) _Pragma("unroll") for (int k = 0; k < 2; ++k) dst[n][k] = *(const LAS bf16x8*)(lds + PG8_SB(b, h) + boff + n * 2048 + k * 1024); } while (0)
; #define PG8_WAIT_V(n) asm volatile("s_waitcnt vmcnt(" #n ")" ::: "memory")
; #define PG8_BAR __builtin_amdgcn_s_barrier()
; template <class Epi, bool ALIGN_EPI>
; __device__ __forceinline__ void gemm_phase(LAS unsigned char* lds, const Gemm g, const StaticOrder& S, const Epi& E) {
;     ...
;         const bool has_next = S.next(ui + 1, nxt);
;         const char* nA = has_next ? (const char*)g.A + (size_t)nxt.pm * tstep : cA; const char* nB = has_next ? (const char*)g.Bt + (size_t)nxt.pn * tstep : cB;
;         for (int t = 0; t < nt; t += 2) {
;             const bool last = (t == nt - 2);
;             const char* a1 = cA + (size_t)(t + 1) * kstep;
;             const char* a2 = last ? nA : cA + (size_t)(t + 2) * kstep; const char* b2 = last ? nB : cB + (size_t)(t + 2) * kstep;
;             const char* a3 = a2 + kstep; const char* b3 = b2 + kstep;
;             PG8_LDB(B0, 0, 0); PG8_LDB(B1, 0, 1); PG8_SCHED; PG8_LDA(At, 0, 0); PG8_STAGE(PG8_SA(1, 1), a1 + hstep, voffA);
;             PG8_WAIT_V(8); PG8_WAIT_L(0); PG8_BAR; PG8_MMA(0, 0, At, B0); PG8_MMA(0, 1, At, B1); PG8_BAR; PG8_SCHED;
;             PG8_LDA(At, 0, 1); PG8_STAGE(PG8_SB(0, 0), b2, voffB); PG8_STAGE(PG8_SB(0, 1), b2 + hstep, voffB); PG8_STAGE(PG8_SA(0, 0), a2, voffA);
;             PG8_WAIT_V(8); PG8_WAIT_L(0); PG8_BAR; PG8_MMA(1, 0, At, B0); PG8_MMA(1, 1, At, B1); PG8_BAR; PG8_SCHED;
;     ...
; #pragma unroll
;         for (int a = 0; a < 2; ++a)
; #pragma unroll
;             for (int b = 0; b < 2; ++b)
; #pragma unroll
;                 for (int m = 0; m < 4; ++m)
; #pragma unroll
;                     for (int n = 0; n < 2; ++n) acc[a][b][m][n] = (f32x4){0.f, 0.f, 0.f, 0.f};
.LBB0_292:
	s_ashr_i32 s69, s68, 31
	s_lshl_b64 s[8:9], s[68:69], 19
	s_add_u32 s70, s34, s8
	s_addc_u32 s71, s35, s9
	s_and_b64 s[8:9], s[0:1], exec
	s_cselect_b32 s5, s71, s81
	s_cselect_b32 s69, s70, s80
	s_ashr_i32 s67, s66, 31
	s_lshl_b64 s[8:9], s[66:67], 19
	s_add_u32 s72, s26, s8
	s_addc_u32 s73, s27, s9
	s_and_b64 s[8:9], s[0:1], exec
	s_cselect_b32 s67, s73, s83
	s_cselect_b32 s79, s72, s82
	s_add_u32 s80, s80, 0x40080
	s_addc_u32 s81, s81, 0
	s_add_u32 vcc_lo, s82, 0x100
	s_addc_u32 vcc_hi, s83, 0
	s_mov_b32 s8, -2
	ds_read_b128 v[148:151], v192
	ds_read_b128 v[152:155], v192 offset:1024
	ds_read_b128 v[156:159], v192 offset:2048
	ds_read_b128 v[160:163], v192 offset:3072
	ds_read_b128 v[164:167], v193
	ds_read_b128 v[168:171], v193 offset:1024
	ds_read_b128 v[172:175], v193 offset:2048
	ds_read_b128 v[176:179], v193 offset:3072
	s_add_u32 s9, s80, 0xfffc0080
	s_addc_u32 s50, s81, -1
	s_cmp_eq_u32 s8, 12
	s_cselect_b32 s85, s5, s50
	s_cselect_b32 s84, s69, s9
	s_cselect_b32 s83, s67, vcc_hi
	s_cselect_b32 s82, s79, vcc_lo
	v_lshl_add_u64 v[224:225], s[80:81], 0, v[140:141]
	s_add_i32 m0, s76, 0xc000
	ds_read_b128 v[180:183], v194
	ds_read_b128 v[196:199], v194 offset:1024
	ds_read_b128 v[200:203], v194 offset:2048
	ds_read_b128 v[204:207], v194 offset:3072
	ds_read_b128 v[208:211], v194 offset:4096
	ds_read_b128 v[212:215], v194 offset:5120
	ds_read_b128 v[216:219], v194 offset:6144
	ds_read_b128 v[220:223], v194 offset:7168
	global_load_lds_dwordx4 v[224:225], off
	v_lshl_add_u64 v[224:225], s[80:81], 0, v[142:143]
	s_add_i32 m0, s76, 0xe000
	s_nop 0
	global_load_lds_dwordx4 v[224:225], off
	s_waitcnt vmcnt(8)
	s_waitcnt lgkmcnt(0)
	s_barrier
	s_setprio 3
	s_waitcnt lgkmcnt(0)
	v_mfma_f32_16x16x32_bf16 v[118:121], v[148:151], v[180:183], 0
	v_mfma_f32_16x16x32_bf16 v[114:117], v[156:159], v[180:183], 0
	v_mfma_f32_16x16x32_bf16 v[102:105], v[148:151], v[200:203], 0
	v_mfma_f32_16x16x32_bf16 v[98:101], v[156:159], v[200:203], 0
	v_mfma_f32_16x16x32_bf16 v[86:89], v[148:151], v[208:211], 0
	v_mfma_f32_16x16x32_bf16 v[82:85], v[156:159], v[208:211], 0
	v_mfma_f32_16x16x32_bf16 v[70:73], v[148:151], v[216:219], 0
	v_mfma_f32_16x16x32_bf16 v[66:69], v[156:159], v[216:219], 0
	v_mfma_f32_16x16x32_bf16 v[118:121], v[152:155], v[196:199], v[118:121]
	v_mfma_f32_16x16x32_bf16 v[114:117], v[160:163], v[196:199], v[114:117]
	v_mfma_f32_16x16x32_bf16 v[102:105], v[152:155], v[204:207], v[102:105]
	v_mfma_f32_16x16x32_bf16 v[98:101], v[160:163], v[204:207], v[98:101]
	v_mfma_f32_16x16x32_bf16 v[86:89], v[152:155], v[212:215], v[86:89]
	v_mfma_f32_16x16x32_bf16 v[82:85], v[160:163], v[212:215], v[82:85]
	v_mfma_f32_16x16x32_bf16 v[70:73], v[152:155], v[220:223], v[70:73]
	v_mfma_f32_16x16x32_bf16 v[66:69], v[160:163], v[220:223], v[66:69]
	s_setprio 0
	s_setprio 3
	v_mfma_f32_16x16x32_bf16 v[126:129], v[164:167], v[180:183], 0
	v_mfma_f32_16x16x32_bf16 v[122:125], v[172:175], v[180:183], 0
	v_mfma_f32_16x16x32_bf16 v[110:113], v[164:167], v[200:203], 0
	v_mfma_f32_16x16x32_bf16 v[106:109], v[172:175], v[200:203], 0
	v_mfma_f32_16x16x32_bf16 v[94:97], v[164:167], v[208:211], 0
	v_mfma_f32_16x16x32_bf16 v[90:93], v[172:175], v[208:211], 0
	v_mfma_f32_16x16x32_bf16 v[78:81], v[164:167], v[216:219], 0
	v_mfma_f32_16x16x32_bf16 v[74:77], v[172:175], v[216:219], 0
	v_mfma_f32_16x16x32_bf16 v[126:129], v[168:171], v[196:199], v[126:129]
	v_mfma_f32_16x16x32_bf16 v[122:125], v[176:179], v[196:199], v[122:125]
	v_mfma_f32_16x16x32_bf16 v[110:113], v[168:171], v[204:207], v[110:113]
	v_mfma_f32_16x16x32_bf16 v[106:109], v[176:179], v[204:207], v[106:109]
	v_mfma_f32_16x16x32_bf16 v[94:97], v[168:171], v[212:215], v[94:97]
	v_mfma_f32_16x16x32_bf16 v[90:93], v[176:179], v[212:215], v[90:93]
	v_mfma_f32_16x16x32_bf16 v[78:81], v[168:171], v[220:223], v[78:81]
	v_mfma_f32_16x16x32_bf16 v[74:77], v[176:179], v[220:223], v[74:77]
	s_setprio 0
	s_barrier
	s_add_i32 s9, s95, s33
	v_lshl_add_u64 v[224:225], s[82:83], 0, v[132:133]
	s_mov_b32 m0, s9
	ds_read_b128 v[180:183], v194 offset:16384
	ds_read_b128 v[196:199], v194 offset:17408
	ds_read_b128 v[200:203], v194 offset:18432
	ds_read_b128 v[204:207], v194 offset:19456
	ds_read_b128 v[208:211], v194 offset:20480
	ds_read_b128 v[212:215], v194 offset:21504
	ds_read_b128 v[216:219], v194 offset:22528
	ds_read_b128 v[220:223], v194 offset:23552
	global_load_lds_dwordx4 v[224:225], off
	s_add_i32 m0, s9, 0x2000
	s_add_u32 s50, s82, 0x40000
	v_lshl_add_u64 v[226:227], s[82:83], 0, v[136:137]
	s_addc_u32 s51, s83, 0
	s_add_i32 s9, s96, s33
	global_load_lds_dwordx4 v[226:227], off
	v_lshl_add_u64 v[228:229], s[50:51], 0, v[132:133]
	s_mov_b32 m0, s9
	v_lshl_add_u64 v[230:231], s[84:85], 0, v[134:135]
	global_load_lds_dwordx4 v[228:229], off
	v_lshl_add_u64 v[228:229], s[50:51], 0, v[136:137]
	s_add_i32 m0, s9, 0x2000
	s_nop 0
	global_load_lds_dwordx4 v[228:229], off
	v_lshl_add_u64 v[228:229], s[84:85], 0, v[130:131]
	s_mov_b32 m0, s76
	s_nop 0
	global_load_lds_dwordx4 v[228:229], off
	s_mov_b32 m0, s77
	s_nop 0
	global_load_lds_dwordx4 v[230:231], off
	s_waitcnt vmcnt(8)
	s_waitcnt lgkmcnt(0)
	s_barrier
; #define PG8_STAGE(bufoff, gbase, voff) do { _Pragma("unroll") for (int _i = 0; _i < 2; ++_i) \
;         __builtin_amdgcn_global_load_lds((const unsigned*)((const char*)(gbase) + (voff)[_i]), (LAS unsigned*)(lds + (bufoff) + ldsw + _i * 8192), 16, 0, 0); } while (0)
; #define PG8_LDA(dst, b, h) do { _Pragma("unroll") for (int m = 0; m < 4; ++m) _Pragma("unroll") for (int k = 0; k < 2; ++k) dst[m][k] = *(const LAS bf16x8*)(lds + PG8_SA(b, h) + aoff + m * 2048 + k * 1024); } while (0)
; #define PG8_LDB(dst, b, h) do { _Pragma("unroll") for (int n = 0; n < 2; ++n) _Pragma("unroll") for (int k = 0; k < 2; ++k) dst[n][k] = *(const LAS bf16x8*)(lds + PG8_SB(b, h) + boff + n * 2048 + k * 1024); } while (0)
; #define PG8_MMA(ai, bj, At, Bt) do { __builtin_amdgcn_s_setprio(3); _Pragma("unroll") for (int m = 0; m < 4; ++m) _Pragma("unroll") for (int n = 0; n < 2; ++n) _Pragma("unroll") for (int k = 0; k < 2; ++k) \
;         acc[ai][bj][m][n] = __builtin_amdgcn_mfma_f32_16x16x32_bf16(Bt[n][k], At[m][k], acc[ai][bj][m][n], 0, 0, 0); __builtin_amdgcn_s_setprio(0); } while (0)
; #define PG8_WAIT_V(n) asm volatile("s_waitcnt vmcnt(" #n ")" ::: "memory")
; #define PG8_WAIT_L(n) asm volatile("s_waitcnt lgkmcnt(" #n ")" ::: "memory")
; #define PG8_BAR __builtin_amdgcn_s_barrier()
; #define PG8_SCHED __builtin_amdgcn_sched_barrier(0)
; template <class Epi, bool ALIGN_EPI>
; __device__ __forceinline__ void gemm_phase(LAS unsigned char* lds, const Gemm g, const StaticOrder& S, const Epi& E) {
;     ...
;             PG8_WAIT_V(8); PG8_WAIT_L(0); PG8_BAR; PG8_MMA(1, 0, At, B0); PG8_MMA(1, 1, At, B1); PG8_BAR; PG8_SCHED;
;             PG8_LDB(B0, 1, 0); PG8_LDB(B1, 1, 1); PG8_SCHED; PG8_LDA(At, 1, 0); PG8_STAGE(PG8_SA(0, 1), a2 + hstep, voffA);
;             PG8_WAIT_V(8); PG8_WAIT_L(0); PG8_BAR; PG8_MMA(0, 0, At, B0); PG8_MMA(0, 1, At, B1); PG8_BAR; PG8_SCHED;
	s_setprio 3
	s_waitcnt lgkmcnt(0)
	v_mfma_f32_16x16x32_bf16 v[54:57], v[148:151], v[180:183], 0
	v_mfma_f32_16x16x32_bf16 v[50:53], v[156:159], v[180:183], 0
	v_mfma_f32_16x16x32_bf16 v[38:41], v[148:151], v[200:203], 0
	v_mfma_f32_16x16x32_bf16 v[34:37], v[156:159], v[200:203], 0
	v_mfma_f32_16x16x32_bf16 v[22:25], v[148:151], v[208:211], 0
	v_mfma_f32_16x16x32_bf16 v[18:21], v[156:159], v[208:211], 0
	v_mfma_f32_16x16x32_bf16 v[6:9], v[148:151], v[216:219], 0
	v_mfma_f32_16x16x32_bf16 v[2:5], v[156:159], v[216:219], 0
	v_mfma_f32_16x16x32_bf16 v[54:57], v[152:155], v[196:199], v[54:57]
	v_mfma_f32_16x16x32_bf16 v[50:53], v[160:163], v[196:199], v[50:53]
	v_mfma_f32_16x16x32_bf16 v[38:41], v[152:155], v[204:207], v[38:41]
	v_mfma_f32_16x16x32_bf16 v[34:37], v[160:163], v[204:207], v[34:37]
	v_mfma_f32_16x16x32_bf16 v[22:25], v[152:155], v[212:215], v[22:25]
	v_mfma_f32_16x16x32_bf16 v[18:21], v[160:163], v[212:215], v[18:21]
	v_mfma_f32_16x16x32_bf16 v[6:9], v[152:155], v[220:223], v[6:9]
	v_mfma_f32_16x16x32_bf16 v[2:5], v[160:163], v[220:223], v[2:5]
	s_setprio 0
	s_setprio 3
	v_mfma_f32_16x16x32_bf16 v[62:65], v[164:167], v[180:183], 0
	v_mfma_f32_16x16x32_bf16 v[58:61], v[172:175], v[180:183], 0
	v_mfma_f32_16x16x32_bf16 v[46:49], v[164:167], v[200:203], 0
	v_mfma_f32_16x16x32_bf16 v[42:45], v[172:175], v[200:203], 0
	v_mfma_f32_16x16x32_bf16 v[30:33], v[164:167], v[208:211], 0
	v_mfma_f32_16x16x32_bf16 v[26:29], v[172:175], v[208:211], 0
	v_mfma_f32_16x16x32_bf16 v[14:17], v[164:167], v[216:219], 0
	v_mfma_f32_16x16x32_bf16 v[10:13], v[172:175], v[216:219], 0
	v_mfma_f32_16x16x32_bf16 v[62:65], v[168:171], v[196:199], v[62:65]
	v_mfma_f32_16x16x32_bf16 v[58:61], v[176:179], v[196:199], v[58:61]
	v_mfma_f32_16x16x32_bf16 v[46:49], v[168:171], v[204:207], v[46:49]
	v_mfma_f32_16x16x32_bf16 v[42:45], v[176:179], v[204:207], v[42:45]
	v_mfma_f32_16x16x32_bf16 v[30:33], v[168:171], v[212:215], v[30:33]
	v_mfma_f32_16x16x32_bf16 v[26:29], v[176:179], v[212:215], v[26:29]
	v_mfma_f32_16x16x32_bf16 v[14:17], v[168:171], v[220:223], v[14:17]
	v_mfma_f32_16x16x32_bf16 v[10:13], v[176:179], v[220:223], v[10:13]
	s_setprio 0
	s_barrier
	s_add_i32 s9, 0, 0x18000
	v_add_u32_e32 v138, s9, v189
	s_add_i32 s89, 0, 0x1c000
	ds_read_b128 v[148:151], v138
	ds_read_b128 v[152:155], v138 offset:1024
	ds_read_b128 v[156:159], v138 offset:2048
	ds_read_b128 v[160:163], v138 offset:3072
	v_add_u32_e32 v138, s89, v189
	ds_read_b128 v[164:167], v138
	ds_read_b128 v[168:171], v138 offset:1024
	ds_read_b128 v[172:175], v138 offset:2048
	ds_read_b128 v[176:179], v138 offset:3072
	s_add_u32 s50, s84, 0x40000
	s_addc_u32 s51, s85, 0
	s_mov_b32 m0, s86
	v_lshl_add_u64 v[232:233], s[50:51], 0, v[130:131]
	ds_read_b128 v[180:183], v194 offset:32768
	ds_read_b128 v[196:199], v194 offset:33792
	ds_read_b128 v[200:203], v194 offset:34816
	ds_read_b128 v[204:207], v194 offset:35840
	ds_read_b128 v[208:211], v194 offset:36864
	ds_read_b128 v[212:215], v194 offset:37888
	ds_read_b128 v[216:219], v194 offset:38912
	ds_read_b128 v[220:223], v194 offset:39936
	global_load_lds_dwordx4 v[232:233], off
	v_lshl_add_u64 v[232:233], s[50:51], 0, v[134:135]
	s_mov_b32 m0, s87
	s_nop 0
	global_load_lds_dwordx4 v[232:233], off
	s_waitcnt vmcnt(8)
	s_waitcnt lgkmcnt(0)
	s_barrier
	s_setprio 3
	s_waitcnt lgkmcnt(0)
	v_mfma_f32_16x16x32_bf16 v[118:121], v[148:151], v[180:183], v[118:121]
	v_mfma_f32_16x16x32_bf16 v[114:117], v[156:159], v[180:183], v[114:117]
	v_mfma_f32_16x16x32_bf16 v[102:105], v[148:151], v[200:203], v[102:105]
	v_mfma_f32_16x16x32_bf16 v[98:101], v[156:159], v[200:203], v[98:101]
	v_mfma_f32_16x16x32_bf16 v[86:89], v[148:151], v[208:211], v[86:89]
	v_mfma_f32_16x16x32_bf16 v[82:85], v[156:159], v[208:211], v[82:85]
	v_mfma_f32_16x16x32_bf16 v[70:73], v[148:151], v[216:219], v[70:73]
	v_mfma_f32_16x16x32_bf16 v[66:69], v[156:159], v[216:219], v[66:69]
	v_mfma_f32_16x16x32_bf16 v[118:121], v[152:155], v[196:199], v[118:121]
	v_mfma_f32_16x16x32_bf16 v[114:117], v[160:163], v[196:199], v[114:117]
	v_mfma_f32_16x16x32_bf16 v[102:105], v[152:155], v[204:207], v[102:105]
	v_mfma_f32_16x16x32_bf16 v[98:101], v[160:163], v[204:207], v[98:101]
	v_mfma_f32_16x16x32_bf16 v[86:89], v[152:155], v[212:215], v[86:89]
	v_mfma_f32_16x16x32_bf16 v[82:85], v[160:163], v[212:215], v[82:85]
	v_mfma_f32_16x16x32_bf16 v[70:73], v[152:155], v[220:223], v[70:73]
	v_mfma_f32_16x16x32_bf16 v[66:69], v[160:163], v[220:223], v[66:69]
	s_setprio 0
	s_setprio 3
	v_mfma_f32_16x16x32_bf16 v[126:129], v[164:167], v[180:183], v[126:129]
	v_mfma_f32_16x16x32_bf16 v[122:125], v[172:175], v[180:183], v[122:125]
	v_mfma_f32_16x16x32_bf16 v[110:113], v[164:167], v[200:203], v[110:113]
	v_mfma_f32_16x16x32_bf16 v[106:109], v[172:175], v[200:203], v[106:109]
	v_mfma_f32_16x16x32_bf16 v[94:97], v[164:167], v[208:211], v[94:97]
	v_mfma_f32_16x16x32_bf16 v[90:93], v[172:175], v[208:211], v[90:93]
	v_mfma_f32_16x16x32_bf16 v[78:81], v[164:167], v[216:219], v[78:81]
	v_mfma_f32_16x16x32_bf16 v[74:77], v[172:175], v[216:219], v[74:77]
	v_mfma_f32_16x16x32_bf16 v[126:129], v[168:171], v[196:199], v[126:129]
	v_mfma_f32_16x16x32_bf16 v[122:125], v[176:179], v[196:199], v[122:125]
	v_mfma_f32_16x16x32_bf16 v[110:113], v[168:171], v[204:207], v[110:113]
	v_mfma_f32_16x16x32_bf16 v[106:109], v[176:179], v[204:207], v[106:109]
	v_mfma_f32_16x16x32_bf16 v[94:97], v[168:171], v[212:215], v[94:97]
	v_mfma_f32_16x16x32_bf16 v[90:93], v[176:179], v[212:215], v[90:93]
	v_mfma_f32_16x16x32_bf16 v[78:81], v[168:171], v[220:223], v[78:81]
	v_mfma_f32_16x16x32_bf16 v[74:77], v[176:179], v[220:223], v[74:77]
	s_setprio 0
	s_barrier
; #define PG8_STAGE(bufoff, gbase, voff) do { _Pragma("unroll") for (int _i = 0; _i < 2; ++_i) \
;         __builtin_amdgcn_global_load_lds((const unsigned*)((const char*)(gbase) + (voff)[_i]), (LAS unsigned*)(lds + (bufoff) + ldsw + _i * 8192), 16, 0, 0); } while (0)
; #define PG8_LDA(dst, b, h) do { _Pragma("unroll") for (int m = 0; m < 4; ++m) _Pragma("unroll") for (int k = 0; k < 2; ++k) dst[m][k] = *(const LAS bf16x8*)(lds + PG8_SA(b, h) + aoff + m * 2048 + k * 1024); } while (0)
; #define PG8_MMA(ai, bj, At, Bt) do { __builtin_amdgcn_s_setprio(3); _Pragma("unroll") for (int m = 0; m < 4; ++m) _Pragma("unroll") for (int n = 0; n < 2; ++n) _Pragma("unroll") for (int k = 0; k < 2; ++k) \
;         acc[ai][bj][m][n] = __builtin_amdgcn_mfma_f32_16x16x32_bf16(Bt[n][k], At[m][k], acc[ai][bj][m][n], 0, 0, 0); __builtin_amdgcn_s_setprio(0); } while (0)
; #define PG8_WAIT_V(n) asm volatile("s_waitcnt vmcnt(" #n ")" ::: "memory")
; #define PG8_WAIT_L(n) asm volatile("s_waitcnt lgkmcnt(" #n ")" ::: "memory")
; #define PG8_BAR __builtin_amdgcn_s_barrier()
; #define PG8_SCHED __builtin_amdgcn_sched_barrier(0)
; template <class Epi, bool ALIGN_EPI>
; __device__ __forceinline__ void gemm_phase(LAS unsigned char* lds, const Gemm g, const StaticOrder& S, const Epi& E) {
;     ...
;             PG8_LDA(At, 1, 1); PG8_STAGE(PG8_SB(1, 0), b3, voffB); PG8_STAGE(PG8_SB(1, 1), b3 + hstep, voffB); PG8_STAGE(PG8_SA(1, 0), a3, voffA);
;             PG8_WAIT_V(8); PG8_WAIT_L(0); PG8_BAR; PG8_MMA(1, 0, At, B0); PG8_MMA(1, 1, At, B1); PG8_BAR; PG8_SCHED;
;         }
	s_add_i32 s9, s9, s33
	v_lshl_add_u64 v[224:225], v[224:225], 0, s[62:63]
	s_mov_b32 m0, s9
	ds_read_b128 v[180:183], v194 offset:49152
	ds_read_b128 v[196:199], v194 offset:50176
	ds_read_b128 v[200:203], v194 offset:51200
	ds_read_b128 v[204:207], v194 offset:52224
	ds_read_b128 v[208:211], v194 offset:53248
	ds_read_b128 v[212:215], v194 offset:54272
	ds_read_b128 v[216:219], v194 offset:55296
	ds_read_b128 v[220:223], v194 offset:56320
	global_load_lds_dwordx4 v[224:225], off
	s_add_i32 m0, s9, 0x2000
	s_add_u32 s50, s82, 0x40080
	v_lshl_add_u64 v[224:225], v[226:227], 0, s[62:63]
	s_addc_u32 s51, s83, 0
	s_add_i32 s9, s89, s33
	global_load_lds_dwordx4 v[224:225], off
	v_lshl_add_u64 v[224:225], s[50:51], 0, v[132:133]
	s_mov_b32 m0, s9
	s_nop 0
	global_load_lds_dwordx4 v[224:225], off
	v_lshl_add_u64 v[224:225], s[50:51], 0, v[136:137]
	s_add_i32 m0, s9, 0x2000
	s_nop 0
	global_load_lds_dwordx4 v[224:225], off
	v_lshl_add_u64 v[224:225], v[228:229], 0, s[62:63]
	s_mov_b32 m0, s93
	s_nop 0
	global_load_lds_dwordx4 v[224:225], off
	v_lshl_add_u64 v[224:225], v[230:231], 0, s[62:63]
	s_mov_b32 m0, s94
	s_nop 0
	global_load_lds_dwordx4 v[224:225], off
	s_waitcnt vmcnt(8)
	s_waitcnt lgkmcnt(0)
	s_barrier
	s_setprio 3
	s_waitcnt lgkmcnt(0)
	v_mfma_f32_16x16x32_bf16 v[54:57], v[148:151], v[180:183], v[54:57]
	v_mfma_f32_16x16x32_bf16 v[50:53], v[156:159], v[180:183], v[50:53]
	v_mfma_f32_16x16x32_bf16 v[38:41], v[148:151], v[200:203], v[38:41]
	v_mfma_f32_16x16x32_bf16 v[34:37], v[156:159], v[200:203], v[34:37]
	v_mfma_f32_16x16x32_bf16 v[22:25], v[148:151], v[208:211], v[22:25]
	v_mfma_f32_16x16x32_bf16 v[18:21], v[156:159], v[208:211], v[18:21]
	v_mfma_f32_16x16x32_bf16 v[6:9], v[148:151], v[216:219], v[6:9]
	v_mfma_f32_16x16x32_bf16 v[2:5], v[156:159], v[216:219], v[2:5]
	v_mfma_f32_16x16x32_bf16 v[54:57], v[152:155], v[196:199], v[54:57]
	v_mfma_f32_16x16x32_bf16 v[50:53], v[160:163], v[196:199], v[50:53]
	v_mfma_f32_16x16x32_bf16 v[38:41], v[152:155], v[204:207], v[38:41]
	v_mfma_f32_16x16x32_bf16 v[34:37], v[160:163], v[204:207], v[34:37]
	v_mfma_f32_16x16x32_bf16 v[22:25], v[152:155], v[212:215], v[22:25]
	v_mfma_f32_16x16x32_bf16 v[18:21], v[160:163], v[212:215], v[18:21]
	v_mfma_f32_16x16x32_bf16 v[6:9], v[152:155], v[220:223], v[6:9]
	v_mfma_f32_16x16x32_bf16 v[2:5], v[160:163], v[220:223], v[2:5]
	s_setprio 0
	s_setprio 3
	v_mfma_f32_16x16x32_bf16 v[62:65], v[164:167], v[180:183], v[62:65]
	v_mfma_f32_16x16x32_bf16 v[58:61], v[172:175], v[180:183], v[58:61]
	v_mfma_f32_16x16x32_bf16 v[46:49], v[164:167], v[200:203], v[46:49]
	v_mfma_f32_16x16x32_bf16 v[42:45], v[172:175], v[200:203], v[42:45]
	v_mfma_f32_16x16x32_bf16 v[30:33], v[164:167], v[208:211], v[30:33]
	v_mfma_f32_16x16x32_bf16 v[26:29], v[172:175], v[208:211], v[26:29]
	v_mfma_f32_16x16x32_bf16 v[14:17], v[164:167], v[216:219], v[14:17]
	v_mfma_f32_16x16x32_bf16 v[10:13], v[172:175], v[216:219], v[10:13]
	v_mfma_f32_16x16x32_bf16 v[62:65], v[168:171], v[196:199], v[62:65]
	v_mfma_f32_16x16x32_bf16 v[58:61], v[176:179], v[196:199], v[58:61]
	v_mfma_f32_16x16x32_bf16 v[46:49], v[168:171], v[204:207], v[46:49]
	v_mfma_f32_16x16x32_bf16 v[42:45], v[176:179], v[204:207], v[42:45]
	v_mfma_f32_16x16x32_bf16 v[30:33], v[168:171], v[212:215], v[30:33]
	v_mfma_f32_16x16x32_bf16 v[26:29], v[176:179], v[212:215], v[26:29]
	v_mfma_f32_16x16x32_bf16 v[14:17], v[168:171], v[220:223], v[14:17]
	v_mfma_f32_16x16x32_bf16 v[10:13], v[176:179], v[220:223], v[10:13]
	s_setprio 0
	s_barrier
	s_add_i32 s8, s8, 2
	s_add_u32 s80, s80, 0x100
	s_addc_u32 s81, s81, 0
	s_add_u32 vcc_lo, vcc_lo, 0x100
	s_addc_u32 vcc_hi, vcc_hi, 0

; #define PG8_STAGE(bufoff, gbase, voff) do { _Pragma("unroll") for (int _i = 0; _i < 2; ++_i) \
;         __builtin_amdgcn_global_load_lds((const unsigned*)((const char*)(gbase) + (voff)[_i]), (LAS unsigned*)(lds + (bufoff) + ldsw + _i * 8192), 16, 0, 0); } while (0)
; #define PG8_LDA(dst, b, h) do { _Pragma("unroll") for (int m = 0; m < 4; ++m) _Pragma("unroll") for (int k = 0; k < 2; ++k) dst[m][k] = *(const LAS bf16x8*)(lds + PG8_SA(b, h) + aoff + m * 2048 + k * 1024); } while (0)
; #define PG8_LDB(dst, b, h) do { _Pragma("unroll") for (int n = 0; n < 2; ++n) _Pragma("unroll") for (int k = 0; k < 2; ++k) dst[n][k] = *(const LAS bf16x8*)(lds + PG8_SB(b, h) + boff + n * 2048 + k * 1024); } while (0)
; #define PG8_WAIT_V(n) asm volatile("s_waitcnt vmcnt(" #n ")" ::: "memory")
; #define PG8_WAIT_L(n) asm volatile("s_waitcnt lgkmcnt(" #n ")" ::: "memory")
; #define PG8_BAR __builtin_amdgcn_s_barrier()
; #define PG8_SCHED __builtin_amdgcn_sched_barrier(0)
; template <class Epi, bool ALIGN_EPI>
; __device__ __forceinline__ void gemm_phase(LAS unsigned char* lds, const Gemm g, const StaticOrder& S, const Epi& E) {
;     ...
;         for (int t = 0; t < nt; t += 2) {
;             const bool last = (t == nt - 2);
;             const char* a1 = cA + (size_t)(t + 1) * kstep;
;             const char* a2 = last ? nA : cA + (size_t)(t + 2) * kstep; const char* b2 = last ? nB : cB + (size_t)(t + 2) * kstep;
;             const char* a3 = a2 + kstep; const char* b3 = b2 + kstep;
;             PG8_LDB(B0, 0, 0); PG8_LDB(B1, 0, 1); PG8_SCHED; PG8_LDA(At, 0, 0); PG8_STAGE(PG8_SA(1, 1), a1 + hstep, voffA);
;             PG8_WAIT_V(8); PG8_WAIT_L(0); PG8_BAR; PG8_MMA(0, 0, At, B0); PG8_MMA(0, 1, At, B1); PG8_BAR; PG8_SCHED;
;             PG8_LDA(At, 0, 1); PG8_STAGE(PG8_SB(0, 0), b2, voffB); PG8_STAGE(PG8_SB(0, 1), b2 + hstep, voffB); PG8_STAGE(PG8_SA(0, 0), a2, voffA);
;             PG8_WAIT_V(8); PG8_WAIT_L(0); PG8_BAR; PG8_MMA(1, 0, At, B0); PG8_MMA(1, 1, At, B1); PG8_BAR; PG8_SCHED;
;     ...
; #pragma unroll
;         for (int a = 0; a < 2; ++a)
; #pragma unroll
;             for (int b = 0; b < 2; ++b)
; #pragma unroll
;                 for (int m = 0; m < 4; ++m)
; #pragma unroll
;                     for (int n = 0; n < 2; ++n) acc[a][b][m][n] = (f32x4){0.f, 0.f, 0.f, 0.f};
.LBB0_519:
	s_ashr_i32 s55, s54, 31
	s_lshl_b64 s[56:57], s[54:55], 19
	s_add_u32 s56, s26, s56
	s_addc_u32 s57, s27, s57
	s_and_b64 s[58:59], s[4:5], exec
	s_cselect_b32 s55, s57, s65
	s_cselect_b32 s61, s56, s64
	s_ashr_i32 s53, s52, 31
	s_lshl_b64 s[58:59], s[52:53], 19
	s_add_u32 s58, s10, s58
	s_addc_u32 s59, s11, s59
	s_and_b64 s[68:69], s[4:5], exec
	s_cselect_b32 s53, s59, s67
	s_cselect_b32 s82, s58, s66
	s_add_u32 s64, s64, 0x40080
	s_addc_u32 s65, s65, 0
	s_add_u32 s83, s66, 0x100
	s_addc_u32 s84, s67, 0
	s_mov_b32 s85, -2
	s_waitcnt lgkmcnt(0)
	ds_read_b128 v[130:133], v214
	ds_read_b128 v[134:137], v214 offset:1024
	ds_read_b128 v[138:141], v214 offset:2048
	ds_read_b128 v[142:145], v214 offset:3072
	ds_read_b128 v[146:149], v215
	ds_read_b128 v[150:153], v215 offset:1024
	ds_read_b128 v[154:157], v215 offset:2048
	ds_read_b128 v[158:161], v215 offset:3072
	s_add_u32 s66, s64, 0xfffc0080
	s_addc_u32 s67, s65, -1
	s_cmp_eq_u32 s85, 12
	s_cselect_b32 s69, s55, s67
	s_cselect_b32 s68, s61, s66
	s_cselect_b32 s67, s53, s84
	s_cselect_b32 s66, s82, s83
	v_lshl_add_u64 v[222:223], s[64:65], 0, v[186:187]
	s_add_i32 m0, s63, 0xc000
	ds_read_b128 v[162:165], v216
	ds_read_b128 v[166:169], v216 offset:1024
	ds_read_b128 v[170:173], v216 offset:2048
	ds_read_b128 v[174:177], v216 offset:3072
	ds_read_b128 v[194:197], v216 offset:4096
	ds_read_b128 v[198:201], v216 offset:5120
	ds_read_b128 v[202:205], v216 offset:6144
	ds_read_b128 v[218:221], v216 offset:7168
	global_load_lds_dwordx4 v[222:223], off
	v_lshl_add_u64 v[222:223], s[64:65], 0, v[188:189]
	s_add_i32 m0, s63, 0xe000
	s_nop 0
	global_load_lds_dwordx4 v[222:223], off
	s_waitcnt vmcnt(8)
	s_waitcnt lgkmcnt(0)
	s_barrier
	s_setprio 3
	s_waitcnt lgkmcnt(0)
	v_mfma_f32_16x16x32_bf16 v[126:129], v[130:133], v[162:165], 0
	v_mfma_f32_16x16x32_bf16 v[122:125], v[138:141], v[162:165], 0
	v_mfma_f32_16x16x32_bf16 v[110:113], v[130:133], v[170:173], 0
	v_mfma_f32_16x16x32_bf16 v[106:109], v[138:141], v[170:173], 0
	v_mfma_f32_16x16x32_bf16 v[94:97], v[130:133], v[194:197], 0
	v_mfma_f32_16x16x32_bf16 v[90:93], v[138:141], v[194:197], 0
	v_mfma_f32_16x16x32_bf16 v[78:81], v[130:133], v[202:205], 0
	v_mfma_f32_16x16x32_bf16 v[74:77], v[138:141], v[202:205], 0
	v_mfma_f32_16x16x32_bf16 v[126:129], v[134:137], v[166:169], v[126:129]
	v_mfma_f32_16x16x32_bf16 v[122:125], v[142:145], v[166:169], v[122:125]
	v_mfma_f32_16x16x32_bf16 v[110:113], v[134:137], v[174:177], v[110:113]
	v_mfma_f32_16x16x32_bf16 v[106:109], v[142:145], v[174:177], v[106:109]
	v_mfma_f32_16x16x32_bf16 v[94:97], v[134:137], v[198:201], v[94:97]
	v_mfma_f32_16x16x32_bf16 v[90:93], v[142:145], v[198:201], v[90:93]
	v_mfma_f32_16x16x32_bf16 v[78:81], v[134:137], v[218:221], v[78:81]
	v_mfma_f32_16x16x32_bf16 v[74:77], v[142:145], v[218:221], v[74:77]
	s_setprio 0
	s_setprio 3
	v_mfma_f32_16x16x32_bf16 v[118:121], v[146:149], v[162:165], 0
	v_mfma_f32_16x16x32_bf16 v[114:117], v[154:157], v[162:165], 0
	v_mfma_f32_16x16x32_bf16 v[102:105], v[146:149], v[170:173], 0
	v_mfma_f32_16x16x32_bf16 v[98:101], v[154:157], v[170:173], 0
	v_mfma_f32_16x16x32_bf16 v[86:89], v[146:149], v[194:197], 0
	v_mfma_f32_16x16x32_bf16 v[82:85], v[154:157], v[194:197], 0
	v_mfma_f32_16x16x32_bf16 v[70:73], v[146:149], v[202:205], 0
	v_mfma_f32_16x16x32_bf16 v[66:69], v[154:157], v[202:205], 0
	v_mfma_f32_16x16x32_bf16 v[118:121], v[150:153], v[166:169], v[118:121]
	v_mfma_f32_16x16x32_bf16 v[114:117], v[158:161], v[166:169], v[114:117]
	v_mfma_f32_16x16x32_bf16 v[102:105], v[150:153], v[174:177], v[102:105]
	v_mfma_f32_16x16x32_bf16 v[98:101], v[158:161], v[174:177], v[98:101]
	v_mfma_f32_16x16x32_bf16 v[86:89], v[150:153], v[198:201], v[86:89]
	v_mfma_f32_16x16x32_bf16 v[82:85], v[158:161], v[198:201], v[82:85]
	v_mfma_f32_16x16x32_bf16 v[70:73], v[150:153], v[218:221], v[70:73]
	v_mfma_f32_16x16x32_bf16 v[66:69], v[158:161], v[218:221], v[66:69]
	s_setprio 0
	s_barrier
	s_add_i32 s86, s80, s33
	v_lshl_add_u64 v[222:223], s[66:67], 0, v[180:181]
	s_mov_b32 m0, s86
	ds_read_b128 v[162:165], v216 offset:16384
	ds_read_b128 v[166:169], v216 offset:17408
	ds_read_b128 v[170:173], v216 offset:18432
	ds_read_b128 v[174:177], v216 offset:19456
	ds_read_b128 v[194:197], v216 offset:20480
	ds_read_b128 v[198:201], v216 offset:21504
	ds_read_b128 v[202:205], v216 offset:22528
	ds_read_b128 v[218:221], v216 offset:23552
	global_load_lds_dwordx4 v[222:223], off
	s_add_i32 m0, s86, 0x2000
	s_add_u32 s86, s66, 0x40000
	v_lshl_add_u64 v[224:225], s[66:67], 0, v[184:185]
	s_addc_u32 s87, s67, 0
	s_add_i32 s88, s81, s33
	global_load_lds_dwordx4 v[224:225], off
	v_lshl_add_u64 v[226:227], s[86:87], 0, v[180:181]
	s_mov_b32 m0, s88
	v_lshl_add_u64 v[228:229], s[68:69], 0, v[182:183]
	global_load_lds_dwordx4 v[226:227], off
	v_lshl_add_u64 v[226:227], s[86:87], 0, v[184:185]
	s_add_i32 m0, s88, 0x2000
	s_nop 0
	global_load_lds_dwordx4 v[226:227], off
	v_lshl_add_u64 v[226:227], s[68:69], 0, v[178:179]
	s_mov_b32 m0, s63
	s_nop 0
	global_load_lds_dwordx4 v[226:227], off
	s_mov_b32 m0, s70
	s_nop 0
	global_load_lds_dwordx4 v[228:229], off
	s_waitcnt vmcnt(8)
	s_waitcnt lgkmcnt(0)
	s_barrier
; #define PG8_STAGE(bufoff, gbase, voff) do { _Pragma("unroll") for (int _i = 0; _i < 2; ++_i) \
;         __builtin_amdgcn_global_load_lds((const unsigned*)((const char*)(gbase) + (voff)[_i]), (LAS unsigned*)(lds + (bufoff) + ldsw + _i * 8192), 16, 0, 0); } while (0)
; #define PG8_LDA(dst, b, h) do { _Pragma("unroll") for (int m = 0; m < 4; ++m) _Pragma("unroll") for (int k = 0; k < 2; ++k) dst[m][k] = *(const LAS bf16x8*)(lds + PG8_SA(b, h) + aoff + m * 2048 + k * 1024); } while (0)
; #define PG8_LDB(dst, b, h) do { _Pragma("unroll") for (int n = 0; n < 2; ++n) _Pragma("unroll") for (int k = 0; k < 2; ++k) dst[n][k] = *(const LAS bf16x8*)(lds + PG8_SB(b, h) + boff + n * 2048 + k * 1024); } while (0)
; #define PG8_MMA(ai, bj, At, Bt) do { __builtin_amdgcn_s_setprio(3); _Pragma("unroll") for (int m = 0; m < 4; ++m) _Pragma("unroll") for (int n = 0; n < 2; ++n) _Pragma("unroll") for (int k = 0; k < 2; ++k) \
;         acc[ai][bj][m][n] = __builtin_amdgcn_mfma_f32_16x16x32_bf16(Bt[n][k], At[m][k], acc[ai][bj][m][n], 0, 0, 0); __builtin_amdgcn_s_setprio(0); } while (0)
; #define PG8_WAIT_V(n) asm volatile("s_waitcnt vmcnt(" #n ")" ::: "memory")
; #define PG8_WAIT_L(n) asm volatile("s_waitcnt lgkmcnt(" #n ")" ::: "memory")
; #define PG8_BAR __builtin_amdgcn_s_barrier()
; #define PG8_SCHED __builtin_amdgcn_sched_barrier(0)
; template <class Epi, bool ALIGN_EPI>
; __device__ __forceinline__ void gemm_phase(LAS unsigned char* lds, const Gemm g, const StaticOrder& S, const Epi& E) {
;     ...
;             PG8_WAIT_V(8); PG8_WAIT_L(0); PG8_BAR; PG8_MMA(1, 0, At, B0); PG8_MMA(1, 1, At, B1); PG8_BAR; PG8_SCHED;
;             PG8_LDB(B0, 1, 0); PG8_LDB(B1, 1, 1); PG8_SCHED; PG8_LDA(At, 1, 0); PG8_STAGE(PG8_SA(0, 1), a2 + hstep, voffA);
;             PG8_WAIT_V(8); PG8_WAIT_L(0); PG8_BAR; PG8_MMA(0, 0, At, B0); PG8_MMA(0, 1, At, B1); PG8_BAR; PG8_SCHED;
	s_setprio 3
	s_waitcnt lgkmcnt(0)
	v_mfma_f32_16x16x32_bf16 v[62:65], v[130:133], v[162:165], 0
	v_mfma_f32_16x16x32_bf16 v[58:61], v[138:141], v[162:165], 0
	v_mfma_f32_16x16x32_bf16 v[46:49], v[130:133], v[170:173], 0
	v_mfma_f32_16x16x32_bf16 v[42:45], v[138:141], v[170:173], 0
	v_mfma_f32_16x16x32_bf16 v[30:33], v[130:133], v[194:197], 0
	v_mfma_f32_16x16x32_bf16 v[26:29], v[138:141], v[194:197], 0
	v_mfma_f32_16x16x32_bf16 v[14:17], v[130:133], v[202:205], 0
	v_mfma_f32_16x16x32_bf16 v[10:13], v[138:141], v[202:205], 0
	v_mfma_f32_16x16x32_bf16 v[62:65], v[134:137], v[166:169], v[62:65]
	v_mfma_f32_16x16x32_bf16 v[58:61], v[142:145], v[166:169], v[58:61]
	v_mfma_f32_16x16x32_bf16 v[46:49], v[134:137], v[174:177], v[46:49]
	v_mfma_f32_16x16x32_bf16 v[42:45], v[142:145], v[174:177], v[42:45]
	v_mfma_f32_16x16x32_bf16 v[30:33], v[134:137], v[198:201], v[30:33]
	v_mfma_f32_16x16x32_bf16 v[26:29], v[142:145], v[198:201], v[26:29]
	v_mfma_f32_16x16x32_bf16 v[14:17], v[134:137], v[218:221], v[14:17]
	v_mfma_f32_16x16x32_bf16 v[10:13], v[142:145], v[218:221], v[10:13]
	s_setprio 0
	s_setprio 3
	v_mfma_f32_16x16x32_bf16 v[54:57], v[146:149], v[162:165], 0
	v_mfma_f32_16x16x32_bf16 v[50:53], v[154:157], v[162:165], 0
	v_mfma_f32_16x16x32_bf16 v[38:41], v[146:149], v[170:173], 0
	v_mfma_f32_16x16x32_bf16 v[34:37], v[154:157], v[170:173], 0
	v_mfma_f32_16x16x32_bf16 v[22:25], v[146:149], v[194:197], 0
	v_mfma_f32_16x16x32_bf16 v[18:21], v[154:157], v[194:197], 0
	v_mfma_f32_16x16x32_bf16 v[6:9], v[146:149], v[202:205], 0
	v_mfma_f32_16x16x32_bf16 v[2:5], v[154:157], v[202:205], 0
	v_mfma_f32_16x16x32_bf16 v[54:57], v[150:153], v[166:169], v[54:57]
	v_mfma_f32_16x16x32_bf16 v[50:53], v[158:161], v[166:169], v[50:53]
	v_mfma_f32_16x16x32_bf16 v[38:41], v[150:153], v[174:177], v[38:41]
	v_mfma_f32_16x16x32_bf16 v[34:37], v[158:161], v[174:177], v[34:37]
	v_mfma_f32_16x16x32_bf16 v[22:25], v[150:153], v[198:201], v[22:25]
	v_mfma_f32_16x16x32_bf16 v[18:21], v[158:161], v[198:201], v[18:21]
	v_mfma_f32_16x16x32_bf16 v[6:9], v[150:153], v[218:221], v[6:9]
	v_mfma_f32_16x16x32_bf16 v[2:5], v[158:161], v[218:221], v[2:5]
	s_setprio 0
	s_barrier
	s_add_i32 s86, 0, 0x18000
	s_add_i32 s87, 0, 0x1c000
	v_add_u32_e32 v142, s86, v212
	v_add_u32_e32 v158, s87, v212
	ds_read_b128 v[130:133], v142
	ds_read_b128 v[134:137], v142 offset:1024
	ds_read_b128 v[138:141], v142 offset:2048
	ds_read_b128 v[142:145], v142 offset:3072
	ds_read_b128 v[146:149], v158
	ds_read_b128 v[150:153], v158 offset:1024
	ds_read_b128 v[154:157], v158 offset:2048
	ds_read_b128 v[158:161], v158 offset:3072
	s_add_u32 s68, s68, 0x40000
	s_addc_u32 s69, s69, 0
	s_mov_b32 m0, s71
	v_lshl_add_u64 v[230:231], s[68:69], 0, v[178:179]
	ds_read_b128 v[162:165], v216 offset:32768
	ds_read_b128 v[166:169], v216 offset:33792
	ds_read_b128 v[170:173], v216 offset:34816
	ds_read_b128 v[174:177], v216 offset:35840
	ds_read_b128 v[194:197], v216 offset:36864
	ds_read_b128 v[198:201], v216 offset:37888
	ds_read_b128 v[202:205], v216 offset:38912
	ds_read_b128 v[218:221], v216 offset:39936
	global_load_lds_dwordx4 v[230:231], off
	v_lshl_add_u64 v[230:231], s[68:69], 0, v[182:183]
	s_mov_b32 m0, s72
	s_nop 0
	global_load_lds_dwordx4 v[230:231], off
	s_waitcnt vmcnt(8)
	s_waitcnt lgkmcnt(0)
	s_barrier
	s_setprio 3
	s_waitcnt lgkmcnt(0)
	v_mfma_f32_16x16x32_bf16 v[126:129], v[130:133], v[162:165], v[126:129]
	v_mfma_f32_16x16x32_bf16 v[122:125], v[138:141], v[162:165], v[122:125]
	v_mfma_f32_16x16x32_bf16 v[110:113], v[130:133], v[170:173], v[110:113]
	v_mfma_f32_16x16x32_bf16 v[106:109], v[138:141], v[170:173], v[106:109]
	v_mfma_f32_16x16x32_bf16 v[94:97], v[130:133], v[194:197], v[94:97]
	v_mfma_f32_16x16x32_bf16 v[90:93], v[138:141], v[194:197], v[90:93]
	v_mfma_f32_16x16x32_bf16 v[78:81], v[130:133], v[202:205], v[78:81]
	v_mfma_f32_16x16x32_bf16 v[74:77], v[138:141], v[202:205], v[74:77]
	v_mfma_f32_16x16x32_bf16 v[126:129], v[134:137], v[166:169], v[126:129]
	v_mfma_f32_16x16x32_bf16 v[122:125], v[142:145], v[166:169], v[122:125]
	v_mfma_f32_16x16x32_bf16 v[110:113], v[134:137], v[174:177], v[110:113]
	v_mfma_f32_16x16x32_bf16 v[106:109], v[142:145], v[174:177], v[106:109]
	v_mfma_f32_16x16x32_bf16 v[94:97], v[134:137], v[198:201], v[94:97]
	v_mfma_f32_16x16x32_bf16 v[90:93], v[142:145], v[198:201], v[90:93]
	v_mfma_f32_16x16x32_bf16 v[78:81], v[134:137], v[218:221], v[78:81]
	v_mfma_f32_16x16x32_bf16 v[74:77], v[142:145], v[218:221], v[74:77]
	s_setprio 0
	s_setprio 3
	v_mfma_f32_16x16x32_bf16 v[118:121], v[146:149], v[162:165], v[118:121]
	v_mfma_f32_16x16x32_bf16 v[114:117], v[154:157], v[162:165], v[114:117]
	v_mfma_f32_16x16x32_bf16 v[102:105], v[146:149], v[170:173], v[102:105]
	v_mfma_f32_16x16x32_bf16 v[98:101], v[154:157], v[170:173], v[98:101]
	v_mfma_f32_16x16x32_bf16 v[86:89], v[146:149], v[194:197], v[86:89]
	v_mfma_f32_16x16x32_bf16 v[82:85], v[154:157], v[194:197], v[82:85]
	v_mfma_f32_16x16x32_bf16 v[70:73], v[146:149], v[202:205], v[70:73]
	v_mfma_f32_16x16x32_bf16 v[66:69], v[154:157], v[202:205], v[66:69]
	v_mfma_f32_16x16x32_bf16 v[118:121], v[150:153], v[166:169], v[118:121]
	v_mfma_f32_16x16x32_bf16 v[114:117], v[158:161], v[166:169], v[114:117]
	v_mfma_f32_16x16x32_bf16 v[102:105], v[150:153], v[174:177], v[102:105]
	v_mfma_f32_16x16x32_bf16 v[98:101], v[158:161], v[174:177], v[98:101]
	v_mfma_f32_16x16x32_bf16 v[86:89], v[150:153], v[198:201], v[86:89]
	v_mfma_f32_16x16x32_bf16 v[82:85], v[158:161], v[198:201], v[82:85]
	v_mfma_f32_16x16x32_bf16 v[70:73], v[150:153], v[218:221], v[70:73]
	v_mfma_f32_16x16x32_bf16 v[66:69], v[158:161], v[218:221], v[66:69]
	s_setprio 0
	s_barrier
; #define PG8_STAGE(bufoff, gbase, voff) do { _Pragma("unroll") for (int _i = 0; _i < 2; ++_i) \
;         __builtin_amdgcn_global_load_lds((const unsigned*)((const char*)(gbase) + (voff)[_i]), (LAS unsigned*)(lds + (bufoff) + ldsw + _i * 8192), 16, 0, 0); } while (0)
; #define PG8_LDA(dst, b, h) do { _Pragma("unroll") for (int m = 0; m < 4; ++m) _Pragma("unroll") for (int k = 0; k < 2; ++k) dst[m][k] = *(const LAS bf16x8*)(lds + PG8_SA(b, h) + aoff + m * 2048 + k * 1024); } while (0)
; #define PG8_MMA(ai, bj, At, Bt) do { __builtin_amdgcn_s_setprio(3); _Pragma("unroll") for (int m = 0; m < 4; ++m) _Pragma("unroll") for (int n = 0; n < 2; ++n) _Pragma("unroll") for (int k = 0; k < 2; ++k) \
;         acc[ai][bj][m][n] = __builtin_amdgcn_mfma_f32_16x16x32_bf16(Bt[n][k], At[m][k], acc[ai][bj][m][n], 0, 0, 0); __builtin_amdgcn_s_setprio(0); } while (0)
; #define PG8_WAIT_V(n) asm volatile("s_waitcnt vmcnt(" #n ")" ::: "memory")
; #define PG8_WAIT_L(n) asm volatile("s_waitcnt lgkmcnt(" #n ")" ::: "memory")
; #define PG8_BAR __builtin_amdgcn_s_barrier()
; #define PG8_SCHED __builtin_amdgcn_sched_barrier(0)
; template <class Epi, bool ALIGN_EPI>
; __device__ __forceinline__ void gemm_phase(LAS unsigned char* lds, const Gemm g, const StaticOrder& S, const Epi& E) {
;     ...
;             PG8_LDA(At, 1, 1); PG8_STAGE(PG8_SB(1, 0), b3, voffB); PG8_STAGE(PG8_SB(1, 1), b3 + hstep, voffB); PG8_STAGE(PG8_SA(1, 0), a3, voffA);
;             PG8_WAIT_V(8); PG8_WAIT_L(0); PG8_BAR; PG8_MMA(1, 0, At, B0); PG8_MMA(1, 1, At, B1); PG8_BAR; PG8_SCHED;
;         }
	s_add_i32 s68, s86, s33
	v_lshl_add_u64 v[222:223], v[222:223], 0, s[18:19]
	s_mov_b32 m0, s68
	ds_read_b128 v[162:165], v216 offset:49152
	ds_read_b128 v[166:169], v216 offset:50176
	ds_read_b128 v[170:173], v216 offset:51200
	ds_read_b128 v[174:177], v216 offset:52224
	ds_read_b128 v[194:197], v216 offset:53248
	ds_read_b128 v[198:201], v216 offset:54272
	ds_read_b128 v[202:205], v216 offset:55296
	ds_read_b128 v[218:221], v216 offset:56320
	global_load_lds_dwordx4 v[222:223], off
	s_add_i32 m0, s68, 0x2000
	s_add_u32 s66, s66, 0x40080
	v_lshl_add_u64 v[222:223], v[224:225], 0, s[18:19]
	s_addc_u32 s67, s67, 0
	s_add_i32 s68, s87, s33
	global_load_lds_dwordx4 v[222:223], off
	v_lshl_add_u64 v[222:223], s[66:67], 0, v[180:181]
	s_mov_b32 m0, s68
	s_nop 0
	global_load_lds_dwordx4 v[222:223], off
	v_lshl_add_u64 v[222:223], s[66:67], 0, v[184:185]
	s_add_i32 m0, s68, 0x2000
	s_nop 0
	global_load_lds_dwordx4 v[222:223], off
	v_lshl_add_u64 v[222:223], v[226:227], 0, s[18:19]
	s_mov_b32 m0, s78
	s_nop 0
	global_load_lds_dwordx4 v[222:223], off
	v_lshl_add_u64 v[222:223], v[228:229], 0, s[18:19]
	s_mov_b32 m0, s79
	s_nop 0
	global_load_lds_dwordx4 v[222:223], off
	s_waitcnt vmcnt(8)
	s_waitcnt lgkmcnt(0)
	s_barrier
	s_setprio 3
	s_waitcnt lgkmcnt(0)
	v_mfma_f32_16x16x32_bf16 v[62:65], v[130:133], v[162:165], v[62:65]
	v_mfma_f32_16x16x32_bf16 v[58:61], v[138:141], v[162:165], v[58:61]
	v_mfma_f32_16x16x32_bf16 v[46:49], v[130:133], v[170:173], v[46:49]
	v_mfma_f32_16x16x32_bf16 v[42:45], v[138:141], v[170:173], v[42:45]
	v_mfma_f32_16x16x32_bf16 v[30:33], v[130:133], v[194:197], v[30:33]
	v_mfma_f32_16x16x32_bf16 v[26:29], v[138:141], v[194:197], v[26:29]
	v_mfma_f32_16x16x32_bf16 v[14:17], v[130:133], v[202:205], v[14:17]
	v_mfma_f32_16x16x32_bf16 v[10:13], v[138:141], v[202:205], v[10:13]
	v_mfma_f32_16x16x32_bf16 v[62:65], v[134:137], v[166:169], v[62:65]
	v_mfma_f32_16x16x32_bf16 v[58:61], v[142:145], v[166:169], v[58:61]
	v_mfma_f32_16x16x32_bf16 v[46:49], v[134:137], v[174:177], v[46:49]
	v_mfma_f32_16x16x32_bf16 v[42:45], v[142:145], v[174:177], v[42:45]
	v_mfma_f32_16x16x32_bf16 v[30:33], v[134:137], v[198:201], v[30:33]
	v_mfma_f32_16x16x32_bf16 v[26:29], v[142:145], v[198:201], v[26:29]
	v_mfma_f32_16x16x32_bf16 v[14:17], v[134:137], v[218:221], v[14:17]
	v_mfma_f32_16x16x32_bf16 v[10:13], v[142:145], v[218:221], v[10:13]
	s_setprio 0
	s_setprio 3
	v_mfma_f32_16x16x32_bf16 v[54:57], v[146:149], v[162:165], v[54:57]
	v_mfma_f32_16x16x32_bf16 v[50:53], v[154:157], v[162:165], v[50:53]
	v_mfma_f32_16x16x32_bf16 v[38:41], v[146:149], v[170:173], v[38:41]
	v_mfma_f32_16x16x32_bf16 v[34:37], v[154:157], v[170:173], v[34:37]
	v_mfma_f32_16x16x32_bf16 v[22:25], v[146:149], v[194:197], v[22:25]
	v_mfma_f32_16x16x32_bf16 v[18:21], v[154:157], v[194:197], v[18:21]
	v_mfma_f32_16x16x32_bf16 v[6:9], v[146:149], v[202:205], v[6:9]
	v_mfma_f32_16x16x32_bf16 v[2:5], v[154:157], v[202:205], v[2:5]
	v_mfma_f32_16x16x32_bf16 v[54:57], v[150:153], v[166:169], v[54:57]
	v_mfma_f32_16x16x32_bf16 v[50:53], v[158:161], v[166:169], v[50:53]
	v_mfma_f32_16x16x32_bf16 v[38:41], v[150:153], v[174:177], v[38:41]
	v_mfma_f32_16x16x32_bf16 v[34:37], v[158:161], v[174:177], v[34:37]
	v_mfma_f32_16x16x32_bf16 v[22:25], v[150:153], v[198:201], v[22:25]
	v_mfma_f32_16x16x32_bf16 v[18:21], v[158:161], v[198:201], v[18:21]
	v_mfma_f32_16x16x32_bf16 v[6:9], v[150:153], v[218:221], v[6:9]
	v_mfma_f32_16x16x32_bf16 v[2:5], v[158:161], v[218:221], v[2:5]
	s_setprio 0
	s_barrier
	s_add_i32 s85, s85, 2
	s_add_u32 s64, s64, 0x100
	s_addc_u32 s65, s65, 0
	s_add_u32 s83, s83, 0x100
	s_addc_u32 s84, s84, 0

; #define PG8_STAGE(bufoff, gbase, voff) do { _Pragma("unroll") for (int _i = 0; _i < 2; ++_i) \
;         __builtin_amdgcn_global_load_lds((const unsigned*)((const char*)(gbase) + (voff)[_i]), (LAS unsigned*)(lds + (bufoff) + ldsw + _i * 8192), 16, 0, 0); } while (0)
; #define PG8_LDA(dst, b, h) do { _Pragma("unroll") for (int m = 0; m < 4; ++m) _Pragma("unroll") for (int k = 0; k < 2; ++k) dst[m][k] = *(const LAS bf16x8*)(lds + PG8_SA(b, h) + aoff + m * 2048 + k * 1024); } while (0)
; #define PG8_LDB(dst, b, h) do { _Pragma("unroll") for (int n = 0; n < 2; ++n) _Pragma("unroll") for (int k = 0; k < 2; ++k) dst[n][k] = *(const LAS bf16x8*)(lds + PG8_SB(b, h) + boff + n * 2048 + k * 1024); } while (0)
; #define PG8_WAIT_V(n) asm volatile("s_waitcnt vmcnt(" #n ")" ::: "memory")
; #define PG8_WAIT_L(n) asm volatile("s_waitcnt lgkmcnt(" #n ")" ::: "memory")
; #define PG8_BAR __builtin_amdgcn_s_barrier()
; #define PG8_SCHED __builtin_amdgcn_sched_barrier(0)
; template <class Epi, bool ALIGN_EPI>
; __device__ __forceinline__ void gemm_phase(LAS unsigned char* lds, const Gemm g, const StaticOrder& S, const Epi& E) {
;     ...
;         for (int t = 0; t < nt; t += 2) {
;             const bool last = (t == nt - 2);
;             const char* a1 = cA + (size_t)(t + 1) * kstep;
;             const char* a2 = last ? nA : cA + (size_t)(t + 2) * kstep; const char* b2 = last ? nB : cB + (size_t)(t + 2) * kstep;
;             const char* a3 = a2 + kstep; const char* b3 = b2 + kstep;
;             PG8_LDB(B0, 0, 0); PG8_LDB(B1, 0, 1); PG8_SCHED; PG8_LDA(At, 0, 0); PG8_STAGE(PG8_SA(1, 1), a1 + hstep, voffA);
;             PG8_WAIT_V(8); PG8_WAIT_L(0); PG8_BAR; PG8_MMA(0, 0, At, B0); PG8_MMA(0, 1, At, B1); PG8_BAR; PG8_SCHED;
;             PG8_LDA(At, 0, 1); PG8_STAGE(PG8_SB(0, 0), b2, voffB); PG8_STAGE(PG8_SB(0, 1), b2 + hstep, voffB); PG8_STAGE(PG8_SA(0, 0), a2, voffA);
;             PG8_WAIT_V(8); PG8_WAIT_L(0); PG8_BAR; PG8_MMA(1, 0, At, B0); PG8_MMA(1, 1, At, B1); PG8_BAR; PG8_SCHED;
;     ...
; #pragma unroll
;         for (int a = 0; a < 2; ++a)
; #pragma unroll
;             for (int b = 0; b < 2; ++b)
; #pragma unroll
;                 for (int m = 0; m < 4; ++m)
; #pragma unroll
;                     for (int n = 0; n < 2; ++n) acc[a][b][m][n] = (f32x4){0.f, 0.f, 0.f, 0.f};
.LBB0_608:
	s_ashr_i32 s63, s62, 31
	s_lshl_b64 s[10:11], s[62:63], 19
	s_add_u32 s64, s34, s10
	s_addc_u32 s65, s35, s11
	s_and_b64 s[10:11], s[0:1], exec
	s_cselect_b32 s12, s65, s7
	s_cselect_b32 s13, s64, s6
	s_ashr_i32 s61, s60, 31
	s_lshl_b64 s[10:11], s[60:61], 19
	s_add_u32 s66, s52, s10
	s_addc_u32 s67, s53, s11
	s_and_b64 s[10:11], s[0:1], exec
	s_cselect_b32 s14, s67, s9
	s_cselect_b32 s15, s66, s8
	s_add_u32 s6, s6, 0x40080
	s_addc_u32 s7, s7, 0
	s_add_u32 s16, s8, 0x100
	s_addc_u32 s17, s9, 0
	s_mov_b32 s61, -2
	ds_read_b128 v[146:149], v168
	ds_read_b128 v[150:153], v168 offset:1024
	ds_read_b128 v[154:157], v168 offset:2048
	ds_read_b128 v[158:161], v168 offset:3072
	ds_read_b128 v[172:175], v169
	ds_read_b128 v[176:179], v169 offset:1024
	ds_read_b128 v[180:183], v169 offset:2048
	ds_read_b128 v[184:187], v169 offset:3072
	s_add_u32 s8, s6, 0xfffc0080
	s_addc_u32 s9, s7, -1
	s_cmp_eq_u32 s61, 12
	s_cselect_b32 s11, s12, s9
	s_cselect_b32 s10, s13, s8
	s_cselect_b32 s9, s14, s17
	s_cselect_b32 s8, s15, s16
	v_lshl_add_u64 v[220:221], s[6:7], 0, v[138:139]
	s_add_i32 m0, s70, 0xc000
	ds_read_b128 v[188:191], v170
	ds_read_b128 v[192:195], v170 offset:1024
	ds_read_b128 v[196:199], v170 offset:2048
	ds_read_b128 v[200:203], v170 offset:3072
	ds_read_b128 v[204:207], v170 offset:4096
	ds_read_b128 v[208:211], v170 offset:5120
	ds_read_b128 v[212:215], v170 offset:6144
	ds_read_b128 v[216:219], v170 offset:7168
	global_load_lds_dwordx4 v[220:221], off
	v_lshl_add_u64 v[220:221], s[6:7], 0, v[140:141]
	s_add_i32 m0, s70, 0xe000
	s_nop 0
	global_load_lds_dwordx4 v[220:221], off
	s_waitcnt vmcnt(8)
	s_waitcnt lgkmcnt(0)
	s_barrier
	s_setprio 3
	s_waitcnt lgkmcnt(0)
	v_mfma_f32_16x16x32_bf16 v[126:129], v[146:149], v[188:191], 0
	v_mfma_f32_16x16x32_bf16 v[118:121], v[154:157], v[188:191], 0
	v_mfma_f32_16x16x32_bf16 v[110:113], v[146:149], v[196:199], 0
	v_mfma_f32_16x16x32_bf16 v[102:105], v[154:157], v[196:199], 0
	v_mfma_f32_16x16x32_bf16 v[94:97], v[146:149], v[204:207], 0
	v_mfma_f32_16x16x32_bf16 v[86:89], v[154:157], v[204:207], 0
	v_mfma_f32_16x16x32_bf16 v[78:81], v[146:149], v[212:215], 0
	v_mfma_f32_16x16x32_bf16 v[70:73], v[154:157], v[212:215], 0
	v_mfma_f32_16x16x32_bf16 v[126:129], v[150:153], v[192:195], v[126:129]
	v_mfma_f32_16x16x32_bf16 v[118:121], v[158:161], v[192:195], v[118:121]
	v_mfma_f32_16x16x32_bf16 v[110:113], v[150:153], v[200:203], v[110:113]
	v_mfma_f32_16x16x32_bf16 v[102:105], v[158:161], v[200:203], v[102:105]
	v_mfma_f32_16x16x32_bf16 v[94:97], v[150:153], v[208:211], v[94:97]
	v_mfma_f32_16x16x32_bf16 v[86:89], v[158:161], v[208:211], v[86:89]
	v_mfma_f32_16x16x32_bf16 v[78:81], v[150:153], v[216:219], v[78:81]
	v_mfma_f32_16x16x32_bf16 v[70:73], v[158:161], v[216:219], v[70:73]
	s_setprio 0
	s_setprio 3
	v_mfma_f32_16x16x32_bf16 v[122:125], v[172:175], v[188:191], 0
	v_mfma_f32_16x16x32_bf16 v[114:117], v[180:183], v[188:191], 0
	v_mfma_f32_16x16x32_bf16 v[106:109], v[172:175], v[196:199], 0
	v_mfma_f32_16x16x32_bf16 v[98:101], v[180:183], v[196:199], 0
	v_mfma_f32_16x16x32_bf16 v[90:93], v[172:175], v[204:207], 0
	v_mfma_f32_16x16x32_bf16 v[82:85], v[180:183], v[204:207], 0
	v_mfma_f32_16x16x32_bf16 v[74:77], v[172:175], v[212:215], 0
	v_mfma_f32_16x16x32_bf16 v[66:69], v[180:183], v[212:215], 0
	v_mfma_f32_16x16x32_bf16 v[122:125], v[176:179], v[192:195], v[122:125]
	v_mfma_f32_16x16x32_bf16 v[114:117], v[184:187], v[192:195], v[114:117]
	v_mfma_f32_16x16x32_bf16 v[106:109], v[176:179], v[200:203], v[106:109]
	v_mfma_f32_16x16x32_bf16 v[98:101], v[184:187], v[200:203], v[98:101]
	v_mfma_f32_16x16x32_bf16 v[90:93], v[176:179], v[208:211], v[90:93]
	v_mfma_f32_16x16x32_bf16 v[82:85], v[184:187], v[208:211], v[82:85]
	v_mfma_f32_16x16x32_bf16 v[74:77], v[176:179], v[216:219], v[74:77]
	v_mfma_f32_16x16x32_bf16 v[66:69], v[184:187], v[216:219], v[66:69]
	s_setprio 0
	s_barrier
	s_add_i32 s63, s80, s33
	v_lshl_add_u64 v[220:221], s[8:9], 0, v[132:133]
	s_mov_b32 m0, s63
	ds_read_b128 v[188:191], v170 offset:16384
	ds_read_b128 v[192:195], v170 offset:17408
	ds_read_b128 v[196:199], v170 offset:18432
	ds_read_b128 v[200:203], v170 offset:19456
	ds_read_b128 v[204:207], v170 offset:20480
	ds_read_b128 v[208:211], v170 offset:21504
	ds_read_b128 v[212:215], v170 offset:22528
	ds_read_b128 v[216:219], v170 offset:23552
	global_load_lds_dwordx4 v[220:221], off
	s_add_i32 m0, s63, 0x2000
	s_add_u32 s84, s8, 0x40000
	v_lshl_add_u64 v[222:223], s[8:9], 0, v[136:137]
	s_addc_u32 s85, s9, 0
	s_add_i32 s63, s81, s33
	global_load_lds_dwordx4 v[222:223], off
	v_lshl_add_u64 v[224:225], s[84:85], 0, v[132:133]
	s_mov_b32 m0, s63
	v_lshl_add_u64 v[226:227], s[10:11], 0, v[134:135]
	global_load_lds_dwordx4 v[224:225], off
	v_lshl_add_u64 v[224:225], s[84:85], 0, v[136:137]
	s_add_i32 m0, s63, 0x2000
	s_nop 0
	global_load_lds_dwordx4 v[224:225], off
	v_lshl_add_u64 v[224:225], s[10:11], 0, v[130:131]
	s_mov_b32 m0, s70
	s_nop 0
	global_load_lds_dwordx4 v[224:225], off
	s_mov_b32 m0, s71
	s_nop 0
	global_load_lds_dwordx4 v[226:227], off
	s_waitcnt vmcnt(8)
	s_waitcnt lgkmcnt(0)
	s_barrier
; #define PG8_STAGE(bufoff, gbase, voff) do { _Pragma("unroll") for (int _i = 0; _i < 2; ++_i) \
;         __builtin_amdgcn_global_load_lds((const unsigned*)((const char*)(gbase) + (voff)[_i]), (LAS unsigned*)(lds + (bufoff) + ldsw + _i * 8192), 16, 0, 0); } while (0)
; #define PG8_LDA(dst, b, h) do { _Pragma("unroll") for (int m = 0; m < 4; ++m) _Pragma("unroll") for (int k = 0; k < 2; ++k) dst[m][k] = *(const LAS bf16x8*)(lds + PG8_SA(b, h) + aoff + m * 2048 + k * 1024); } while (0)
; #define PG8_LDB(dst, b, h) do { _Pragma("unroll") for (int n = 0; n < 2; ++n) _Pragma("unroll") for (int k = 0; k < 2; ++k) dst[n][k] = *(const LAS bf16x8*)(lds + PG8_SB(b, h) + boff + n * 2048 + k * 1024); } while (0)
; #define PG8_MMA(ai, bj, At, Bt) do { __builtin_amdgcn_s_setprio(3); _Pragma("unroll") for (int m = 0; m < 4; ++m) _Pragma("unroll") for (int n = 0; n < 2; ++n) _Pragma("unroll") for (int k = 0; k < 2; ++k) \
;         acc[ai][bj][m][n] = __builtin_amdgcn_mfma_f32_16x16x32_bf16(Bt[n][k], At[m][k], acc[ai][bj][m][n], 0, 0, 0); __builtin_amdgcn_s_setprio(0); } while (0)
; #define PG8_WAIT_V(n) asm volatile("s_waitcnt vmcnt(" #n ")" ::: "memory")
; #define PG8_WAIT_L(n) asm volatile("s_waitcnt lgkmcnt(" #n ")" ::: "memory")
; #define PG8_BAR __builtin_amdgcn_s_barrier()
; #define PG8_SCHED __builtin_amdgcn_sched_barrier(0)
; template <class Epi, bool ALIGN_EPI>
; __device__ __forceinline__ void gemm_phase(LAS unsigned char* lds, const Gemm g, const StaticOrder& S, const Epi& E) {
;     ...
;             PG8_WAIT_V(8); PG8_WAIT_L(0); PG8_BAR; PG8_MMA(1, 0, At, B0); PG8_MMA(1, 1, At, B1); PG8_BAR; PG8_SCHED;
;             PG8_LDB(B0, 1, 0); PG8_LDB(B1, 1, 1); PG8_SCHED; PG8_LDA(At, 1, 0); PG8_STAGE(PG8_SA(0, 1), a2 + hstep, voffA);
;             PG8_WAIT_V(8); PG8_WAIT_L(0); PG8_BAR; PG8_MMA(0, 0, At, B0); PG8_MMA(0, 1, At, B1); PG8_BAR; PG8_SCHED;
	s_setprio 3
	s_waitcnt lgkmcnt(0)
	v_mfma_f32_16x16x32_bf16 v[62:65], v[146:149], v[188:191], 0
	v_mfma_f32_16x16x32_bf16 v[54:57], v[154:157], v[188:191], 0
	v_mfma_f32_16x16x32_bf16 v[46:49], v[146:149], v[196:199], 0
	v_mfma_f32_16x16x32_bf16 v[38:41], v[154:157], v[196:199], 0
	v_mfma_f32_16x16x32_bf16 v[30:33], v[146:149], v[204:207], 0
	v_mfma_f32_16x16x32_bf16 v[22:25], v[154:157], v[204:207], 0
	v_mfma_f32_16x16x32_bf16 v[14:17], v[146:149], v[212:215], 0
	v_mfma_f32_16x16x32_bf16 v[6:9], v[154:157], v[212:215], 0
	v_mfma_f32_16x16x32_bf16 v[62:65], v[150:153], v[192:195], v[62:65]
	v_mfma_f32_16x16x32_bf16 v[54:57], v[158:161], v[192:195], v[54:57]
	v_mfma_f32_16x16x32_bf16 v[46:49], v[150:153], v[200:203], v[46:49]
	v_mfma_f32_16x16x32_bf16 v[38:41], v[158:161], v[200:203], v[38:41]
	v_mfma_f32_16x16x32_bf16 v[30:33], v[150:153], v[208:211], v[30:33]
	v_mfma_f32_16x16x32_bf16 v[22:25], v[158:161], v[208:211], v[22:25]
	v_mfma_f32_16x16x32_bf16 v[14:17], v[150:153], v[216:219], v[14:17]
	v_mfma_f32_16x16x32_bf16 v[6:9], v[158:161], v[216:219], v[6:9]
	s_setprio 0
	s_setprio 3
	v_mfma_f32_16x16x32_bf16 v[58:61], v[172:175], v[188:191], 0
	v_mfma_f32_16x16x32_bf16 v[50:53], v[180:183], v[188:191], 0
	v_mfma_f32_16x16x32_bf16 v[42:45], v[172:175], v[196:199], 0
	v_mfma_f32_16x16x32_bf16 v[34:37], v[180:183], v[196:199], 0
	v_mfma_f32_16x16x32_bf16 v[26:29], v[172:175], v[204:207], 0
	v_mfma_f32_16x16x32_bf16 v[18:21], v[180:183], v[204:207], 0
	v_mfma_f32_16x16x32_bf16 v[10:13], v[172:175], v[212:215], 0
	v_mfma_f32_16x16x32_bf16 v[2:5], v[180:183], v[212:215], 0
	v_mfma_f32_16x16x32_bf16 v[58:61], v[176:179], v[192:195], v[58:61]
	v_mfma_f32_16x16x32_bf16 v[50:53], v[184:187], v[192:195], v[50:53]
	v_mfma_f32_16x16x32_bf16 v[42:45], v[176:179], v[200:203], v[42:45]
	v_mfma_f32_16x16x32_bf16 v[34:37], v[184:187], v[200:203], v[34:37]
	v_mfma_f32_16x16x32_bf16 v[26:29], v[176:179], v[208:211], v[26:29]
	v_mfma_f32_16x16x32_bf16 v[18:21], v[184:187], v[208:211], v[18:21]
	v_mfma_f32_16x16x32_bf16 v[10:13], v[176:179], v[216:219], v[10:13]
	v_mfma_f32_16x16x32_bf16 v[2:5], v[184:187], v[216:219], v[2:5]
	s_setprio 0
	s_barrier
	s_add_i32 s63, 0, 0x18000
	s_add_i32 s84, 0, 0x1c000
	v_add_u32_e32 v158, s63, v166
	v_add_u32_e32 v184, s84, v166
	ds_read_b128 v[146:149], v158
	ds_read_b128 v[150:153], v158 offset:1024
	ds_read_b128 v[154:157], v158 offset:2048
	ds_read_b128 v[158:161], v158 offset:3072
	ds_read_b128 v[172:175], v184
	ds_read_b128 v[176:179], v184 offset:1024
	ds_read_b128 v[180:183], v184 offset:2048
	ds_read_b128 v[184:187], v184 offset:3072
	s_add_u32 s10, s10, 0x40000
	s_addc_u32 s11, s11, 0
	s_mov_b32 m0, s72
	v_lshl_add_u64 v[228:229], s[10:11], 0, v[130:131]
	ds_read_b128 v[188:191], v170 offset:32768
	ds_read_b128 v[192:195], v170 offset:33792
	ds_read_b128 v[196:199], v170 offset:34816
	ds_read_b128 v[200:203], v170 offset:35840
	ds_read_b128 v[204:207], v170 offset:36864
	ds_read_b128 v[208:211], v170 offset:37888
	ds_read_b128 v[212:215], v170 offset:38912
	ds_read_b128 v[216:219], v170 offset:39936
	global_load_lds_dwordx4 v[228:229], off
	v_lshl_add_u64 v[228:229], s[10:11], 0, v[134:135]
	s_mov_b32 m0, s73
	s_nop 0
	global_load_lds_dwordx4 v[228:229], off
	s_waitcnt vmcnt(8)
	s_waitcnt lgkmcnt(0)
	s_barrier
	s_setprio 3
	s_waitcnt lgkmcnt(0)
	v_mfma_f32_16x16x32_bf16 v[126:129], v[146:149], v[188:191], v[126:129]
	v_mfma_f32_16x16x32_bf16 v[118:121], v[154:157], v[188:191], v[118:121]
	v_mfma_f32_16x16x32_bf16 v[110:113], v[146:149], v[196:199], v[110:113]
	v_mfma_f32_16x16x32_bf16 v[102:105], v[154:157], v[196:199], v[102:105]
	v_mfma_f32_16x16x32_bf16 v[94:97], v[146:149], v[204:207], v[94:97]
	v_mfma_f32_16x16x32_bf16 v[86:89], v[154:157], v[204:207], v[86:89]
	v_mfma_f32_16x16x32_bf16 v[78:81], v[146:149], v[212:215], v[78:81]
	v_mfma_f32_16x16x32_bf16 v[70:73], v[154:157], v[212:215], v[70:73]
	v_mfma_f32_16x16x32_bf16 v[126:129], v[150:153], v[192:195], v[126:129]
	v_mfma_f32_16x16x32_bf16 v[118:121], v[158:161], v[192:195], v[118:121]
	v_mfma_f32_16x16x32_bf16 v[110:113], v[150:153], v[200:203], v[110:113]
	v_mfma_f32_16x16x32_bf16 v[102:105], v[158:161], v[200:203], v[102:105]
	v_mfma_f32_16x16x32_bf16 v[94:97], v[150:153], v[208:211], v[94:97]
	v_mfma_f32_16x16x32_bf16 v[86:89], v[158:161], v[208:211], v[86:89]
	v_mfma_f32_16x16x32_bf16 v[78:81], v[150:153], v[216:219], v[78:81]
	v_mfma_f32_16x16x32_bf16 v[70:73], v[158:161], v[216:219], v[70:73]
	s_setprio 0
	s_setprio 3
	v_mfma_f32_16x16x32_bf16 v[122:125], v[172:175], v[188:191], v[122:125]
	v_mfma_f32_16x16x32_bf16 v[114:117], v[180:183], v[188:191], v[114:117]
	v_mfma_f32_16x16x32_bf16 v[106:109], v[172:175], v[196:199], v[106:109]
	v_mfma_f32_16x16x32_bf16 v[98:101], v[180:183], v[196:199], v[98:101]
	v_mfma_f32_16x16x32_bf16 v[90:93], v[172:175], v[204:207], v[90:93]
	v_mfma_f32_16x16x32_bf16 v[82:85], v[180:183], v[204:207], v[82:85]
	v_mfma_f32_16x16x32_bf16 v[74:77], v[172:175], v[212:215], v[74:77]
	v_mfma_f32_16x16x32_bf16 v[66:69], v[180:183], v[212:215], v[66:69]
	v_mfma_f32_16x16x32_bf16 v[122:125], v[176:179], v[192:195], v[122:125]
	v_mfma_f32_16x16x32_bf16 v[114:117], v[184:187], v[192:195], v[114:117]
	v_mfma_f32_16x16x32_bf16 v[106:109], v[176:179], v[200:203], v[106:109]
	v_mfma_f32_16x16x32_bf16 v[98:101], v[184:187], v[200:203], v[98:101]
	v_mfma_f32_16x16x32_bf16 v[90:93], v[176:179], v[208:211], v[90:93]
	v_mfma_f32_16x16x32_bf16 v[82:85], v[184:187], v[208:211], v[82:85]
	v_mfma_f32_16x16x32_bf16 v[74:77], v[176:179], v[216:219], v[74:77]
	v_mfma_f32_16x16x32_bf16 v[66:69], v[184:187], v[216:219], v[66:69]
	s_setprio 0
	s_barrier
; #define PG8_STAGE(bufoff, gbase, voff) do { _Pragma("unroll") for (int _i = 0; _i < 2; ++_i) \
;         __builtin_amdgcn_global_load_lds((const unsigned*)((const char*)(gbase) + (voff)[_i]), (LAS unsigned*)(lds + (bufoff) + ldsw + _i * 8192), 16, 0, 0); } while (0)
; #define PG8_LDA(dst, b, h) do { _Pragma("unroll") for (int m = 0; m < 4; ++m) _Pragma("unroll") for (int k = 0; k < 2; ++k) dst[m][k] = *(const LAS bf16x8*)(lds + PG8_SA(b, h) + aoff + m * 2048 + k * 1024); } while (0)
; #define PG8_MMA(ai, bj, At, Bt) do { __builtin_amdgcn_s_setprio(3); _Pragma("unroll") for (int m = 0; m < 4; ++m) _Pragma("unroll") for (int n = 0; n < 2; ++n) _Pragma("unroll") for (int k = 0; k < 2; ++k) \
;         acc[ai][bj][m][n] = __builtin_amdgcn_mfma_f32_16x16x32_bf16(Bt[n][k], At[m][k], acc[ai][bj][m][n], 0, 0, 0); __builtin_amdgcn_s_setprio(0); } while (0)
; #define PG8_WAIT_V(n) asm volatile("s_waitcnt vmcnt(" #n ")" ::: "memory")
; #define PG8_WAIT_L(n) asm volatile("s_waitcnt lgkmcnt(" #n ")" ::: "memory")
; #define PG8_BAR __builtin_amdgcn_s_barrier()
; #define PG8_SCHED __builtin_amdgcn_sched_barrier(0)
; template <class Epi, bool ALIGN_EPI>
; __device__ __forceinline__ void gemm_phase(LAS unsigned char* lds, const Gemm g, const StaticOrder& S, const Epi& E) {
;     ...
;             PG8_LDA(At, 1, 1); PG8_STAGE(PG8_SB(1, 0), b3, voffB); PG8_STAGE(PG8_SB(1, 1), b3 + hstep, voffB); PG8_STAGE(PG8_SA(1, 0), a3, voffA);
;             PG8_WAIT_V(8); PG8_WAIT_L(0); PG8_BAR; PG8_MMA(1, 0, At, B0); PG8_MMA(1, 1, At, B1); PG8_BAR; PG8_SCHED;
;         }
	s_add_i32 s10, s63, s33
	v_lshl_add_u64 v[220:221], v[220:221], 0, s[56:57]
	s_mov_b32 m0, s10
	ds_read_b128 v[188:191], v170 offset:49152
	ds_read_b128 v[192:195], v170 offset:50176
	ds_read_b128 v[196:199], v170 offset:51200
	ds_read_b128 v[200:203], v170 offset:52224
	ds_read_b128 v[204:207], v170 offset:53248
	ds_read_b128 v[208:211], v170 offset:54272
	ds_read_b128 v[212:215], v170 offset:55296
	ds_read_b128 v[216:219], v170 offset:56320
	global_load_lds_dwordx4 v[220:221], off
	s_add_i32 m0, s10, 0x2000
	s_add_u32 s8, s8, 0x40080
	v_lshl_add_u64 v[220:221], v[222:223], 0, s[56:57]
	s_addc_u32 s9, s9, 0
	s_add_i32 s10, s84, s33
	global_load_lds_dwordx4 v[220:221], off
	v_lshl_add_u64 v[220:221], s[8:9], 0, v[132:133]
	s_mov_b32 m0, s10
	s_nop 0
	global_load_lds_dwordx4 v[220:221], off
	v_lshl_add_u64 v[220:221], s[8:9], 0, v[136:137]
	s_add_i32 m0, s10, 0x2000
	s_nop 0
	global_load_lds_dwordx4 v[220:221], off
	v_lshl_add_u64 v[220:221], v[224:225], 0, s[56:57]
	s_mov_b32 m0, s78
	s_nop 0
	global_load_lds_dwordx4 v[220:221], off
	v_lshl_add_u64 v[220:221], v[226:227], 0, s[56:57]
	s_mov_b32 m0, s79
	s_nop 0
	global_load_lds_dwordx4 v[220:221], off
	s_waitcnt vmcnt(8)
	s_waitcnt lgkmcnt(0)
	s_barrier
	s_setprio 3
	s_waitcnt lgkmcnt(0)
	v_mfma_f32_16x16x32_bf16 v[62:65], v[146:149], v[188:191], v[62:65]
	v_mfma_f32_16x16x32_bf16 v[54:57], v[154:157], v[188:191], v[54:57]
	v_mfma_f32_16x16x32_bf16 v[46:49], v[146:149], v[196:199], v[46:49]
	v_mfma_f32_16x16x32_bf16 v[38:41], v[154:157], v[196:199], v[38:41]
	v_mfma_f32_16x16x32_bf16 v[30:33], v[146:149], v[204:207], v[30:33]
	v_mfma_f32_16x16x32_bf16 v[22:25], v[154:157], v[204:207], v[22:25]
	v_mfma_f32_16x16x32_bf16 v[14:17], v[146:149], v[212:215], v[14:17]
	v_mfma_f32_16x16x32_bf16 v[6:9], v[154:157], v[212:215], v[6:9]
	v_mfma_f32_16x16x32_bf16 v[62:65], v[150:153], v[192:195], v[62:65]
	v_mfma_f32_16x16x32_bf16 v[54:57], v[158:161], v[192:195], v[54:57]
	v_mfma_f32_16x16x32_bf16 v[46:49], v[150:153], v[200:203], v[46:49]
	v_mfma_f32_16x16x32_bf16 v[38:41], v[158:161], v[200:203], v[38:41]
	v_mfma_f32_16x16x32_bf16 v[30:33], v[150:153], v[208:211], v[30:33]
	v_mfma_f32_16x16x32_bf16 v[22:25], v[158:161], v[208:211], v[22:25]
	v_mfma_f32_16x16x32_bf16 v[14:17], v[150:153], v[216:219], v[14:17]
	v_mfma_f32_16x16x32_bf16 v[6:9], v[158:161], v[216:219], v[6:9]
	s_setprio 0
	s_setprio 3
	v_mfma_f32_16x16x32_bf16 v[58:61], v[172:175], v[188:191], v[58:61]
	v_mfma_f32_16x16x32_bf16 v[50:53], v[180:183], v[188:191], v[50:53]
	v_mfma_f32_16x16x32_bf16 v[42:45], v[172:175], v[196:199], v[42:45]
	v_mfma_f32_16x16x32_bf16 v[34:37], v[180:183], v[196:199], v[34:37]
	v_mfma_f32_16x16x32_bf16 v[26:29], v[172:175], v[204:207], v[26:29]
	v_mfma_f32_16x16x32_bf16 v[18:21], v[180:183], v[204:207], v[18:21]
	v_mfma_f32_16x16x32_bf16 v[10:13], v[172:175], v[212:215], v[10:13]
	v_mfma_f32_16x16x32_bf16 v[2:5], v[180:183], v[212:215], v[2:5]
	v_mfma_f32_16x16x32_bf16 v[58:61], v[176:179], v[192:195], v[58:61]
	v_mfma_f32_16x16x32_bf16 v[50:53], v[184:187], v[192:195], v[50:53]
	v_mfma_f32_16x16x32_bf16 v[42:45], v[176:179], v[200:203], v[42:45]
	v_mfma_f32_16x16x32_bf16 v[34:37], v[184:187], v[200:203], v[34:37]
	v_mfma_f32_16x16x32_bf16 v[26:29], v[176:179], v[208:211], v[26:29]
	v_mfma_f32_16x16x32_bf16 v[18:21], v[184:187], v[208:211], v[18:21]
	v_mfma_f32_16x16x32_bf16 v[10:13], v[176:179], v[216:219], v[10:13]
	v_mfma_f32_16x16x32_bf16 v[2:5], v[184:187], v[216:219], v[2:5]
	s_setprio 0
	s_barrier
	s_add_i32 s61, s61, 2
	s_add_u32 s6, s6, 0x100
	s_addc_u32 s7, s7, 0
	s_add_u32 s16, s16, 0x100
	s_addc_u32 s17, s17, 0

; #define PG8_STAGE(bufoff, gbase, voff) do { _Pragma("unroll") for (int _i = 0; _i < 2; ++_i) \
;         __builtin_amdgcn_global_load_lds((const unsigned*)((const char*)(gbase) + (voff)[_i]), (LAS unsigned*)(lds + (bufoff) + ldsw + _i * 8192), 16, 0, 0); } while (0)
; #define PG8_LDA(dst, b, h) do { _Pragma("unroll") for (int m = 0; m < 4; ++m) _Pragma("unroll") for (int k = 0; k < 2; ++k) dst[m][k] = *(const LAS bf16x8*)(lds + PG8_SA(b, h) + aoff + m * 2048 + k * 1024); } while (0)
; #define PG8_LDB(dst, b, h) do { _Pragma("unroll") for (int n = 0; n < 2; ++n) _Pragma("unroll") for (int k = 0; k < 2; ++k) dst[n][k] = *(const LAS bf16x8*)(lds + PG8_SB(b, h) + boff + n * 2048 + k * 1024); } while (0)
; #define PG8_WAIT_V(n) asm volatile("s_waitcnt vmcnt(" #n ")" ::: "memory")
; #define PG8_WAIT_L(n) asm volatile("s_waitcnt lgkmcnt(" #n ")" ::: "memory")
; #define PG8_BAR __builtin_amdgcn_s_barrier()
; #define PG8_SCHED __builtin_amdgcn_sched_barrier(0)
; template <class Epi, bool ALIGN_EPI>
; __device__ __forceinline__ void gemm_phase(LAS unsigned char* lds, const Gemm g, const StaticOrder& S, const Epi& E) {
;     ...
;         for (int t = 0; t < nt; t += 2) {
;             const bool last = (t == nt - 2);
;             const char* a1 = cA + (size_t)(t + 1) * kstep;
;             const char* a2 = last ? nA : cA + (size_t)(t + 2) * kstep; const char* b2 = last ? nB : cB + (size_t)(t + 2) * kstep;
;             const char* a3 = a2 + kstep; const char* b3 = b2 + kstep;
;             PG8_LDB(B0, 0, 0); PG8_LDB(B1, 0, 1); PG8_SCHED; PG8_LDA(At, 0, 0); PG8_STAGE(PG8_SA(1, 1), a1 + hstep, voffA);
;             PG8_WAIT_V(8); PG8_WAIT_L(0); PG8_BAR; PG8_MMA(0, 0, At, B0); PG8_MMA(0, 1, At, B1); PG8_BAR; PG8_SCHED;
;             PG8_LDA(At, 0, 1); PG8_STAGE(PG8_SB(0, 0), b2, voffB); PG8_STAGE(PG8_SB(0, 1), b2 + hstep, voffB); PG8_STAGE(PG8_SA(0, 0), a2, voffA);
;             PG8_WAIT_V(8); PG8_WAIT_L(0); PG8_BAR; PG8_MMA(1, 0, At, B0); PG8_MMA(1, 1, At, B1); PG8_BAR; PG8_SCHED;
;     ...
; #pragma unroll
;         for (int a = 0; a < 2; ++a)
; #pragma unroll
;             for (int b = 0; b < 2; ++b)
; #pragma unroll
;                 for (int m = 0; m < 4; ++m)
; #pragma unroll
;                     for (int n = 0; n < 2; ++n) acc[a][b][m][n] = (f32x4){0.f, 0.f, 0.f, 0.f};
.LBB0_695:
	s_add_u32 s50, s50, 0xb0080
	s_addc_u32 s51, s51, 0
	s_add_u32 s73, s52, 0x100
	s_addc_u32 s76, s53, 0
	s_mov_b32 s77, -2
	s_waitcnt lgkmcnt(0)
	ds_read_b128 v[130:133], v196
	ds_read_b128 v[134:137], v196 offset:1024
	ds_read_b128 v[138:141], v196 offset:2048
	ds_read_b128 v[142:145], v196 offset:3072
	ds_read_b128 v[146:149], v197
	ds_read_b128 v[150:153], v197 offset:1024
	ds_read_b128 v[170:173], v197 offset:2048
	ds_read_b128 v[174:177], v197 offset:3072
	s_add_u32 s52, s50, 0xfff50080
	s_addc_u32 s53, s51, -1
	s_cmp_eq_u32 s77, 40
	s_cselect_b32 s55, s5, s53
	s_cselect_b32 s54, s4, s52
	s_cselect_b32 s53, s19, s76
	s_cselect_b32 s52, s18, s73
	v_lshl_add_u64 v[186:187], s[50:51], 0, v[162:163]
	s_add_i32 m0, s58, 0xc000
	ds_read_b128 v[178:181], v198
	ds_read_b128 v[182:185], v198 offset:1024
	ds_read_b128 v[200:203], v198 offset:2048
	ds_read_b128 v[204:207], v198 offset:3072
	ds_read_b128 v[208:211], v198 offset:4096
	ds_read_b128 v[212:215], v198 offset:5120
	ds_read_b128 v[216:219], v198 offset:6144
	ds_read_b128 v[220:223], v198 offset:7168
	global_load_lds_dwordx4 v[186:187], off
	v_lshl_add_u64 v[186:187], s[50:51], 0, v[164:165]
	s_add_i32 m0, s58, 0xe000
	s_nop 0
	global_load_lds_dwordx4 v[186:187], off
	s_waitcnt vmcnt(8)
	s_waitcnt lgkmcnt(0)
	s_barrier
	s_setprio 3
	s_waitcnt lgkmcnt(0)
	v_mfma_f32_16x16x32_bf16 v[126:129], v[130:133], v[178:181], 0
	v_mfma_f32_16x16x32_bf16 v[122:125], v[138:141], v[178:181], 0
	v_mfma_f32_16x16x32_bf16 v[110:113], v[130:133], v[200:203], 0
	v_mfma_f32_16x16x32_bf16 v[106:109], v[138:141], v[200:203], 0
	v_mfma_f32_16x16x32_bf16 v[94:97], v[130:133], v[208:211], 0
	v_mfma_f32_16x16x32_bf16 v[90:93], v[138:141], v[208:211], 0
	v_mfma_f32_16x16x32_bf16 v[78:81], v[130:133], v[216:219], 0
	v_mfma_f32_16x16x32_bf16 v[74:77], v[138:141], v[216:219], 0
	v_mfma_f32_16x16x32_bf16 v[126:129], v[134:137], v[182:185], v[126:129]
	v_mfma_f32_16x16x32_bf16 v[122:125], v[142:145], v[182:185], v[122:125]
	v_mfma_f32_16x16x32_bf16 v[110:113], v[134:137], v[204:207], v[110:113]
	v_mfma_f32_16x16x32_bf16 v[106:109], v[142:145], v[204:207], v[106:109]
	v_mfma_f32_16x16x32_bf16 v[94:97], v[134:137], v[212:215], v[94:97]
	v_mfma_f32_16x16x32_bf16 v[90:93], v[142:145], v[212:215], v[90:93]
	v_mfma_f32_16x16x32_bf16 v[78:81], v[134:137], v[220:223], v[78:81]
	v_mfma_f32_16x16x32_bf16 v[74:77], v[142:145], v[220:223], v[74:77]
	s_setprio 0
	s_setprio 3
	v_mfma_f32_16x16x32_bf16 v[118:121], v[146:149], v[178:181], 0
	v_mfma_f32_16x16x32_bf16 v[114:117], v[170:173], v[178:181], 0
	v_mfma_f32_16x16x32_bf16 v[102:105], v[146:149], v[200:203], 0
	v_mfma_f32_16x16x32_bf16 v[98:101], v[170:173], v[200:203], 0
	v_mfma_f32_16x16x32_bf16 v[86:89], v[146:149], v[208:211], 0
	v_mfma_f32_16x16x32_bf16 v[82:85], v[170:173], v[208:211], 0
	v_mfma_f32_16x16x32_bf16 v[70:73], v[146:149], v[216:219], 0
	v_mfma_f32_16x16x32_bf16 v[66:69], v[170:173], v[216:219], 0
	v_mfma_f32_16x16x32_bf16 v[118:121], v[150:153], v[182:185], v[118:121]
	v_mfma_f32_16x16x32_bf16 v[114:117], v[174:177], v[182:185], v[114:117]
	v_mfma_f32_16x16x32_bf16 v[102:105], v[150:153], v[204:207], v[102:105]
	v_mfma_f32_16x16x32_bf16 v[98:101], v[174:177], v[204:207], v[98:101]
	v_mfma_f32_16x16x32_bf16 v[86:89], v[150:153], v[212:215], v[86:89]
	v_mfma_f32_16x16x32_bf16 v[82:85], v[174:177], v[212:215], v[82:85]
	v_mfma_f32_16x16x32_bf16 v[70:73], v[150:153], v[220:223], v[70:73]
	v_mfma_f32_16x16x32_bf16 v[66:69], v[174:177], v[220:223], v[66:69]
	s_setprio 0
	s_barrier
	s_add_i32 s78, s67, s57
	v_lshl_add_u64 v[186:187], s[52:53], 0, v[156:157]
	s_mov_b32 m0, s78
	ds_read_b128 v[178:181], v198 offset:16384
	ds_read_b128 v[182:185], v198 offset:17408
	ds_read_b128 v[200:203], v198 offset:18432
	ds_read_b128 v[204:207], v198 offset:19456
	ds_read_b128 v[208:211], v198 offset:20480
	ds_read_b128 v[212:215], v198 offset:21504
	ds_read_b128 v[216:219], v198 offset:22528
	ds_read_b128 v[220:223], v198 offset:23552
	global_load_lds_dwordx4 v[186:187], off
	s_add_i32 m0, s78, 0x2000
	s_add_u32 s78, s52, 0xb0000
	v_lshl_add_u64 v[224:225], s[52:53], 0, v[160:161]
	s_addc_u32 s79, s53, 0
	s_add_i32 s80, s68, s57
	global_load_lds_dwordx4 v[224:225], off
	v_lshl_add_u64 v[226:227], s[78:79], 0, v[156:157]
	s_mov_b32 m0, s80
	v_lshl_add_u64 v[228:229], s[54:55], 0, v[158:159]
	global_load_lds_dwordx4 v[226:227], off
	v_lshl_add_u64 v[226:227], s[78:79], 0, v[160:161]
	s_add_i32 m0, s80, 0x2000
	s_nop 0
	global_load_lds_dwordx4 v[226:227], off
	v_lshl_add_u64 v[226:227], s[54:55], 0, v[154:155]
	s_mov_b32 m0, s58
	s_nop 0
	global_load_lds_dwordx4 v[226:227], off
	s_mov_b32 m0, s59
	s_nop 0
	global_load_lds_dwordx4 v[228:229], off
	s_waitcnt vmcnt(8)
	s_waitcnt lgkmcnt(0)
	s_barrier
; #define PG8_STAGE(bufoff, gbase, voff) do { _Pragma("unroll") for (int _i = 0; _i < 2; ++_i) \
;         __builtin_amdgcn_global_load_lds((const unsigned*)((const char*)(gbase) + (voff)[_i]), (LAS unsigned*)(lds + (bufoff) + ldsw + _i * 8192), 16, 0, 0); } while (0)
; #define PG8_LDA(dst, b, h) do { _Pragma("unroll") for (int m = 0; m < 4; ++m) _Pragma("unroll") for (int k = 0; k < 2; ++k) dst[m][k] = *(const LAS bf16x8*)(lds + PG8_SA(b, h) + aoff + m * 2048 + k * 1024); } while (0)
; #define PG8_LDB(dst, b, h) do { _Pragma("unroll") for (int n = 0; n < 2; ++n) _Pragma("unroll") for (int k = 0; k < 2; ++k) dst[n][k] = *(const LAS bf16x8*)(lds + PG8_SB(b, h) + boff + n * 2048 + k * 1024); } while (0)
; #define PG8_MMA(ai, bj, At, Bt) do { __builtin_amdgcn_s_setprio(3); _Pragma("unroll") for (int m = 0; m < 4; ++m) _Pragma("unroll") for (int n = 0; n < 2; ++n) _Pragma("unroll") for (int k = 0; k < 2; ++k) \
;         acc[ai][bj][m][n] = __builtin_amdgcn_mfma_f32_16x16x32_bf16(Bt[n][k], At[m][k], acc[ai][bj][m][n], 0, 0, 0); __builtin_amdgcn_s_setprio(0); } while (0)
; #define PG8_WAIT_V(n) asm volatile("s_waitcnt vmcnt(" #n ")" ::: "memory")
; #define PG8_WAIT_L(n) asm volatile("s_waitcnt lgkmcnt(" #n ")" ::: "memory")
; #define PG8_BAR __builtin_amdgcn_s_barrier()
; #define PG8_SCHED __builtin_amdgcn_sched_barrier(0)
; template <class Epi, bool ALIGN_EPI>
; __device__ __forceinline__ void gemm_phase(LAS unsigned char* lds, const Gemm g, const StaticOrder& S, const Epi& E) {
;     ...
;             PG8_WAIT_V(8); PG8_WAIT_L(0); PG8_BAR; PG8_MMA(1, 0, At, B0); PG8_MMA(1, 1, At, B1); PG8_BAR; PG8_SCHED;
;             PG8_LDB(B0, 1, 0); PG8_LDB(B1, 1, 1); PG8_SCHED; PG8_LDA(At, 1, 0); PG8_STAGE(PG8_SA(0, 1), a2 + hstep, voffA);
;             PG8_WAIT_V(8); PG8_WAIT_L(0); PG8_BAR; PG8_MMA(0, 0, At, B0); PG8_MMA(0, 1, At, B1); PG8_BAR; PG8_SCHED;
	s_setprio 3
	s_waitcnt lgkmcnt(0)
	v_mfma_f32_16x16x32_bf16 v[62:65], v[130:133], v[178:181], 0
	v_mfma_f32_16x16x32_bf16 v[58:61], v[138:141], v[178:181], 0
	v_mfma_f32_16x16x32_bf16 v[46:49], v[130:133], v[200:203], 0
	v_mfma_f32_16x16x32_bf16 v[42:45], v[138:141], v[200:203], 0
	v_mfma_f32_16x16x32_bf16 v[30:33], v[130:133], v[208:211], 0
	v_mfma_f32_16x16x32_bf16 v[26:29], v[138:141], v[208:211], 0
	v_mfma_f32_16x16x32_bf16 v[14:17], v[130:133], v[216:219], 0
	v_mfma_f32_16x16x32_bf16 v[10:13], v[138:141], v[216:219], 0
	v_mfma_f32_16x16x32_bf16 v[62:65], v[134:137], v[182:185], v[62:65]
	v_mfma_f32_16x16x32_bf16 v[58:61], v[142:145], v[182:185], v[58:61]
	v_mfma_f32_16x16x32_bf16 v[46:49], v[134:137], v[204:207], v[46:49]
	v_mfma_f32_16x16x32_bf16 v[42:45], v[142:145], v[204:207], v[42:45]
	v_mfma_f32_16x16x32_bf16 v[30:33], v[134:137], v[212:215], v[30:33]
	v_mfma_f32_16x16x32_bf16 v[26:29], v[142:145], v[212:215], v[26:29]
	v_mfma_f32_16x16x32_bf16 v[14:17], v[134:137], v[220:223], v[14:17]
	v_mfma_f32_16x16x32_bf16 v[10:13], v[142:145], v[220:223], v[10:13]
	s_setprio 0
	s_setprio 3
	v_mfma_f32_16x16x32_bf16 v[54:57], v[146:149], v[178:181], 0
	v_mfma_f32_16x16x32_bf16 v[50:53], v[170:173], v[178:181], 0
	v_mfma_f32_16x16x32_bf16 v[38:41], v[146:149], v[200:203], 0
	v_mfma_f32_16x16x32_bf16 v[34:37], v[170:173], v[200:203], 0
	v_mfma_f32_16x16x32_bf16 v[22:25], v[146:149], v[208:211], 0
	v_mfma_f32_16x16x32_bf16 v[18:21], v[170:173], v[208:211], 0
	v_mfma_f32_16x16x32_bf16 v[6:9], v[146:149], v[216:219], 0
	v_mfma_f32_16x16x32_bf16 v[2:5], v[170:173], v[216:219], 0
	v_mfma_f32_16x16x32_bf16 v[54:57], v[150:153], v[182:185], v[54:57]
	v_mfma_f32_16x16x32_bf16 v[50:53], v[174:177], v[182:185], v[50:53]
	v_mfma_f32_16x16x32_bf16 v[38:41], v[150:153], v[204:207], v[38:41]
	v_mfma_f32_16x16x32_bf16 v[34:37], v[174:177], v[204:207], v[34:37]
	v_mfma_f32_16x16x32_bf16 v[22:25], v[150:153], v[212:215], v[22:25]
	v_mfma_f32_16x16x32_bf16 v[18:21], v[174:177], v[212:215], v[18:21]
	v_mfma_f32_16x16x32_bf16 v[6:9], v[150:153], v[220:223], v[6:9]
	v_mfma_f32_16x16x32_bf16 v[2:5], v[174:177], v[220:223], v[2:5]
	s_setprio 0
	s_barrier
	s_add_i32 s78, 0, 0x18000
	s_add_i32 s79, 0, 0x1c000
	v_add_u32_e32 v142, s78, v194
	v_add_u32_e32 v174, s79, v194
	ds_read_b128 v[130:133], v142
	ds_read_b128 v[134:137], v142 offset:1024
	ds_read_b128 v[138:141], v142 offset:2048
	ds_read_b128 v[142:145], v142 offset:3072
	ds_read_b128 v[146:149], v174
	ds_read_b128 v[150:153], v174 offset:1024
	ds_read_b128 v[170:173], v174 offset:2048
	ds_read_b128 v[174:177], v174 offset:3072
	s_add_u32 s54, s54, 0xb0000
	s_addc_u32 s55, s55, 0
	s_mov_b32 m0, s60
	v_lshl_add_u64 v[230:231], s[54:55], 0, v[154:155]
	ds_read_b128 v[178:181], v198 offset:32768
	ds_read_b128 v[182:185], v198 offset:33792
	ds_read_b128 v[200:203], v198 offset:34816
	ds_read_b128 v[204:207], v198 offset:35840
	ds_read_b128 v[208:211], v198 offset:36864
	ds_read_b128 v[212:215], v198 offset:37888
	ds_read_b128 v[216:219], v198 offset:38912
	ds_read_b128 v[220:223], v198 offset:39936
	global_load_lds_dwordx4 v[230:231], off
	v_lshl_add_u64 v[230:231], s[54:55], 0, v[158:159]
	s_mov_b32 m0, s61
	s_nop 0
	global_load_lds_dwordx4 v[230:231], off
	s_waitcnt vmcnt(8)
	s_waitcnt lgkmcnt(0)
	s_barrier
	s_setprio 3
	s_waitcnt lgkmcnt(0)
	v_mfma_f32_16x16x32_bf16 v[126:129], v[130:133], v[178:181], v[126:129]
	v_mfma_f32_16x16x32_bf16 v[122:125], v[138:141], v[178:181], v[122:125]
	v_mfma_f32_16x16x32_bf16 v[110:113], v[130:133], v[200:203], v[110:113]
	v_mfma_f32_16x16x32_bf16 v[106:109], v[138:141], v[200:203], v[106:109]
	v_mfma_f32_16x16x32_bf16 v[94:97], v[130:133], v[208:211], v[94:97]
	v_mfma_f32_16x16x32_bf16 v[90:93], v[138:141], v[208:211], v[90:93]
	v_mfma_f32_16x16x32_bf16 v[78:81], v[130:133], v[216:219], v[78:81]
	v_mfma_f32_16x16x32_bf16 v[74:77], v[138:141], v[216:219], v[74:77]
	v_mfma_f32_16x16x32_bf16 v[126:129], v[134:137], v[182:185], v[126:129]
	v_mfma_f32_16x16x32_bf16 v[122:125], v[142:145], v[182:185], v[122:125]
	v_mfma_f32_16x16x32_bf16 v[110:113], v[134:137], v[204:207], v[110:113]
	v_mfma_f32_16x16x32_bf16 v[106:109], v[142:145], v[204:207], v[106:109]
	v_mfma_f32_16x16x32_bf16 v[94:97], v[134:137], v[212:215], v[94:97]
	v_mfma_f32_16x16x32_bf16 v[90:93], v[142:145], v[212:215], v[90:93]
	v_mfma_f32_16x16x32_bf16 v[78:81], v[134:137], v[220:223], v[78:81]
	v_mfma_f32_16x16x32_bf16 v[74:77], v[142:145], v[220:223], v[74:77]
	s_setprio 0
	s_setprio 3
	v_mfma_f32_16x16x32_bf16 v[118:121], v[146:149], v[178:181], v[118:121]
	v_mfma_f32_16x16x32_bf16 v[114:117], v[170:173], v[178:181], v[114:117]
	v_mfma_f32_16x16x32_bf16 v[102:105], v[146:149], v[200:203], v[102:105]
	v_mfma_f32_16x16x32_bf16 v[98:101], v[170:173], v[200:203], v[98:101]
	v_mfma_f32_16x16x32_bf16 v[86:89], v[146:149], v[208:211], v[86:89]
	v_mfma_f32_16x16x32_bf16 v[82:85], v[170:173], v[208:211], v[82:85]
	v_mfma_f32_16x16x32_bf16 v[70:73], v[146:149], v[216:219], v[70:73]
	v_mfma_f32_16x16x32_bf16 v[66:69], v[170:173], v[216:219], v[66:69]
	v_mfma_f32_16x16x32_bf16 v[118:121], v[150:153], v[182:185], v[118:121]
	v_mfma_f32_16x16x32_bf16 v[114:117], v[174:177], v[182:185], v[114:117]
	v_mfma_f32_16x16x32_bf16 v[102:105], v[150:153], v[204:207], v[102:105]
	v_mfma_f32_16x16x32_bf16 v[98:101], v[174:177], v[204:207], v[98:101]
	v_mfma_f32_16x16x32_bf16 v[86:89], v[150:153], v[212:215], v[86:89]
	v_mfma_f32_16x16x32_bf16 v[82:85], v[174:177], v[212:215], v[82:85]
	v_mfma_f32_16x16x32_bf16 v[70:73], v[150:153], v[220:223], v[70:73]
	v_mfma_f32_16x16x32_bf16 v[66:69], v[174:177], v[220:223], v[66:69]
	s_setprio 0
	s_barrier
; #define PG8_STAGE(bufoff, gbase, voff) do { _Pragma("unroll") for (int _i = 0; _i < 2; ++_i) \
;         __builtin_amdgcn_global_load_lds((const unsigned*)((const char*)(gbase) + (voff)[_i]), (LAS unsigned*)(lds + (bufoff) + ldsw + _i * 8192), 16, 0, 0); } while (0)
; #define PG8_LDA(dst, b, h) do { _Pragma("unroll") for (int m = 0; m < 4; ++m) _Pragma("unroll") for (int k = 0; k < 2; ++k) dst[m][k] = *(const LAS bf16x8*)(lds + PG8_SA(b, h) + aoff + m * 2048 + k * 1024); } while (0)
; #define PG8_MMA(ai, bj, At, Bt) do { __builtin_amdgcn_s_setprio(3); _Pragma("unroll") for (int m = 0; m < 4; ++m) _Pragma("unroll") for (int n = 0; n < 2; ++n) _Pragma("unroll") for (int k = 0; k < 2; ++k) \
;         acc[ai][bj][m][n] = __builtin_amdgcn_mfma_f32_16x16x32_bf16(Bt[n][k], At[m][k], acc[ai][bj][m][n], 0, 0, 0); __builtin_amdgcn_s_setprio(0); } while (0)
; #define PG8_WAIT_V(n) asm volatile("s_waitcnt vmcnt(" #n ")" ::: "memory")
; #define PG8_WAIT_L(n) asm volatile("s_waitcnt lgkmcnt(" #n ")" ::: "memory")
; #define PG8_BAR __builtin_amdgcn_s_barrier()
; #define PG8_SCHED __builtin_amdgcn_sched_barrier(0)
; template <class Epi, bool ALIGN_EPI>
; __device__ __forceinline__ void gemm_phase(LAS unsigned char* lds, const Gemm g, const StaticOrder& S, const Epi& E) {
;     ...
;             PG8_LDA(At, 1, 1); PG8_STAGE(PG8_SB(1, 0), b3, voffB); PG8_STAGE(PG8_SB(1, 1), b3 + hstep, voffB); PG8_STAGE(PG8_SA(1, 0), a3, voffA);
;             PG8_WAIT_V(8); PG8_WAIT_L(0); PG8_BAR; PG8_MMA(1, 0, At, B0); PG8_MMA(1, 1, At, B1); PG8_BAR; PG8_SCHED;
;         }
	s_add_i32 s54, s78, s57
	v_lshl_add_u64 v[186:187], v[186:187], 0, s[14:15]
	s_mov_b32 m0, s54
	ds_read_b128 v[178:181], v198 offset:49152
	ds_read_b128 v[182:185], v198 offset:50176
	ds_read_b128 v[200:203], v198 offset:51200
	ds_read_b128 v[204:207], v198 offset:52224
	ds_read_b128 v[208:211], v198 offset:53248
	ds_read_b128 v[212:215], v198 offset:54272
	ds_read_b128 v[216:219], v198 offset:55296
	ds_read_b128 v[220:223], v198 offset:56320
	global_load_lds_dwordx4 v[186:187], off
	s_add_i32 m0, s54, 0x2000
	s_add_u32 s52, s52, 0xb0080
	v_lshl_add_u64 v[186:187], v[224:225], 0, s[14:15]
	s_addc_u32 s53, s53, 0
	s_add_i32 s54, s79, s57
	global_load_lds_dwordx4 v[186:187], off
	v_lshl_add_u64 v[186:187], s[52:53], 0, v[156:157]
	s_mov_b32 m0, s54
	s_nop 0
	global_load_lds_dwordx4 v[186:187], off
	v_lshl_add_u64 v[186:187], s[52:53], 0, v[160:161]
	s_add_i32 m0, s54, 0x2000
	s_nop 0
	global_load_lds_dwordx4 v[186:187], off
	v_lshl_add_u64 v[186:187], v[226:227], 0, s[14:15]
	s_mov_b32 m0, s63
	s_nop 0
	global_load_lds_dwordx4 v[186:187], off
	v_lshl_add_u64 v[186:187], v[228:229], 0, s[14:15]
	s_mov_b32 m0, s64
	s_nop 0
	global_load_lds_dwordx4 v[186:187], off
	s_waitcnt vmcnt(8)
	s_waitcnt lgkmcnt(0)
	s_barrier
	s_setprio 3
	s_waitcnt lgkmcnt(0)
	v_mfma_f32_16x16x32_bf16 v[62:65], v[130:133], v[178:181], v[62:65]
	v_mfma_f32_16x16x32_bf16 v[58:61], v[138:141], v[178:181], v[58:61]
	v_mfma_f32_16x16x32_bf16 v[46:49], v[130:133], v[200:203], v[46:49]
	v_mfma_f32_16x16x32_bf16 v[42:45], v[138:141], v[200:203], v[42:45]
	v_mfma_f32_16x16x32_bf16 v[30:33], v[130:133], v[208:211], v[30:33]
	v_mfma_f32_16x16x32_bf16 v[26:29], v[138:141], v[208:211], v[26:29]
	v_mfma_f32_16x16x32_bf16 v[14:17], v[130:133], v[216:219], v[14:17]
	v_mfma_f32_16x16x32_bf16 v[10:13], v[138:141], v[216:219], v[10:13]
	v_mfma_f32_16x16x32_bf16 v[62:65], v[134:137], v[182:185], v[62:65]
	v_mfma_f32_16x16x32_bf16 v[58:61], v[142:145], v[182:185], v[58:61]
	v_mfma_f32_16x16x32_bf16 v[46:49], v[134:137], v[204:207], v[46:49]
	v_mfma_f32_16x16x32_bf16 v[42:45], v[142:145], v[204:207], v[42:45]
	v_mfma_f32_16x16x32_bf16 v[30:33], v[134:137], v[212:215], v[30:33]
	v_mfma_f32_16x16x32_bf16 v[26:29], v[142:145], v[212:215], v[26:29]
	v_mfma_f32_16x16x32_bf16 v[14:17], v[134:137], v[220:223], v[14:17]
	v_mfma_f32_16x16x32_bf16 v[10:13], v[142:145], v[220:223], v[10:13]
	s_setprio 0
	s_setprio 3
	v_mfma_f32_16x16x32_bf16 v[54:57], v[146:149], v[178:181], v[54:57]
	v_mfma_f32_16x16x32_bf16 v[50:53], v[170:173], v[178:181], v[50:53]
	v_mfma_f32_16x16x32_bf16 v[38:41], v[146:149], v[200:203], v[38:41]
	v_mfma_f32_16x16x32_bf16 v[34:37], v[170:173], v[200:203], v[34:37]
	v_mfma_f32_16x16x32_bf16 v[22:25], v[146:149], v[208:211], v[22:25]
	v_mfma_f32_16x16x32_bf16 v[18:21], v[170:173], v[208:211], v[18:21]
	v_mfma_f32_16x16x32_bf16 v[6:9], v[146:149], v[216:219], v[6:9]
	v_mfma_f32_16x16x32_bf16 v[2:5], v[170:173], v[216:219], v[2:5]
	v_mfma_f32_16x16x32_bf16 v[54:57], v[150:153], v[182:185], v[54:57]
	v_mfma_f32_16x16x32_bf16 v[50:53], v[174:177], v[182:185], v[50:53]
	v_mfma_f32_16x16x32_bf16 v[38:41], v[150:153], v[204:207], v[38:41]
	v_mfma_f32_16x16x32_bf16 v[34:37], v[174:177], v[204:207], v[34:37]
	v_mfma_f32_16x16x32_bf16 v[22:25], v[150:153], v[212:215], v[22:25]
	v_mfma_f32_16x16x32_bf16 v[18:21], v[174:177], v[212:215], v[18:21]
	v_mfma_f32_16x16x32_bf16 v[6:9], v[150:153], v[220:223], v[6:9]
	v_mfma_f32_16x16x32_bf16 v[2:5], v[174:177], v[220:223], v[2:5]
	s_setprio 0
	s_barrier
	s_add_i32 s77, s77, 2
	s_add_u32 s50, s50, 0x100
	s_addc_u32 s51, s51, 0
	s_add_u32 s73, s73, 0x100
	s_addc_u32 s76, s76, 0

; #define PG8_STAGE(bufoff, gbase, voff) do { _Pragma("unroll") for (int _i = 0; _i < 2; ++_i) \
;         __builtin_amdgcn_global_load_lds((const unsigned*)((const char*)(gbase) + (voff)[_i]), (LAS unsigned*)(lds + (bufoff) + ldsw + _i * 8192), 16, 0, 0); } while (0)
; #define PG8_LDA(dst, b, h) do { _Pragma("unroll") for (int m = 0; m < 4; ++m) _Pragma("unroll") for (int k = 0; k < 2; ++k) dst[m][k] = *(const LAS bf16x8*)(lds + PG8_SA(b, h) + aoff + m * 2048 + k * 1024); } while (0)
; #define PG8_LDB(dst, b, h) do { _Pragma("unroll") for (int n = 0; n < 2; ++n) _Pragma("unroll") for (int k = 0; k < 2; ++k) dst[n][k] = *(const LAS bf16x8*)(lds + PG8_SB(b, h) + boff + n * 2048 + k * 1024); } while (0)
; #define PG8_MMA(ai, bj, At, Bt) do { __builtin_amdgcn_s_setprio(3); _Pragma("unroll") for (int m = 0; m < 4; ++m) _Pragma("unroll") for (int n = 0; n < 2; ++n) _Pragma("unroll") for (int k = 0; k < 2; ++k) \
;         acc[ai][bj][m][n] = __builtin_amdgcn_mfma_f32_16x16x32_bf16(Bt[n][k], At[m][k], acc[ai][bj][m][n], 0, 0, 0); __builtin_amdgcn_s_setprio(0); } while (0)
; #define PG8_WAIT_V(n) asm volatile("s_waitcnt vmcnt(" #n ")" ::: "memory")
; #define PG8_WAIT_L(n) asm volatile("s_waitcnt lgkmcnt(" #n ")" ::: "memory")
; #define PG8_BAR __builtin_amdgcn_s_barrier()
; template <class Epi, bool ALIGN_EPI>
; __device__ __forceinline__ void gemm_phase(LAS unsigned char* lds, const Gemm g, const StaticOrder& S, const Epi& E) {
;     ...
;         const char* nA = has_next ? (const char*)g.A + (size_t)nxt.pm * tstep : cA; const char* nB = has_next ? (const char*)g.Bt + (size_t)nxt.pn * tstep : cB;
;         for (int t = 0; t < nt; t += 2) {
;             const bool last = (t == nt - 2);
;             const char* a1 = cA + (size_t)(t + 1) * kstep;
;             const char* a2 = last ? nA : cA + (size_t)(t + 2) * kstep; const char* b2 = last ? nB : cB + (size_t)(t + 2) * kstep;
;             const char* a3 = a2 + kstep; const char* b3 = b2 + kstep;
;             PG8_LDB(B0, 0, 0); PG8_LDB(B1, 0, 1); PG8_SCHED; PG8_LDA(At, 0, 0); PG8_STAGE(PG8_SA(1, 1), a1 + hstep, voffA);
;             PG8_WAIT_V(8); PG8_WAIT_L(0); PG8_BAR; PG8_MMA(0, 0, At, B0); PG8_MMA(0, 1, At, B1); PG8_BAR; PG8_SCHED;
;             PG8_LDA(At, 0, 1); PG8_STAGE(PG8_SB(0, 0), b2, voffB); PG8_STAGE(PG8_SB(0, 1), b2 + hstep, voffB); PG8_STAGE(PG8_SA(0, 0), a2, voffA);
.LBB0_786:
	s_ashr_i32 s79, s78, 31
	s_lshl_b64 s[8:9], s[78:79], 19
	s_add_u32 s80, s34, s8
	s_addc_u32 s81, s35, s9
	s_and_b64 s[8:9], s[10:11], exec
	s_cselect_b32 s50, s81, s5
	s_cselect_b32 s55, s80, s4
	s_ashr_i32 s73, s72, 31
	s_lshl_b64 s[8:9], s[72:73], 19
	s_add_u32 s82, s18, s8
	s_addc_u32 s83, s19, s9
	s_and_b64 s[8:9], s[10:11], exec
	s_cselect_b32 s73, s83, s7
	s_cselect_b32 s79, s82, s6
	s_add_u32 s4, s4, 0x40080
	s_addc_u32 s5, s5, 0
	s_add_u32 s85, s6, 0x100
	s_addc_u32 s88, s7, 0
	s_mov_b32 s89, -2
	s_waitcnt lgkmcnt(0)
	ds_read_b128 v[130:133], v220
	ds_read_b128 v[134:137], v220 offset:1024
	ds_read_b128 v[138:141], v220 offset:2048
	ds_read_b128 v[142:145], v220 offset:3072
	ds_read_b128 v[166:169], v221
	ds_read_b128 v[170:173], v221 offset:1024
	ds_read_b128 v[174:177], v221 offset:2048
	ds_read_b128 v[178:181], v221 offset:3072
	s_add_u32 s6, s4, 0xfffc0080
	s_addc_u32 s7, s5, -1
	s_cmp_eq_u32 s89, 12
	s_cselect_b32 s9, s50, s7
	s_cselect_b32 s8, s55, s6
	s_cselect_b32 s7, s73, s88
	s_cselect_b32 s6, s79, s85
	v_lshl_add_u64 v[230:231], s[4:5], 0, v[158:159]
	s_add_i32 m0, s77, 0xc000
	ds_read_b128 v[182:185], v222
	ds_read_b128 v[186:189], v222 offset:1024
	ds_read_b128 v[190:193], v222 offset:2048
	ds_read_b128 v[194:197], v222 offset:3072
	ds_read_b128 v[198:201], v222 offset:4096
	ds_read_b128 v[202:205], v222 offset:5120
	ds_read_b128 v[206:209], v222 offset:6144
	ds_read_b128 v[226:229], v222 offset:7168
	global_load_lds_dwordx4 v[230:231], off
	v_lshl_add_u64 v[230:231], s[4:5], 0, v[160:161]
	s_add_i32 m0, s77, 0xe000
	s_nop 0
	global_load_lds_dwordx4 v[230:231], off
	s_waitcnt vmcnt(8)
	s_waitcnt lgkmcnt(0)
	s_barrier
	s_setprio 3
	s_waitcnt lgkmcnt(0)
	v_mfma_f32_16x16x32_bf16 v[126:129], v[130:133], v[182:185], 0
	v_mfma_f32_16x16x32_bf16 v[122:125], v[138:141], v[182:185], 0
	v_mfma_f32_16x16x32_bf16 v[110:113], v[130:133], v[190:193], 0
	v_mfma_f32_16x16x32_bf16 v[106:109], v[138:141], v[190:193], 0
	v_mfma_f32_16x16x32_bf16 v[94:97], v[130:133], v[198:201], 0
	v_mfma_f32_16x16x32_bf16 v[90:93], v[138:141], v[198:201], 0
	v_mfma_f32_16x16x32_bf16 v[78:81], v[130:133], v[206:209], 0
	v_mfma_f32_16x16x32_bf16 v[74:77], v[138:141], v[206:209], 0
	v_mfma_f32_16x16x32_bf16 v[126:129], v[134:137], v[186:189], v[126:129]
	v_mfma_f32_16x16x32_bf16 v[122:125], v[142:145], v[186:189], v[122:125]
	v_mfma_f32_16x16x32_bf16 v[110:113], v[134:137], v[194:197], v[110:113]
	v_mfma_f32_16x16x32_bf16 v[106:109], v[142:145], v[194:197], v[106:109]
	v_mfma_f32_16x16x32_bf16 v[94:97], v[134:137], v[202:205], v[94:97]
	v_mfma_f32_16x16x32_bf16 v[90:93], v[142:145], v[202:205], v[90:93]
	v_mfma_f32_16x16x32_bf16 v[78:81], v[134:137], v[226:229], v[78:81]
	v_mfma_f32_16x16x32_bf16 v[74:77], v[142:145], v[226:229], v[74:77]
	s_setprio 0
	s_setprio 3
	v_mfma_f32_16x16x32_bf16 v[118:121], v[166:169], v[182:185], 0
	v_mfma_f32_16x16x32_bf16 v[114:117], v[174:177], v[182:185], 0
	v_mfma_f32_16x16x32_bf16 v[102:105], v[166:169], v[190:193], 0
	v_mfma_f32_16x16x32_bf16 v[98:101], v[174:177], v[190:193], 0
	v_mfma_f32_16x16x32_bf16 v[86:89], v[166:169], v[198:201], 0
	v_mfma_f32_16x16x32_bf16 v[82:85], v[174:177], v[198:201], 0
	v_mfma_f32_16x16x32_bf16 v[70:73], v[166:169], v[206:209], 0
	v_mfma_f32_16x16x32_bf16 v[66:69], v[174:177], v[206:209], 0
	v_mfma_f32_16x16x32_bf16 v[118:121], v[170:173], v[186:189], v[118:121]
	v_mfma_f32_16x16x32_bf16 v[114:117], v[178:181], v[186:189], v[114:117]
	v_mfma_f32_16x16x32_bf16 v[102:105], v[170:173], v[194:197], v[102:105]
	v_mfma_f32_16x16x32_bf16 v[98:101], v[178:181], v[194:197], v[98:101]
	v_mfma_f32_16x16x32_bf16 v[86:89], v[170:173], v[202:205], v[86:89]
	v_mfma_f32_16x16x32_bf16 v[82:85], v[178:181], v[202:205], v[82:85]
	v_mfma_f32_16x16x32_bf16 v[70:73], v[170:173], v[226:229], v[70:73]
	v_mfma_f32_16x16x32_bf16 v[66:69], v[178:181], v[226:229], v[66:69]
	s_setprio 0
	s_barrier
	s_add_i32 s90, s69, s76
	v_lshl_add_u64 v[230:231], s[6:7], 0, v[148:149]
	s_mov_b32 m0, s90
	ds_read_b128 v[182:185], v222 offset:16384
	ds_read_b128 v[186:189], v222 offset:17408
	ds_read_b128 v[190:193], v222 offset:18432
	ds_read_b128 v[194:197], v222 offset:19456
	ds_read_b128 v[198:201], v222 offset:20480
	ds_read_b128 v[202:205], v222 offset:21504
	ds_read_b128 v[206:209], v222 offset:22528
	ds_read_b128 v[226:229], v222 offset:23552
	global_load_lds_dwordx4 v[230:231], off
	s_add_i32 m0, s90, 0x2000
	s_add_u32 s90, s6, 0x40000
	v_lshl_add_u64 v[232:233], s[6:7], 0, v[152:153]
	s_addc_u32 s91, s7, 0
	s_add_i32 s92, s70, s76
	global_load_lds_dwordx4 v[232:233], off
	v_lshl_add_u64 v[234:235], s[90:91], 0, v[148:149]
	s_mov_b32 m0, s92
	v_lshl_add_u64 v[236:237], s[8:9], 0, v[150:151]
	global_load_lds_dwordx4 v[234:235], off
	v_lshl_add_u64 v[234:235], s[90:91], 0, v[152:153]
	s_add_i32 m0, s92, 0x2000
	s_nop 0
	global_load_lds_dwordx4 v[234:235], off
	v_lshl_add_u64 v[234:235], s[8:9], 0, v[146:147]
	s_mov_b32 m0, s77
	s_nop 0
	global_load_lds_dwordx4 v[234:235], off
	s_mov_b32 m0, s87
	s_nop 0
	global_load_lds_dwordx4 v[236:237], off
	s_waitcnt vmcnt(8)
	s_waitcnt lgkmcnt(0)
	s_barrier
; #define PG8_STAGE(bufoff, gbase, voff) do { _Pragma("unroll") for (int _i = 0; _i < 2; ++_i) \
;         __builtin_amdgcn_global_load_lds((const unsigned*)((const char*)(gbase) + (voff)[_i]), (LAS unsigned*)(lds + (bufoff) + ldsw + _i * 8192), 16, 0, 0); } while (0)
; #define PG8_LDA(dst, b, h) do { _Pragma("unroll") for (int m = 0; m < 4; ++m) _Pragma("unroll") for (int k = 0; k < 2; ++k) dst[m][k] = *(const LAS bf16x8*)(lds + PG8_SA(b, h) + aoff + m * 2048 + k * 1024); } while (0)
; #define PG8_LDB(dst, b, h) do { _Pragma("unroll") for (int n = 0; n < 2; ++n) _Pragma("unroll") for (int k = 0; k < 2; ++k) dst[n][k] = *(const LAS bf16x8*)(lds + PG8_SB(b, h) + boff + n * 2048 + k * 1024); } while (0)
; #define PG8_MMA(ai, bj, At, Bt) do { __builtin_amdgcn_s_setprio(3); _Pragma("unroll") for (int m = 0; m < 4; ++m) _Pragma("unroll") for (int n = 0; n < 2; ++n) _Pragma("unroll") for (int k = 0; k < 2; ++k) \
;         acc[ai][bj][m][n] = __builtin_amdgcn_mfma_f32_16x16x32_bf16(Bt[n][k], At[m][k], acc[ai][bj][m][n], 0, 0, 0); __builtin_amdgcn_s_setprio(0); } while (0)
; #define PG8_WAIT_V(n) asm volatile("s_waitcnt vmcnt(" #n ")" ::: "memory")
; #define PG8_WAIT_L(n) asm volatile("s_waitcnt lgkmcnt(" #n ")" ::: "memory")
; #define PG8_BAR __builtin_amdgcn_s_barrier()
; #define PG8_SCHED __builtin_amdgcn_sched_barrier(0)
; template <class Epi, bool ALIGN_EPI>
; __device__ __forceinline__ void gemm_phase(LAS unsigned char* lds, const Gemm g, const StaticOrder& S, const Epi& E) {
;     ...
;             PG8_WAIT_V(8); PG8_WAIT_L(0); PG8_BAR; PG8_MMA(1, 0, At, B0); PG8_MMA(1, 1, At, B1); PG8_BAR; PG8_SCHED;
;             PG8_LDB(B0, 1, 0); PG8_LDB(B1, 1, 1); PG8_SCHED; PG8_LDA(At, 1, 0); PG8_STAGE(PG8_SA(0, 1), a2 + hstep, voffA);
;             PG8_WAIT_V(8); PG8_WAIT_L(0); PG8_BAR; PG8_MMA(0, 0, At, B0); PG8_MMA(0, 1, At, B1); PG8_BAR; PG8_SCHED;
	s_setprio 3
	s_waitcnt lgkmcnt(0)
	v_mfma_f32_16x16x32_bf16 v[62:65], v[130:133], v[182:185], 0
	v_mfma_f32_16x16x32_bf16 v[58:61], v[138:141], v[182:185], 0
	v_mfma_f32_16x16x32_bf16 v[46:49], v[130:133], v[190:193], 0
	v_mfma_f32_16x16x32_bf16 v[42:45], v[138:141], v[190:193], 0
	v_mfma_f32_16x16x32_bf16 v[30:33], v[130:133], v[198:201], 0
	v_mfma_f32_16x16x32_bf16 v[26:29], v[138:141], v[198:201], 0
	v_mfma_f32_16x16x32_bf16 v[14:17], v[130:133], v[206:209], 0
	v_mfma_f32_16x16x32_bf16 v[10:13], v[138:141], v[206:209], 0
	v_mfma_f32_16x16x32_bf16 v[62:65], v[134:137], v[186:189], v[62:65]
	v_mfma_f32_16x16x32_bf16 v[58:61], v[142:145], v[186:189], v[58:61]
	v_mfma_f32_16x16x32_bf16 v[46:49], v[134:137], v[194:197], v[46:49]
	v_mfma_f32_16x16x32_bf16 v[42:45], v[142:145], v[194:197], v[42:45]
	v_mfma_f32_16x16x32_bf16 v[30:33], v[134:137], v[202:205], v[30:33]
	v_mfma_f32_16x16x32_bf16 v[26:29], v[142:145], v[202:205], v[26:29]
	v_mfma_f32_16x16x32_bf16 v[14:17], v[134:137], v[226:229], v[14:17]
	v_mfma_f32_16x16x32_bf16 v[10:13], v[142:145], v[226:229], v[10:13]
	s_setprio 0
	s_setprio 3
	v_mfma_f32_16x16x32_bf16 v[54:57], v[166:169], v[182:185], 0
	v_mfma_f32_16x16x32_bf16 v[50:53], v[174:177], v[182:185], 0
	v_mfma_f32_16x16x32_bf16 v[38:41], v[166:169], v[190:193], 0
	v_mfma_f32_16x16x32_bf16 v[34:37], v[174:177], v[190:193], 0
	v_mfma_f32_16x16x32_bf16 v[22:25], v[166:169], v[198:201], 0
	v_mfma_f32_16x16x32_bf16 v[18:21], v[174:177], v[198:201], 0
	v_mfma_f32_16x16x32_bf16 v[6:9], v[166:169], v[206:209], 0
	v_mfma_f32_16x16x32_bf16 v[2:5], v[174:177], v[206:209], 0
	v_mfma_f32_16x16x32_bf16 v[54:57], v[170:173], v[186:189], v[54:57]
	v_mfma_f32_16x16x32_bf16 v[50:53], v[178:181], v[186:189], v[50:53]
	v_mfma_f32_16x16x32_bf16 v[38:41], v[170:173], v[194:197], v[38:41]
	v_mfma_f32_16x16x32_bf16 v[34:37], v[178:181], v[194:197], v[34:37]
	v_mfma_f32_16x16x32_bf16 v[22:25], v[170:173], v[202:205], v[22:25]
	v_mfma_f32_16x16x32_bf16 v[18:21], v[178:181], v[202:205], v[18:21]
	v_mfma_f32_16x16x32_bf16 v[6:9], v[170:173], v[226:229], v[6:9]
	v_mfma_f32_16x16x32_bf16 v[2:5], v[178:181], v[226:229], v[2:5]
	s_setprio 0
	s_barrier
	s_add_i32 s90, 0, 0x18000
	s_add_i32 s91, 0, 0x1c000
	v_add_u32_e32 v142, s90, v217
	v_add_u32_e32 v154, s91, v217
	ds_read_b128 v[130:133], v142
	ds_read_b128 v[134:137], v142 offset:1024
	ds_read_b128 v[138:141], v142 offset:2048
	ds_read_b128 v[142:145], v142 offset:3072
	ds_read_b128 v[166:169], v154
	ds_read_b128 v[170:173], v154 offset:1024
	ds_read_b128 v[174:177], v154 offset:2048
	ds_read_b128 v[178:181], v154 offset:3072
	s_add_u32 s8, s8, 0x40000
	s_addc_u32 s9, s9, 0
	s_mov_b32 m0, s33
	v_lshl_add_u64 v[238:239], s[8:9], 0, v[146:147]
	ds_read_b128 v[182:185], v222 offset:32768
	ds_read_b128 v[186:189], v222 offset:33792
	ds_read_b128 v[190:193], v222 offset:34816
	ds_read_b128 v[194:197], v222 offset:35840
	ds_read_b128 v[198:201], v222 offset:36864
	ds_read_b128 v[202:205], v222 offset:37888
	ds_read_b128 v[206:209], v222 offset:38912
	ds_read_b128 v[226:229], v222 offset:39936
	global_load_lds_dwordx4 v[238:239], off
	v_lshl_add_u64 v[238:239], s[8:9], 0, v[150:151]
	s_mov_b32 m0, s14
	s_nop 0
	global_load_lds_dwordx4 v[238:239], off
	s_waitcnt vmcnt(8)
	s_waitcnt lgkmcnt(0)
	s_barrier
	s_setprio 3
	s_waitcnt lgkmcnt(0)
	v_mfma_f32_16x16x32_bf16 v[126:129], v[130:133], v[182:185], v[126:129]
	v_mfma_f32_16x16x32_bf16 v[122:125], v[138:141], v[182:185], v[122:125]
	v_mfma_f32_16x16x32_bf16 v[110:113], v[130:133], v[190:193], v[110:113]
	v_mfma_f32_16x16x32_bf16 v[106:109], v[138:141], v[190:193], v[106:109]
	v_mfma_f32_16x16x32_bf16 v[94:97], v[130:133], v[198:201], v[94:97]
	v_mfma_f32_16x16x32_bf16 v[90:93], v[138:141], v[198:201], v[90:93]
	v_mfma_f32_16x16x32_bf16 v[78:81], v[130:133], v[206:209], v[78:81]
	v_mfma_f32_16x16x32_bf16 v[74:77], v[138:141], v[206:209], v[74:77]
	v_mfma_f32_16x16x32_bf16 v[126:129], v[134:137], v[186:189], v[126:129]
	v_mfma_f32_16x16x32_bf16 v[122:125], v[142:145], v[186:189], v[122:125]
	v_mfma_f32_16x16x32_bf16 v[110:113], v[134:137], v[194:197], v[110:113]
	v_mfma_f32_16x16x32_bf16 v[106:109], v[142:145], v[194:197], v[106:109]
	v_mfma_f32_16x16x32_bf16 v[94:97], v[134:137], v[202:205], v[94:97]
	v_mfma_f32_16x16x32_bf16 v[90:93], v[142:145], v[202:205], v[90:93]
	v_mfma_f32_16x16x32_bf16 v[78:81], v[134:137], v[226:229], v[78:81]
	v_mfma_f32_16x16x32_bf16 v[74:77], v[142:145], v[226:229], v[74:77]
	s_setprio 0
	s_setprio 3
	v_mfma_f32_16x16x32_bf16 v[118:121], v[166:169], v[182:185], v[118:121]
	v_mfma_f32_16x16x32_bf16 v[114:117], v[174:177], v[182:185], v[114:117]
	v_mfma_f32_16x16x32_bf16 v[102:105], v[166:169], v[190:193], v[102:105]
	v_mfma_f32_16x16x32_bf16 v[98:101], v[174:177], v[190:193], v[98:101]
	v_mfma_f32_16x16x32_bf16 v[86:89], v[166:169], v[198:201], v[86:89]
	v_mfma_f32_16x16x32_bf16 v[82:85], v[174:177], v[198:201], v[82:85]
	v_mfma_f32_16x16x32_bf16 v[70:73], v[166:169], v[206:209], v[70:73]
	v_mfma_f32_16x16x32_bf16 v[66:69], v[174:177], v[206:209], v[66:69]
	v_mfma_f32_16x16x32_bf16 v[118:121], v[170:173], v[186:189], v[118:121]
	v_mfma_f32_16x16x32_bf16 v[114:117], v[178:181], v[186:189], v[114:117]
	v_mfma_f32_16x16x32_bf16 v[102:105], v[170:173], v[194:197], v[102:105]
	v_mfma_f32_16x16x32_bf16 v[98:101], v[178:181], v[194:197], v[98:101]
	v_mfma_f32_16x16x32_bf16 v[86:89], v[170:173], v[202:205], v[86:89]
	v_mfma_f32_16x16x32_bf16 v[82:85], v[178:181], v[202:205], v[82:85]
	v_mfma_f32_16x16x32_bf16 v[70:73], v[170:173], v[226:229], v[70:73]
	v_mfma_f32_16x16x32_bf16 v[66:69], v[178:181], v[226:229], v[66:69]
	s_setprio 0
	s_barrier
; #define PG8_STAGE(bufoff, gbase, voff) do { _Pragma("unroll") for (int _i = 0; _i < 2; ++_i) \
;         __builtin_amdgcn_global_load_lds((const unsigned*)((const char*)(gbase) + (voff)[_i]), (LAS unsigned*)(lds + (bufoff) + ldsw + _i * 8192), 16, 0, 0); } while (0)
; #define PG8_LDA(dst, b, h) do { _Pragma("unroll") for (int m = 0; m < 4; ++m) _Pragma("unroll") for (int k = 0; k < 2; ++k) dst[m][k] = *(const LAS bf16x8*)(lds + PG8_SA(b, h) + aoff + m * 2048 + k * 1024); } while (0)
; #define PG8_MMA(ai, bj, At, Bt) do { __builtin_amdgcn_s_setprio(3); _Pragma("unroll") for (int m = 0; m < 4; ++m) _Pragma("unroll") for (int n = 0; n < 2; ++n) _Pragma("unroll") for (int k = 0; k < 2; ++k) \
;         acc[ai][bj][m][n] = __builtin_amdgcn_mfma_f32_16x16x32_bf16(Bt[n][k], At[m][k], acc[ai][bj][m][n], 0, 0, 0); __builtin_amdgcn_s_setprio(0); } while (0)
; #define PG8_WAIT_V(n) asm volatile("s_waitcnt vmcnt(" #n ")" ::: "memory")
; #define PG8_WAIT_L(n) asm volatile("s_waitcnt lgkmcnt(" #n ")" ::: "memory")
; #define PG8_BAR __builtin_amdgcn_s_barrier()
; #define PG8_SCHED __builtin_amdgcn_sched_barrier(0)
; template <class Epi, bool ALIGN_EPI>
; __device__ __forceinline__ void gemm_phase(LAS unsigned char* lds, const Gemm g, const StaticOrder& S, const Epi& E) {
;     ...
;             PG8_LDA(At, 1, 1); PG8_STAGE(PG8_SB(1, 0), b3, voffB); PG8_STAGE(PG8_SB(1, 1), b3 + hstep, voffB); PG8_STAGE(PG8_SA(1, 0), a3, voffA);
;             PG8_WAIT_V(8); PG8_WAIT_L(0); PG8_BAR; PG8_MMA(1, 0, At, B0); PG8_MMA(1, 1, At, B1); PG8_BAR; PG8_SCHED;
	s_add_i32 s8, s90, s76
	v_lshl_add_u64 v[230:231], v[230:231], 0, s[60:61]
	s_mov_b32 m0, s8
	ds_read_b128 v[182:185], v222 offset:49152
	ds_read_b128 v[186:189], v222 offset:50176
	ds_read_b128 v[190:193], v222 offset:51200
	ds_read_b128 v[194:197], v222 offset:52224
	ds_read_b128 v[198:201], v222 offset:53248
	ds_read_b128 v[202:205], v222 offset:54272
	ds_read_b128 v[206:209], v222 offset:55296
	ds_read_b128 v[226:229], v222 offset:56320
	global_load_lds_dwordx4 v[230:231], off
	s_add_i32 m0, s8, 0x2000
	s_add_u32 s6, s6, 0x40080
	v_lshl_add_u64 v[230:231], v[232:233], 0, s[60:61]
	s_addc_u32 s7, s7, 0
	s_add_i32 s8, s91, s76
	global_load_lds_dwordx4 v[230:231], off
	v_lshl_add_u64 v[230:231], s[6:7], 0, v[148:149]
	s_mov_b32 m0, s8
	s_nop 0
	global_load_lds_dwordx4 v[230:231], off
	v_lshl_add_u64 v[230:231], s[6:7], 0, v[152:153]
	s_add_i32 m0, s8, 0x2000
	s_nop 0
	global_load_lds_dwordx4 v[230:231], off
	v_lshl_add_u64 v[230:231], v[234:235], 0, s[60:61]
	s_mov_b32 m0, s65
	s_nop 0
	global_load_lds_dwordx4 v[230:231], off
	v_lshl_add_u64 v[230:231], v[236:237], 0, s[60:61]
	s_mov_b32 m0, s66
	s_nop 0
	global_load_lds_dwordx4 v[230:231], off
	s_waitcnt vmcnt(8)
	s_waitcnt lgkmcnt(0)
	s_barrier
	s_setprio 3
	s_waitcnt lgkmcnt(0)
	v_mfma_f32_16x16x32_bf16 v[62:65], v[130:133], v[182:185], v[62:65]
	v_mfma_f32_16x16x32_bf16 v[58:61], v[138:141], v[182:185], v[58:61]
	v_mfma_f32_16x16x32_bf16 v[46:49], v[130:133], v[190:193], v[46:49]
	v_mfma_f32_16x16x32_bf16 v[42:45], v[138:141], v[190:193], v[42:45]
	v_mfma_f32_16x16x32_bf16 v[30:33], v[130:133], v[198:201], v[30:33]
	v_mfma_f32_16x16x32_bf16 v[26:29], v[138:141], v[198:201], v[26:29]
	v_mfma_f32_16x16x32_bf16 v[14:17], v[130:133], v[206:209], v[14:17]
	v_mfma_f32_16x16x32_bf16 v[10:13], v[138:141], v[206:209], v[10:13]
	v_mfma_f32_16x16x32_bf16 v[62:65], v[134:137], v[186:189], v[62:65]
	v_mfma_f32_16x16x32_bf16 v[58:61], v[142:145], v[186:189], v[58:61]
	v_mfma_f32_16x16x32_bf16 v[46:49], v[134:137], v[194:197], v[46:49]
	v_mfma_f32_16x16x32_bf16 v[42:45], v[142:145], v[194:197], v[42:45]
	v_mfma_f32_16x16x32_bf16 v[30:33], v[134:137], v[202:205], v[30:33]
	v_mfma_f32_16x16x32_bf16 v[26:29], v[142:145], v[202:205], v[26:29]
	v_mfma_f32_16x16x32_bf16 v[14:17], v[134:137], v[226:229], v[14:17]
	v_mfma_f32_16x16x32_bf16 v[10:13], v[142:145], v[226:229], v[10:13]
	s_setprio 0
	s_setprio 3
	v_mfma_f32_16x16x32_bf16 v[54:57], v[166:169], v[182:185], v[54:57]
	v_mfma_f32_16x16x32_bf16 v[50:53], v[174:177], v[182:185], v[50:53]
	v_mfma_f32_16x16x32_bf16 v[38:41], v[166:169], v[190:193], v[38:41]
	v_mfma_f32_16x16x32_bf16 v[34:37], v[174:177], v[190:193], v[34:37]
	v_mfma_f32_16x16x32_bf16 v[22:25], v[166:169], v[198:201], v[22:25]
	v_mfma_f32_16x16x32_bf16 v[18:21], v[174:177], v[198:201], v[18:21]
	v_mfma_f32_16x16x32_bf16 v[6:9], v[166:169], v[206:209], v[6:9]
	v_mfma_f32_16x16x32_bf16 v[2:5], v[174:177], v[206:209], v[2:5]
	v_mfma_f32_16x16x32_bf16 v[54:57], v[170:173], v[186:189], v[54:57]
	v_mfma_f32_16x16x32_bf16 v[50:53], v[178:181], v[186:189], v[50:53]
	v_mfma_f32_16x16x32_bf16 v[38:41], v[170:173], v[194:197], v[38:41]
	v_mfma_f32_16x16x32_bf16 v[34:37], v[178:181], v[194:197], v[34:37]
	v_mfma_f32_16x16x32_bf16 v[22:25], v[170:173], v[202:205], v[22:25]
	v_mfma_f32_16x16x32_bf16 v[18:21], v[178:181], v[202:205], v[18:21]
	v_mfma_f32_16x16x32_bf16 v[6:9], v[170:173], v[226:229], v[6:9]
	v_mfma_f32_16x16x32_bf16 v[2:5], v[178:181], v[226:229], v[2:5]
	s_setprio 0
	s_barrier
	s_add_i32 s89, s89, 2
	s_add_u32 s4, s4, 0x100
	s_addc_u32 s5, s5, 0
	s_add_u32 s85, s85, 0x100
	s_addc_u32 s88, s88, 0

; #define LAS __attribute__((address_space(3)))
; template <bool SAMPLE>
; DI void attn_unit(const Params& p, LAS unsigned char* lds, int b, int cp, int hp) {
;     ...
;     const int tid = tid_, lane = tid & 63, w = __builtin_amdgcn_readfirstlane(tid >> 6), r32 = lane & 31, h = lane >> 5;
;     const int cl = SAMPLE ? 0 : (w >> 2), hl = (w >> 1) & 1, head = hp * 2 + hl, qoff = SAMPLE ? 0 : 32 * (w & 1);
;     const bf16_t* Qb = (const bf16_t*)(p.ws + WS_A);
;     bf16_t* CAT = (bf16_t*)(p.ws + WS_CAT);
;     const size_t qrow = SAMPLE ? (size_t)MP + b * 16 + (r32 & 15) : (size_t)b * SEQ + (2 * cp + cl) * 64 + qoff + r32;
;     bf16x8 qf[4];
; #pragma unroll
;     for (int d0 = 0; d0 < 4; ++d0) qf[d0] = *(const bf16x8*)(Qb + qrow * MW + head * 64 + d0 * 16 + h * 8);
;     LAS float* bt = (LAS float*)(lds + AT_B);
;     const int j_first = SAMPLE ? 0 : (cp >= 4 ? 0 : 8 - 2 * cp), j_last = SAMPLE ? 8 : 9;
;     u32x4 ka[2], va_[2], kb_[2], vb_[2];
;     attn_load_tile<SAMPLE>(p, b, cp, hp, j_first, ka, va_);
;     __syncthreads();
;     attn_store_tile(lds + (j_first & 1) * AT_BUF, ka, va_);
;     attn_load_tile<SAMPLE>(p, b, cp, hp, j_first + 1, ka, va_);
;     if (j_first + 2 <= j_last) attn_load_tile<SAMPLE>(p, b, cp, hp, j_first + 2, kb_, vb_);
; DI void phase_mix_odd(const Params& p, LAS unsigned char* lds) {
;     ...
;             { LAS float* bt = (LAS float*)(lds + AT_B); const float* relb = p.in[18]; const int hp = uid & 3;
;               __syncthreads();
;               for (int i = threadIdx.x; i < 2 * 513; i += 512) { const int hh = i >= 513 ? 1 : 0, j = i - hh * 513; bt[hh * 516 + j] = relb[(hp * 2 + hh) * 513 + j] * LOG2E; } }
;             if (uid < 1024) attn_unit<false>(p, lds, (uid & 31) >> 2, uid >> 5, uid & 3);
;             else { const int s_ = uid - 1024; attn_unit<true>(p, lds, s_ >> 2, 0, s_ & 3); }
.LBB0_1004:
	v_cmp_lt_u32_e32 vcc, s73, v3
	v_cmp_lt_u32_e64 s[4:5], s78, v3
	s_or_b64 s[10:11], s[4:5], s[10:11]
	v_cndmask_b32_e64 v4, 0, 1, vcc
	v_cndmask_b32_e32 v5, 0, v186, vcc
	v_or_b32_e32 v4, s9, v4
	v_add_u32_e32 v6, v5, v3
	v_mad_u32_u24 v4, v4, s78, v6
	v_ashrrev_i32_e32 v5, 31, v4
	v_lshl_add_u64 v[4:5], v[4:5], 2, s[40:41]
	global_load_dword v4, v[4:5], off
	v_add_u32_e32 v5, 0x200, v3
	v_cndmask_b32_e32 v7, 0, v187, vcc
	v_mov_b32_e32 v3, v5
	v_lshlrev_b32_e32 v5, 2, v6
	v_add3_u32 v5, s79, v7, v5
	s_waitcnt vmcnt(0)
	v_mul_f32_e32 v4, 0x3fb8aa3b, v4
	ds_write_b32 v5, v4
	s_andn2_b64 exec, exec, s[10:11]
	s_cbranch_execnz .LBB0_1004
	s_or_b64 exec, exec, s[10:11]
	s_cmpk_gt_i32 s85, 0x3ff
	s_cbranch_scc0 .LBB0_1038
	s_add_i32 s4, s85, 0xfffffc00
	s_lshr_b32 s4, s4, 2
	v_mov_b32_e32 v3, v148
	s_lshl_b32 s5, s4, 4
	v_readfirstlane_b32 s13, v3
	s_bfe_u32 s9, s13, 0x10007
	s_add_i32 s18, s5, 0x8000
	v_and_or_b32 v168, v3, 15, s18
	v_mov_b32_e32 v169, v2
	s_lshl_b32 s19, s12, 7
	s_lshl_b32 s5, s9, 6
	v_lshlrev_b64 v[4:5], 10, v[168:169]
	s_or_b32 s33, s5, s19
	v_bfe_u32 v144, v3, 5, 1
	v_lshl_add_u64 v[4:5], s[24:25], 0, v[4:5]
	s_lshl_b32 s10, s33, 1
	s_mov_b32 s11, s8
	v_lshl_add_u64 v[4:5], v[4:5], 0, s[10:11]
	v_lshlrev_b32_e32 v170, 4, v144
	v_mov_b32_e32 v171, v2
	s_mov_b32 s5, s8
	v_lshl_add_u64 v[4:5], v[4:5], 0, v[170:171]
	s_lshl_b64 s[4:5], s[4:5], 9
	global_load_dwordx4 v[84:87], v[4:5], off
	global_load_dwordx4 v[88:91], v[4:5], off offset:32
	global_load_dwordx4 v[92:95], v[4:5], off offset:64
	global_load_dwordx4 v[96:99], v[4:5], off offset:96
	v_or_b32_e32 v6, s19, v183
	v_mov_b32_e32 v5, s5
	v_or_b32_e32 v4, s4, v150
	v_lshlrev_b64 v[4:5], 11, v[4:5]
	v_lshlrev_b32_e32 v102, 2, v6
	v_mov_b32_e32 v21, s5
	v_or_b32_e32 v20, s4, v152
	v_or_b32_e32 v4, v4, v102
	v_lshlrev_b64 v[20:21], 11, v[20:21]
	v_lshl_add_u64 v[8:9], s[20:21], 0, v[4:5]
	v_lshl_add_u64 v[16:17], s[22:23], 0, v[4:5]
	v_or_b32_e32 v20, v20, v102
	global_load_dwordx4 v[4:7], v[8:9], off offset:16
	s_nop 0
	global_load_dwordx4 v[8:11], v[8:9], off
	s_nop 0
	global_load_dwordx4 v[12:15], v[16:17], off offset:16
	s_nop 0
	global_load_dwordx4 v[16:19], v[16:17], off
	v_lshl_add_u64 v[24:25], s[20:21], 0, v[20:21]
	v_lshl_add_u64 v[32:33], s[22:23], 0, v[20:21]
	global_load_dwordx4 v[20:23], v[24:25], off offset:16
	s_nop 0
	global_load_dwordx4 v[24:27], v[24:25], off
	s_nop 0
	global_load_dwordx4 v[28:31], v[32:33], off offset:16
	s_nop 0
	global_load_dwordx4 v[32:35], v[32:33], off
	s_or_b32 s10, s4, 64
	s_bitset1_b32 s4, 7
	v_mov_b32_e32 v37, s5
	v_or_b32_e32 v36, s10, v150
	v_mov_b32_e32 v53, s5
	v_or_b32_e32 v52, s10, v152
	v_mov_b32_e32 v69, s5
	v_or_b32_e32 v68, s4, v150
	v_mov_b32_e32 v101, s5
	v_or_b32_e32 v100, s4, v152
	v_lshlrev_b64 v[36:37], 11, v[36:37]
	v_lshlrev_b64 v[52:53], 11, v[52:53]
	v_lshlrev_b64 v[68:69], 11, v[68:69]
	v_lshlrev_b64 v[100:101], 11, v[100:101]
	v_or_b32_e32 v36, v36, v102
	v_or_b32_e32 v52, v52, v102
	v_or_b32_e32 v68, v68, v102
	v_or_b32_e32 v100, v100, v102
	v_lshl_add_u64 v[40:41], s[20:21], 0, v[36:37]
	v_lshl_add_u64 v[48:49], s[22:23], 0, v[36:37]
	v_lshl_add_u64 v[56:57], s[20:21], 0, v[52:53]
	v_lshl_add_u64 v[64:65], s[22:23], 0, v[52:53]
	v_lshl_add_u64 v[72:73], s[20:21], 0, v[68:69]
	v_lshl_add_u64 v[80:81], s[22:23], 0, v[68:69]
	v_lshl_add_u64 v[102:103], s[20:21], 0, v[100:101]
	v_lshl_add_u64 v[100:101], s[22:23], 0, v[100:101]
	s_waitcnt lgkmcnt(0)
	s_barrier
; #define LAS __attribute__((address_space(3)))
; template <bool SAMPLE>
; DI void attn_unit(const Params& p, LAS unsigned char* lds, int b, int cp, int hp) {
;     ...
;     u32x4 ka[2], va_[2], kb_[2], vb_[2];
;     attn_load_tile<SAMPLE>(p, b, cp, hp, j_first, ka, va_);
;     __syncthreads();
;     attn_store_tile(lds + (j_first & 1) * AT_BUF, ka, va_);
;     attn_load_tile<SAMPLE>(p, b, cp, hp, j_first + 1, ka, va_);
;     if (j_first + 2 <= j_last) attn_load_tile<SAMPLE>(p, b, cp, hp, j_first + 2, kb_, vb_);
;     f32x16 o0, o1;
; #pragma unroll
;     for (int r = 0; r < 16; ++r) { o0[r] = 0.f; o1[r] = 0.f; }
;     float lsum = 0.f;
;     const int i16 = lane & 15, qd = i16 >> 2, pp = i16 & 3, g16 = (lane >> 4) & 1;
;     const int koff = r32 * KSTR + hl * 128 + h * 16;
;     const int voff = AT_V + (4 * h + qd) * VSTR + hl * 128 + (16 * g16 + 4 * pp) * 2;
;     const LAS float* bth = bt + hl * 516;
	global_load_dwordx4 v[36:39], v[40:41], off offset:16
	s_nop 0
	global_load_dwordx4 v[40:43], v[40:41], off
	s_nop 0
	global_load_dwordx4 v[44:47], v[48:49], off offset:16
	s_nop 0
	global_load_dwordx4 v[48:51], v[48:49], off
	s_nop 0
	global_load_dwordx4 v[52:55], v[56:57], off offset:16
	s_nop 0
	global_load_dwordx4 v[56:59], v[56:57], off
	s_nop 0
	global_load_dwordx4 v[60:63], v[64:65], off offset:16
	s_nop 0
	global_load_dwordx4 v[64:67], v[64:65], off
	s_nop 0
	global_load_dwordx4 v[68:71], v[72:73], off offset:16
	s_nop 0
	global_load_dwordx4 v[72:75], v[72:73], off
	s_nop 0
	global_load_dwordx4 v[76:79], v[80:81], off offset:16
	s_nop 0
	global_load_dwordx4 v[80:83], v[80:81], off
	s_nop 0
	global_load_dwordx4 v[124:127], v[102:103], off
	global_load_dwordx4 v[130:133], v[102:103], off offset:16
	global_load_dwordx4 v[134:137], v[100:101], off
	global_load_dwordx4 v[138:141], v[100:101], off offset:16
	s_and_b32 s4, s84, 3
	v_lshl_or_b32 v172, s4, 9, v190
	s_lshl_b64 s[4:5], s[56:57], 18
	s_and_b32 s5, s5, 0x3ffff
	s_and_b32 s4, s4, 0xfff00000
	v_and_b32_e32 v171, 31, v3
	v_lshl_add_u64 v[174:175], v[160:161], 0, s[4:5]
	v_lshl_add_u64 v[176:177], v[162:163], 0, s[4:5]
	s_lshl_b32 s4, s9, 7
	v_add_u32_e32 v142, s18, v150
	v_mov_b32_e32 v143, v2
	s_mulk_i32 s9, 0x810
	s_mov_b32 s5, s8
	v_mov_b32_e32 v159, v2
	s_add_i32 s76, s9, 0
	v_mov_b32_e32 v173, v2
	s_add_i32 s76, s76, 0x12800
	s_mov_b32 s77, 0
	v_mov_b32_e32 v196, 0
	s_mov_b32 s86, 0
	s_waitcnt vmcnt(22)
	v_cvt_pk_bf16_f32 v8, v8, v9
	v_cvt_pk_bf16_f32 v9, v10, v11
	v_cvt_pk_bf16_f32 v10, v4, v5
	v_cvt_pk_bf16_f32 v11, v6, v7
	s_waitcnt vmcnt(20)
	v_cvt_pk_bf16_f32 v4, v16, v17
	v_cvt_pk_bf16_f32 v5, v18, v19
	v_cvt_pk_bf16_f32 v6, v12, v13
	v_cvt_pk_bf16_f32 v7, v14, v15
	s_waitcnt vmcnt(18)
	v_cvt_pk_bf16_f32 v12, v24, v25
	v_cvt_pk_bf16_f32 v13, v26, v27
	v_cvt_pk_bf16_f32 v14, v20, v21
	v_cvt_pk_bf16_f32 v15, v22, v23
	s_waitcnt vmcnt(16)
	v_cvt_pk_bf16_f32 v16, v32, v33
	v_cvt_pk_bf16_f32 v17, v34, v35
	v_cvt_pk_bf16_f32 v18, v28, v29
	v_cvt_pk_bf16_f32 v19, v30, v31
	ds_write_b128 v188, v[8:11]
	ds_write_b128 v189, v[4:7] offset:17408
	ds_write_b128 v188, v[12:15] offset:8704
	ds_write_b128 v189, v[16:19] offset:27648
	v_lshrrev_b32_e32 v4, 2, v3
	v_and_b32_e32 v5, 16, v3
	v_lshlrev_b32_e32 v8, 2, v144
	v_lshlrev_b32_e32 v3, 2, v3
	v_and_or_b32 v4, v4, 3, v8
	v_and_or_b32 v3, v3, 12, v5
	v_mul_u32_u24_e32 v4, 0x140, v4
	v_lshl_or_b32 v3, v3, 1, s4
	v_mul_u32_u24_e32 v6, 0x110, v171
	v_add3_u32 v192, v3, v4, 0
	v_lshlrev_b64 v[4:5], 10, v[142:143]
	v_add3_u32 v18, v170, v6, s4
	v_lshl_add_u64 v[6:7], s[54:55], 0, v[4:5]
	s_lshl_b32 s4, s12, 8
	v_lshl_add_u64 v[4:5], s[6:7], 0, v[4:5]
	v_lshl_add_u32 v3, v171, 2, s9
	v_lshl_add_u64 v[6:7], v[6:7], 0, s[4:5]
	v_lshl_add_u64 v[4:5], v[4:5], 0, s[4:5]
	v_sub_u32_e32 v3, v3, v170
	v_lshl_add_u64 v[178:179], v[6:7], 0, v[158:159]
	v_lshl_add_u64 v[180:181], v[4:5], 0, v[158:159]
	v_add_u32_e32 v159, 0, v3
	v_sub_u32_e32 v3, v171, v8
	v_mov_b64_e32 v[16:17], 0
	v_add_u32_e32 v194, 0x2c5, v3
	v_mov_b32_e32 v3, v2
	v_mov_b64_e32 v[4:5], 0
	v_mov_b64_e32 v[6:7], 0
	v_mov_b64_e32 v[8:9], 0
	v_mov_b64_e32 v[10:11], 0
	v_mov_b64_e32 v[12:13], 0
	v_mov_b64_e32 v[14:15], 0
	v_mov_b64_e32 v[34:35], v[16:17]
	v_add_u32_e32 v195, 0, v18
	v_mov_b64_e32 v[32:33], v[14:15]
	v_mov_b64_e32 v[30:31], v[12:13]
	v_mov_b64_e32 v[28:29], v[10:11]
	v_mov_b64_e32 v[26:27], v[8:9]
	v_mov_b64_e32 v[24:25], v[6:7]
	v_mov_b64_e32 v[22:23], v[4:5]
	v_mov_b64_e32 v[20:21], v[2:3]
	v_mov_b64_e32 v[18:19], v[16:17]
	s_waitcnt vmcnt(14)
	v_cvt_pk_bf16_f32 v100, v40, v41
	v_cvt_pk_bf16_f32 v101, v42, v43
	v_cvt_pk_bf16_f32 v102, v36, v37
	v_cvt_pk_bf16_f32 v103, v38, v39
	s_waitcnt vmcnt(12)
	v_cvt_pk_bf16_f32 v104, v48, v49
	v_cvt_pk_bf16_f32 v105, v50, v51
	v_cvt_pk_bf16_f32 v106, v44, v45
	v_cvt_pk_bf16_f32 v107, v46, v47
	s_waitcnt vmcnt(10)
	v_cvt_pk_bf16_f32 v112, v56, v57
	v_cvt_pk_bf16_f32 v113, v58, v59
	v_cvt_pk_bf16_f32 v114, v52, v53
	v_cvt_pk_bf16_f32 v115, v54, v55
	s_waitcnt vmcnt(8)
	v_cvt_pk_bf16_f32 v120, v64, v65
	v_cvt_pk_bf16_f32 v121, v66, v67
	v_cvt_pk_bf16_f32 v122, v60, v61
	v_cvt_pk_bf16_f32 v123, v62, v63
	s_waitcnt vmcnt(6)
	v_cvt_pk_bf16_f32 v108, v72, v73
	v_cvt_pk_bf16_f32 v109, v74, v75
	v_cvt_pk_bf16_f32 v110, v68, v69
	v_cvt_pk_bf16_f32 v111, v70, v71
	s_waitcnt vmcnt(4)
	v_cvt_pk_bf16_f32 v116, v80, v81
	v_cvt_pk_bf16_f32 v117, v82, v83
	v_cvt_pk_bf16_f32 v118, v76, v77
	v_cvt_pk_bf16_f32 v119, v78, v79
	s_waitcnt vmcnt(3)
	v_cvt_pk_bf16_f32 v128, v124, v125
	v_cvt_pk_bf16_f32 v129, v126, v127
	s_waitcnt vmcnt(2)
	v_cvt_pk_bf16_f32 v130, v130, v131
	v_cvt_pk_bf16_f32 v131, v132, v133
	s_waitcnt vmcnt(1)
	v_cvt_pk_bf16_f32 v124, v134, v135
	v_cvt_pk_bf16_f32 v125, v136, v137
	s_waitcnt vmcnt(0)
	v_cvt_pk_bf16_f32 v126, v138, v139
	v_cvt_pk_bf16_f32 v127, v140, v141
	v_add_u32_e32 v193, 0xd800, v192
	v_mov_b64_e32 v[16:17], v[14:15]
	v_mov_b64_e32 v[14:15], v[12:13]
	v_mov_b64_e32 v[12:13], v[10:11]
	v_mov_b64_e32 v[10:11], v[8:9]
	v_mov_b64_e32 v[8:9], v[6:7]
	v_mov_b64_e32 v[6:7], v[4:5]
	v_mov_b64_e32 v[4:5], v[2:3]

; template <bool SAMPLE>
; DI void attn_load_tile(const Params& p, int b, int cp, int hp, int j, u32x4 (&kr)[2], u32x4 (&vr)[2]) {
;     ...
;             } else if (key < 16) {
;                 const size_t row = (size_t)MP + b * 16 + key;
;                 kr[i] = *(const u32x4*)(Kb + row * MW + hp * 128 + chunk * 8);
;                 vr[i] = *(const u32x4*)(Vb + row * MW + hp * 128 + chunk * 8);
;             } else { kr[i] = (u32x4){0u, 0u, 0u, 0u}; vr[i] = (u32x4){0u, 0u, 0u, 0u}; }
.LBB0_1016:
	s_andn2_b64 vcc, exec, s[70:71]
	s_cbranch_vccnz .LBB0_1020
	v_mov_b64_e32 v[4:5], 0
	v_mov_b32_e32 v3, v2
	v_mov_b64_e32 v[118:119], v[4:5]
	v_mov_b64_e32 v[110:111], v[4:5]
	v_mov_b64_e32 v[116:117], v[2:3]
	v_mov_b64_e32 v[108:109], v[2:3]
	s_and_saveexec_b64 s[70:71], s[0:1]
	s_cbranch_execz .LBB0_1019
	global_load_dwordx4 v[108:111], v[178:179], off
	global_load_dwordx4 v[116:119], v[180:181], off

; #define LAS __attribute__((address_space(3)))
; template <bool SAMPLE>
; DI void attn_unit(const Params& p, LAS unsigned char* lds, int b, int cp, int hp) {
;     ...
;     const int j_first = SAMPLE ? 0 : (cp >= 4 ? 0 : 8 - 2 * cp), j_last = SAMPLE ? 8 : 9;
;     u32x4 ka[2], va_[2], kb_[2], vb_[2];
;     attn_load_tile<SAMPLE>(p, b, cp, hp, j_first, ka, va_);
;     __syncthreads();
;     attn_store_tile(lds + (j_first & 1) * AT_BUF, ka, va_);
;     attn_load_tile<SAMPLE>(p, b, cp, hp, j_first + 1, ka, va_);
;     if (j_first + 2 <= j_last) attn_load_tile<SAMPLE>(p, b, cp, hp, j_first + 2, kb_, vb_);
;     f32x16 o0, o1;
; #pragma unroll
;     for (int r = 0; r < 16; ++r) { o0[r] = 0.f; o1[r] = 0.f; }
;     float lsum = 0.f;
;     const int i16 = lane & 15, qd = i16 >> 2, pp = i16 & 3, g16 = (lane >> 4) & 1;
;     const int koff = r32 * KSTR + hl * 128 + h * 16;
;     const int voff = AT_V + (4 * h + qd) * VSTR + hl * 128 + (16 * g16 + 4 * pp) * 2;
;     const LAS float* bth = bt + hl * 516;
.LBB0_1050:
	s_cmp_gt_i32 s5, 9
	s_cbranch_scc1 .LBB0_1078
	s_lshl_b32 s10, s57, 10
	s_and_b32 s36, s10, 0x1c00000
	s_and_b32 s10, s84, 3
	v_lshlrev_b32_e32 v4, 2, v3
	v_and_b32_e32 v5, 16, v3
	s_lshl_b32 s37, s10, 8
	s_lshl_b32 s10, s13, 7
	v_and_or_b32 v4, v4, 12, v5
	v_mul_u32_u24_e32 v5, 0x110, v159
	s_mul_i32 s9, s13, 0x810
	v_lshl_or_b32 v4, v4, 1, s10
	v_add3_u32 v18, v170, v5, s10
	s_add_i32 s10, s76, -4
	s_add_i32 s12, s9, 0
	s_ashr_i32 s11, s10, 31
	s_add_i32 s12, s12, 0x12800
	s_and_b32 s38, s57, 0x7000
	s_lshl_b64 s[18:19], s[10:11], 16
	s_add_u32 s13, s36, s18
	v_lshlrev_b32_e32 v6, 2, v8
	v_lshrrev_b32_e32 v3, 2, v3
	s_addc_u32 s19, 0, s19
	s_or_b32 s18, s13, s37
	s_lshl_b64 s[10:11], s[10:11], 6
	v_and_or_b32 v3, v3, 3, v6
	s_add_u32 s10, s10, s38
	v_mul_u32_u24_e32 v3, 0x140, v3
	s_addc_u32 s11, s11, 0
	v_add3_u32 v171, v4, v3, 0
	v_mov_b32_e32 v5, s11
	v_or_b32_e32 v4, s10, v150
	s_add_u32 s10, s28, s37
	v_lshlrev_b64 v[4:5], 10, v[4:5]
	s_addc_u32 s11, s29, 0
	v_lshl_add_u64 v[174:175], s[10:11], 0, v[4:5]
	s_add_i32 s10, s76, -6
	s_ashr_i32 s11, s10, 31
	s_lshl_b64 s[10:11], s[10:11], 16
	s_add_u32 s10, s36, s10
	s_addc_u32 s11, 0, s11
	s_or_b32 s10, s10, s37
	v_lshl_add_u64 v[176:177], v[166:167], 0, s[10:11]
	s_lshl_b32 s11, s71, 1
	s_lshl_b32 s10, s70, 8
	s_and_b32 s11, s11, 0x80
	s_or_b32 s10, s10, s11
	v_lshl_or_b32 v3, v159, 2, s10
	v_sub_u32_e32 v3, v3, v170
	s_lshl_b32 s10, s5, 8
	v_subrev_u32_e32 v3, s10, v3
	s_lshl_b32 s10, s5, 6
	v_add_u32_e32 v179, 0, v3
	v_or_b32_e32 v3, s10, v6
	s_lshl_b32 s11, s70, 6
	v_subrev_u32_e32 v3, s11, v3
	s_or_b32 s11, s11, s33
	v_sub_u32_e32 v4, s11, v6
	v_subrev_u32_e32 v181, s10, v4
	v_add_u32_e32 v4, s33, v159
	v_sub_u32_e32 v180, s33, v3
	v_sub_u32_e32 v3, v4, v3
	v_mov_b64_e32 v[16:17], 0
	v_lshl_add_u32 v192, v3, 2, 0
	v_mov_b32_e32 v3, v2
	v_mov_b64_e32 v[4:5], 0
	v_mov_b64_e32 v[6:7], 0
	v_mov_b64_e32 v[8:9], 0
	v_mov_b64_e32 v[10:11], 0
	v_mov_b64_e32 v[12:13], 0
	v_mov_b64_e32 v[14:15], 0
	v_mov_b64_e32 v[34:35], v[16:17]
	v_add_u32_e32 v193, 0, v18
	v_mov_b64_e32 v[32:33], v[14:15]
	v_mov_b64_e32 v[30:31], v[12:13]
	v_mov_b64_e32 v[28:29], v[10:11]
	v_mov_b64_e32 v[26:27], v[8:9]
	v_mov_b64_e32 v[24:25], v[6:7]
	v_mov_b64_e32 v[22:23], v[4:5]
	v_mov_b64_e32 v[20:21], v[2:3]
	v_mov_b64_e32 v[18:19], v[16:17]
	v_add_u32_e32 v178, 0xd800, v171
	v_lshl_add_u64 v[172:173], v[166:167], 0, s[18:19]
	s_sub_i32 s13, 0, s70
	v_mov_b32_e32 v194, 0
	v_mov_b64_e32 v[16:17], v[14:15]
	v_mov_b64_e32 v[14:15], v[12:13]
	v_mov_b64_e32 v[12:13], v[10:11]
	v_mov_b64_e32 v[10:11], v[8:9]
	v_mov_b64_e32 v[8:9], v[6:7]
	v_mov_b64_e32 v[6:7], v[4:5]
	v_mov_b64_e32 v[4:5], v[2:3]
	s_branch .LBB0_1054

; template <bool SAMPLE>
; DI void attn_unit(const Params& p, LAS unsigned char* lds, int b, int cp, int hp) {
;     ...
;     f32x16 o0, o1;
; #pragma unroll
;     for (int r = 0; r < 16; ++r) { o0[r] = 0.f; o1[r] = 0.f; }
;     float lsum = 0.f;
.LBB0_1078:
	v_mov_b64_e32 v[16:17], 0
	v_mov_b32_e32 v3, v2
	v_mov_b64_e32 v[4:5], 0
	v_mov_b64_e32 v[6:7], 0
	v_mov_b64_e32 v[8:9], 0
	v_mov_b64_e32 v[10:11], 0
	v_mov_b64_e32 v[12:13], 0
	v_mov_b64_e32 v[14:15], 0
	v_mov_b64_e32 v[34:35], v[16:17]
	v_mov_b64_e32 v[32:33], v[14:15]
	v_mov_b64_e32 v[30:31], v[12:13]
	v_mov_b64_e32 v[28:29], v[10:11]
	v_mov_b64_e32 v[26:27], v[8:9]
	v_mov_b64_e32 v[24:25], v[6:7]
	v_mov_b64_e32 v[22:23], v[4:5]
	v_mov_b64_e32 v[20:21], v[2:3]
	v_mov_b64_e32 v[18:19], v[16:17]
	v_mov_b32_e32 v194, 0
	v_mov_b64_e32 v[16:17], v[14:15]
	v_mov_b64_e32 v[14:15], v[12:13]
	v_mov_b64_e32 v[12:13], v[10:11]
	v_mov_b64_e32 v[10:11], v[8:9]
	v_mov_b64_e32 v[8:9], v[6:7]
	v_mov_b64_e32 v[6:7], v[4:5]
	v_mov_b64_e32 v[4:5], v[2:3]

; #define LAS __attribute__((address_space(3)))
; template <bool SAMPLE>
; DI void attn_unit(const Params& p, LAS unsigned char* lds, int b, int cp, int hp) {
;     ...
;     const int tid = tid_, lane = tid & 63, w = __builtin_amdgcn_readfirstlane(tid >> 6), r32 = lane & 31, h = lane >> 5;
;     const int cl = SAMPLE ? 0 : (w >> 2), hl = (w >> 1) & 1, head = hp * 2 + hl, qoff = SAMPLE ? 0 : 32 * (w & 1);
;     const bf16_t* Qb = (const bf16_t*)(p.ws + WS_A);
;     bf16_t* CAT = (bf16_t*)(p.ws + WS_CAT);
;     const size_t qrow = SAMPLE ? (size_t)MP + b * 16 + (r32 & 15) : (size_t)b * SEQ + (2 * cp + cl) * 64 + qoff + r32;
;     bf16x8 qf[4];
; #pragma unroll
;     for (int d0 = 0; d0 < 4; ++d0) qf[d0] = *(const bf16x8*)(Qb + qrow * MW + head * 64 + d0 * 16 + h * 8);
;     LAS float* bt = (LAS float*)(lds + AT_B);
;     const int j_first = SAMPLE ? 0 : (cp >= 4 ? 0 : 8 - 2 * cp), j_last = SAMPLE ? 8 : 9;
;     u32x4 ka[2], va_[2], kb_[2], vb_[2];
;     attn_load_tile<SAMPLE>(p, b, cp, hp, j_first, ka, va_);
;     __syncthreads();
;     attn_store_tile(lds + (j_first & 1) * AT_BUF, ka, va_);
;     attn_load_tile<SAMPLE>(p, b, cp, hp, j_first + 1, ka, va_);
;     if (j_first + 2 <= j_last) attn_load_tile<SAMPLE>(p, b, cp, hp, j_first + 2, kb_, vb_);
; DI void phase_mix_odd(const Params& p, LAS unsigned char* lds) {
;     ...
;             LAS float* bt = (LAS float*)(lds + AT_B); const float* relb = p.in[18]; const int hp = blk & 3;
;             __syncthreads();
;             for (int i = threadIdx.x; i < 2 * 513; i += 512) { const int hh = i >= 513 ? 1 : 0, j = i - hh * 513; bt[hh * 516 + j] = relb[(hp * 2 + hh) * 513 + j] * LOG2E; }
;         }
;         if (blk < 32) attn_unit<true>(p, lds, blk >> 2, 0, blk & 3);
.LBB0_1138:
	v_cmp_lt_u32_e32 vcc, s11, v4
	v_cmp_lt_u32_e64 s[4:5], s12, v4
	s_or_b64 s[8:9], s[4:5], s[8:9]
	v_cndmask_b32_e64 v5, 0, 1, vcc
	v_cndmask_b32_e32 v6, 0, v2, vcc
	v_or_b32_e32 v5, s10, v5
	v_add_u32_e32 v8, v6, v4
	v_mad_u32_u24 v6, v5, s12, v8
	v_ashrrev_i32_e32 v7, 31, v6
	v_lshl_add_u64 v[6:7], v[6:7], 2, s[40:41]
	global_load_dword v5, v[6:7], off
	v_add_u32_e32 v6, 0x200, v4
	v_cndmask_b32_e32 v7, 0, v3, vcc
	v_mov_b32_e32 v4, v6
	v_lshlrev_b32_e32 v6, 2, v8
	v_add3_u32 v6, s13, v7, v6
	s_waitcnt vmcnt(0)
	v_mul_f32_e32 v5, 0x3fb8aa3b, v5
	ds_write_b32 v6, v5
	s_andn2_b64 exec, exec, s[8:9]
	s_cbranch_execnz .LBB0_1138
	s_or_b64 exec, exec, s[8:9]
	s_lshl_b32 s84, s85, 7
	s_cmp_lt_i32 s2, 32
	s_mov_b32 s4, 0
	v_add_u32_e32 v172, v149, v184
	v_add_u32_e32 v173, v149, v185
	s_cbranch_scc0 .LBB0_1181
	s_ashr_i32 s8, s2, 2
	s_lshl_b32 s5, s8, 4
	s_ashr_i32 s9, s5, 31
	s_add_u32 s10, s5, 0x8000
	s_addc_u32 s11, s9, 0
	s_ashr_i32 s9, s8, 31
	s_lshl_b64 s[40:41], s[8:9], 9
	v_or_b32_e32 v4, s84, v183
	v_mov_b32_e32 v3, s41
	v_or_b32_e32 v2, s40, v150
	v_lshlrev_b64 v[2:3], 11, v[2:3]
	v_lshlrev_b32_e32 v102, 2, v4
	v_or_b32_e32 v2, v2, v102
	v_lshl_add_u64 v[8:9], s[20:21], 0, v[2:3]
	v_lshl_add_u64 v[16:17], s[22:23], 0, v[2:3]
	v_mov_b32_e32 v3, s41
	v_or_b32_e32 v2, s40, v152
	v_lshlrev_b64 v[2:3], 11, v[2:3]
	v_or_b32_e32 v2, v2, v102
	s_or_b32 s5, s40, 64
	v_lshl_add_u64 v[24:25], s[20:21], 0, v[2:3]
	v_lshl_add_u64 v[32:33], s[22:23], 0, v[2:3]
	v_mov_b32_e32 v3, s41
	v_or_b32_e32 v2, s5, v150
	v_lshlrev_b64 v[2:3], 11, v[2:3]
	v_or_b32_e32 v2, v2, v102
	v_lshl_add_u64 v[40:41], s[20:21], 0, v[2:3]
	v_lshl_add_u64 v[48:49], s[22:23], 0, v[2:3]
	v_mov_b32_e32 v3, s41
	v_or_b32_e32 v2, s5, v152
	v_lshlrev_b64 v[44:45], 11, v[2:3]
	v_mov_b32_e32 v3, v148
	v_mov_b32_e32 v161, s11
	v_readfirstlane_b32 s12, v3
	s_bfe_u32 s5, s12, 0x10007
	v_and_or_b32 v160, v3, 15, s10
	s_lshl_b32 s13, s5, 6
	v_lshlrev_b64 v[4:5], 10, v[160:161]
	s_or_b32 s13, s13, s84
	v_lshl_add_u64 v[12:13], s[24:25], 0, v[4:5]
	s_lshl_b32 s56, s13, 1
	global_load_dwordx4 v[4:7], v[8:9], off offset:16
	s_nop 0
	global_load_dwordx4 v[8:11], v[8:9], off
	s_mov_b32 s57, s4
	v_lshl_add_u64 v[28:29], v[12:13], 0, s[56:57]
	global_load_dwordx4 v[12:15], v[16:17], off offset:16
	s_nop 0
	global_load_dwordx4 v[16:19], v[16:17], off
	s_nop 0
	global_load_dwordx4 v[20:23], v[24:25], off offset:16
	s_nop 0
	global_load_dwordx4 v[24:27], v[24:25], off
	v_mov_b32_e32 v2, 0
	v_bfe_u32 v142, v3, 5, 1
	v_lshlrev_b32_e32 v162, 4, v142
	v_mov_b32_e32 v163, v2
	v_lshl_add_u64 v[36:37], v[28:29], 0, v[162:163]
	global_load_dwordx4 v[28:31], v[32:33], off offset:16
	s_nop 0
	global_load_dwordx4 v[32:35], v[32:33], off
	s_nop 0
	global_load_dwordx4 v[84:87], v[36:37], off
	global_load_dwordx4 v[88:91], v[36:37], off offset:32
	global_load_dwordx4 v[92:95], v[36:37], off offset:64
	global_load_dwordx4 v[96:99], v[36:37], off offset:96
	s_or_b32 s18, s40, 0x80
	v_mov_b32_e32 v61, s41
	v_or_b32_e32 v60, s18, v150
	v_mov_b32_e32 v101, s41
	v_or_b32_e32 v100, s18, v152
	v_lshlrev_b64 v[68:69], 11, v[60:61]
	v_lshlrev_b64 v[100:101], 11, v[100:101]
	v_or_b32_e32 v44, v44, v102
	v_or_b32_e32 v68, v68, v102
	v_or_b32_e32 v100, v100, v102
	v_lshl_add_u64 v[56:57], s[20:21], 0, v[44:45]
	v_lshl_add_u64 v[64:65], s[22:23], 0, v[44:45]
	v_lshl_add_u64 v[72:73], s[20:21], 0, v[68:69]
	v_lshl_add_u64 v[80:81], s[22:23], 0, v[68:69]
	v_lshl_add_u64 v[102:103], s[20:21], 0, v[100:101]
	v_lshl_add_u64 v[100:101], s[22:23], 0, v[100:101]
	s_waitcnt lgkmcnt(0)
	s_barrier
; #define LAS __attribute__((address_space(3)))
; template <bool SAMPLE>
; DI void attn_unit(const Params& p, LAS unsigned char* lds, int b, int cp, int hp) {
;     ...
;     u32x4 ka[2], va_[2], kb_[2], vb_[2];
;     attn_load_tile<SAMPLE>(p, b, cp, hp, j_first, ka, va_);
;     __syncthreads();
;     attn_store_tile(lds + (j_first & 1) * AT_BUF, ka, va_);
;     attn_load_tile<SAMPLE>(p, b, cp, hp, j_first + 1, ka, va_);
;     if (j_first + 2 <= j_last) attn_load_tile<SAMPLE>(p, b, cp, hp, j_first + 2, kb_, vb_);
;     f32x16 o0, o1;
; #pragma unroll
;     for (int r = 0; r < 16; ++r) { o0[r] = 0.f; o1[r] = 0.f; }
;     float lsum = 0.f;
;     const int i16 = lane & 15, qd = i16 >> 2, pp = i16 & 3, g16 = (lane >> 4) & 1;
;     const int koff = r32 * KSTR + hl * 128 + h * 16;
;     const int voff = AT_V + (4 * h + qd) * VSTR + hl * 128 + (16 * g16 + 4 * pp) * 2;
;     const LAS float* bth = bt + hl * 516;
	global_load_dwordx4 v[36:39], v[40:41], off offset:16
	s_nop 0
	global_load_dwordx4 v[40:43], v[40:41], off
	s_nop 0
	global_load_dwordx4 v[44:47], v[48:49], off offset:16
	s_nop 0
	global_load_dwordx4 v[48:51], v[48:49], off
	s_nop 0
	global_load_dwordx4 v[52:55], v[56:57], off offset:16
	s_nop 0
	global_load_dwordx4 v[56:59], v[56:57], off
	s_nop 0
	global_load_dwordx4 v[60:63], v[64:65], off offset:16
	s_nop 0
	global_load_dwordx4 v[64:67], v[64:65], off
	s_nop 0
	global_load_dwordx4 v[68:71], v[72:73], off offset:16
	s_nop 0
	global_load_dwordx4 v[72:75], v[72:73], off
	s_nop 0
	global_load_dwordx4 v[76:79], v[80:81], off offset:16
	s_nop 0
	global_load_dwordx4 v[80:83], v[80:81], off
	s_nop 0
	global_load_dwordx4 v[124:127], v[102:103], off
	global_load_dwordx4 v[130:133], v[102:103], off offset:16
	global_load_dwordx4 v[134:137], v[100:101], off
	global_load_dwordx4 v[138:141], v[100:101], off offset:16
	v_lshl_add_u64 v[100:101], s[10:11], 0, v[150:151]
	v_lshlrev_b64 v[100:101], 10, v[100:101]
	v_and_b32_e32 v151, 31, v3
	v_lshl_add_u64 v[102:103], s[54:55], 0, v[100:101]
	v_lshl_add_u64 v[100:101], s[6:7], 0, v[100:101]
	s_lshl_b32 s6, s5, 7
	s_mulk_i32 s5, 0x810
	s_lshl_b32 s10, s84, 1
	s_mov_b32 s11, s4
	v_lshl_add_u64 v[102:103], v[102:103], 0, s[10:11]
	v_mov_b32_e32 v159, v2
	v_lshl_add_u64 v[100:101], v[100:101], 0, s[10:11]
	s_add_i32 s33, s5, 0
	v_lshl_add_u64 v[164:165], v[102:103], 0, v[158:159]
	v_lshl_add_u64 v[158:159], v[100:101], 0, v[158:159]
	s_add_i32 s33, s33, 0x12800
	v_add_lshl_u32 v166, s84, v183, 2
	v_mov_b32_e32 v167, v2
	s_mov_b32 s58, 0x60000
	s_mov_b64 s[10:11], 0x70000
	s_mov_b32 s59, 0x70000
	s_mov_b32 s60, 0x80000
	s_mov_b32 s61, 0x90000
	s_mov_b64 s[40:41], 0x40000
	s_mov_b32 s62, 0
	v_mov_b32_e32 v178, 0
	s_mov_b32 s63, 0
	s_waitcnt vmcnt(26)
	v_cvt_pk_bf16_f32 v8, v8, v9
	v_cvt_pk_bf16_f32 v9, v10, v11
	v_cvt_pk_bf16_f32 v10, v4, v5
	v_cvt_pk_bf16_f32 v11, v6, v7
	s_waitcnt vmcnt(25)
	v_cvt_pk_bf16_f32 v6, v12, v13
	s_waitcnt vmcnt(24)
	v_cvt_pk_bf16_f32 v4, v16, v17
	v_cvt_pk_bf16_f32 v5, v18, v19
	v_cvt_pk_bf16_f32 v7, v14, v15
	s_waitcnt vmcnt(22)
	v_cvt_pk_bf16_f32 v12, v24, v25
	v_cvt_pk_bf16_f32 v13, v26, v27
	v_cvt_pk_bf16_f32 v14, v20, v21
	v_cvt_pk_bf16_f32 v15, v22, v23
	s_waitcnt vmcnt(20)
	v_cvt_pk_bf16_f32 v16, v32, v33
	v_cvt_pk_bf16_f32 v17, v34, v35
	v_cvt_pk_bf16_f32 v18, v28, v29
	v_cvt_pk_bf16_f32 v19, v30, v31
	ds_write_b128 v172, v[8:11]
	ds_write_b128 v173, v[4:7] offset:17408
	ds_write_b128 v172, v[12:15] offset:8704
	ds_write_b128 v173, v[16:19] offset:27648
	v_mul_u32_u24_e32 v6, 0x110, v151
	v_lshrrev_b32_e32 v4, 2, v3
	v_and_b32_e32 v5, 16, v3
	v_add3_u32 v18, v162, v6, s6
	v_lshlrev_b32_e32 v6, 2, v142
	v_lshlrev_b32_e32 v3, 2, v3
	v_and_or_b32 v4, v4, 3, v6
	v_and_or_b32 v3, v3, 12, v5
	v_mul_u32_u24_e32 v4, 0x140, v4
	v_lshl_or_b32 v3, v3, 1, s6
	v_add3_u32 v163, v3, v4, 0
	v_lshl_add_u32 v3, v151, 2, s5
	s_lshl_b64 s[6:7], s[8:9], 20
	v_sub_u32_e32 v3, v3, v162
	v_lshl_or_b32 v4, v150, 11, s6
	v_mov_b32_e32 v5, s7
	v_add_u32_e32 v175, 0, v3
	v_sub_u32_e32 v3, v151, v6
	v_mov_b64_e32 v[16:17], 0
	v_lshl_add_u64 v[168:169], s[20:21], 0, v[4:5]
	v_lshl_add_u64 v[170:171], s[22:23], 0, v[4:5]
	v_add_u32_e32 v176, 0x2c5, v3
	v_mov_b32_e32 v3, v2
	v_mov_b64_e32 v[4:5], 0
	v_mov_b64_e32 v[6:7], 0
	v_mov_b64_e32 v[8:9], 0
	v_mov_b64_e32 v[10:11], 0
	v_mov_b64_e32 v[12:13], 0
	v_mov_b64_e32 v[14:15], 0
	v_mov_b64_e32 v[34:35], v[16:17]
	v_add_u32_e32 v177, 0, v18
	v_mov_b64_e32 v[32:33], v[14:15]
	v_mov_b64_e32 v[30:31], v[12:13]
	v_mov_b64_e32 v[28:29], v[10:11]
	v_mov_b64_e32 v[26:27], v[8:9]
	v_mov_b64_e32 v[24:25], v[6:7]
	v_mov_b64_e32 v[22:23], v[4:5]
	v_mov_b64_e32 v[20:21], v[2:3]
	v_mov_b64_e32 v[18:19], v[16:17]
	s_waitcnt vmcnt(14)
	v_cvt_pk_bf16_f32 v100, v40, v41
	v_cvt_pk_bf16_f32 v101, v42, v43
	v_cvt_pk_bf16_f32 v102, v36, v37
	v_cvt_pk_bf16_f32 v103, v38, v39
	s_waitcnt vmcnt(12)
	v_cvt_pk_bf16_f32 v104, v48, v49
	v_cvt_pk_bf16_f32 v105, v50, v51
	v_cvt_pk_bf16_f32 v106, v44, v45
	v_cvt_pk_bf16_f32 v107, v46, v47
	s_waitcnt vmcnt(10)
	v_cvt_pk_bf16_f32 v112, v56, v57
	v_cvt_pk_bf16_f32 v113, v58, v59
	v_cvt_pk_bf16_f32 v114, v52, v53
	v_cvt_pk_bf16_f32 v115, v54, v55
	s_waitcnt vmcnt(8)
	v_cvt_pk_bf16_f32 v120, v64, v65
	v_cvt_pk_bf16_f32 v121, v66, v67
	v_cvt_pk_bf16_f32 v122, v60, v61
	v_cvt_pk_bf16_f32 v123, v62, v63
	s_waitcnt vmcnt(6)
	v_cvt_pk_bf16_f32 v108, v72, v73
	v_cvt_pk_bf16_f32 v109, v74, v75
	v_cvt_pk_bf16_f32 v110, v68, v69
	v_cvt_pk_bf16_f32 v111, v70, v71
	s_waitcnt vmcnt(4)
	v_cvt_pk_bf16_f32 v116, v80, v81
	v_cvt_pk_bf16_f32 v117, v82, v83
	v_cvt_pk_bf16_f32 v118, v76, v77
	v_cvt_pk_bf16_f32 v119, v78, v79
	s_waitcnt vmcnt(3)
	v_cvt_pk_bf16_f32 v128, v124, v125
	v_cvt_pk_bf16_f32 v129, v126, v127
	s_waitcnt vmcnt(2)
	v_cvt_pk_bf16_f32 v130, v130, v131
	v_cvt_pk_bf16_f32 v131, v132, v133
	s_waitcnt vmcnt(1)
	v_cvt_pk_bf16_f32 v124, v134, v135
	v_cvt_pk_bf16_f32 v125, v136, v137
	s_waitcnt vmcnt(0)
	v_cvt_pk_bf16_f32 v126, v138, v139
	v_cvt_pk_bf16_f32 v127, v140, v141
	v_add_u32_e32 v174, 0xd800, v163
	s_mov_b64 s[8:9], 0x60000
	s_mov_b64 s[20:21], 0x80000
	s_mov_b64 s[22:23], 0x90000
	v_mov_b64_e32 v[16:17], v[14:15]
	v_mov_b64_e32 v[14:15], v[12:13]
	v_mov_b64_e32 v[12:13], v[10:11]
	v_mov_b64_e32 v[10:11], v[8:9]
	v_mov_b64_e32 v[8:9], v[6:7]
	v_mov_b64_e32 v[6:7], v[4:5]
	v_mov_b64_e32 v[4:5], v[2:3]

; template <bool SAMPLE>
; DI void attn_load_tile(const Params& p, int b, int cp, int hp, int j, u32x4 (&kr)[2], u32x4 (&vr)[2]) {
;     ...
;             } else if (key < 16) {
;                 const size_t row = (size_t)MP + b * 16 + key;
;                 kr[i] = *(const u32x4*)(Kb + row * MW + hp * 128 + chunk * 8);
;                 vr[i] = *(const u32x4*)(Vb + row * MW + hp * 128 + chunk * 8);
;             } else { kr[i] = (u32x4){0u, 0u, 0u, 0u}; vr[i] = (u32x4){0u, 0u, 0u, 0u}; }
.LBB0_1150:
	s_andn2_b64 vcc, exec, s[56:57]
	s_cbranch_vccnz .LBB0_1154
	v_mov_b64_e32 v[4:5], 0
	v_mov_b32_e32 v3, v2
	v_mov_b64_e32 v[118:119], v[4:5]
	v_mov_b64_e32 v[110:111], v[4:5]
	v_mov_b64_e32 v[116:117], v[2:3]
	v_mov_b64_e32 v[108:109], v[2:3]
	s_and_saveexec_b64 s[56:57], s[0:1]
	s_cbranch_execz .LBB0_1153
	global_load_dwordx4 v[108:111], v[164:165], off
	global_load_dwordx4 v[116:119], v[158:159], off

; #define PG8_STAGE(bufoff, gbase, voff) do { _Pragma("unroll") for (int _i = 0; _i < 2; ++_i) \
;         __builtin_amdgcn_global_load_lds((const unsigned*)((const char*)(gbase) + (voff)[_i]), (LAS unsigned*)(lds + (bufoff) + ldsw + _i * 8192), 16, 0, 0); } while (0)
; #define PG8_LDA(dst, b, h) do { _Pragma("unroll") for (int m = 0; m < 4; ++m) _Pragma("unroll") for (int k = 0; k < 2; ++k) dst[m][k] = *(const LAS bf16x8*)(lds + PG8_SA(b, h) + aoff + m * 2048 + k * 1024); } while (0)
; #define PG8_LDB(dst, b, h) do { _Pragma("unroll") for (int n = 0; n < 2; ++n) _Pragma("unroll") for (int k = 0; k < 2; ++k) dst[n][k] = *(const LAS bf16x8*)(lds + PG8_SB(b, h) + boff + n * 2048 + k * 1024); } while (0)
; #define PG8_MMA(ai, bj, At, Bt) do { __builtin_amdgcn_s_setprio(3); _Pragma("unroll") for (int m = 0; m < 4; ++m) _Pragma("unroll") for (int n = 0; n < 2; ++n) _Pragma("unroll") for (int k = 0; k < 2; ++k) \
;         acc[ai][bj][m][n] = __builtin_amdgcn_mfma_f32_16x16x32_bf16(Bt[n][k], At[m][k], acc[ai][bj][m][n], 0, 0, 0); __builtin_amdgcn_s_setprio(0); } while (0)
; #define PG8_WAIT_V(n) asm volatile("s_waitcnt vmcnt(" #n ")" ::: "memory")
; #define PG8_WAIT_L(n) asm volatile("s_waitcnt lgkmcnt(" #n ")" ::: "memory")
; #define PG8_BAR __builtin_amdgcn_s_barrier()
; template <class Epi, bool ALIGN_EPI>
; __device__ __forceinline__ void gemm_phase(LAS unsigned char* lds, const Gemm g, const StaticOrder& S, const Epi& E) {
;     ...
;         const char* nA = has_next ? (const char*)g.A + (size_t)nxt.pm * tstep : cA; const char* nB = has_next ? (const char*)g.Bt + (size_t)nxt.pn * tstep : cB;
;         for (int t = 0; t < nt; t += 2) {
;             const bool last = (t == nt - 2);
;             const char* a1 = cA + (size_t)(t + 1) * kstep;
;             const char* a2 = last ? nA : cA + (size_t)(t + 2) * kstep; const char* b2 = last ? nB : cB + (size_t)(t + 2) * kstep;
;             const char* a3 = a2 + kstep; const char* b3 = b2 + kstep;
;             PG8_LDB(B0, 0, 0); PG8_LDB(B1, 0, 1); PG8_SCHED; PG8_LDA(At, 0, 0); PG8_STAGE(PG8_SA(1, 1), a1 + hstep, voffA);
;             PG8_WAIT_V(8); PG8_WAIT_L(0); PG8_BAR; PG8_MMA(0, 0, At, B0); PG8_MMA(0, 1, At, B1); PG8_BAR; PG8_SCHED;
;             PG8_LDA(At, 0, 1); PG8_STAGE(PG8_SB(0, 0), b2, voffB); PG8_STAGE(PG8_SB(0, 1), b2 + hstep, voffB); PG8_STAGE(PG8_SA(0, 0), a2, voffA);
.LBB0_1338:
	s_ashr_i32 s19, s18, 31
	s_lshl_b64 s[20:21], s[18:19], 19
	s_add_u32 s20, s26, s20
	s_addc_u32 s21, s27, s21
	s_and_b64 s[22:23], s[4:5], exec
	s_cselect_b32 s19, s21, s41
	s_cselect_b32 s37, s20, s40
	s_ashr_i32 s17, s16, 31
	s_lshl_b64 s[22:23], s[16:17], 19
	s_add_u32 s22, s33, s22
	s_addc_u32 s23, s46, s23
	s_and_b64 s[44:45], s[4:5], exec
	s_cselect_b32 s17, s23, s43
	s_cselect_b32 s58, s22, s42
	s_add_u32 s40, s40, 0x40080
	s_addc_u32 s41, s41, 0
	s_add_u32 s59, s42, 0x100
	s_addc_u32 s60, s43, 0
	s_mov_b32 s61, -2
	s_waitcnt lgkmcnt(0)
	ds_read_b128 v[130:133], v196
	ds_read_b128 v[134:137], v196 offset:1024
	ds_read_b128 v[138:141], v196 offset:2048
	ds_read_b128 v[142:145], v196 offset:3072
	ds_read_b128 v[146:149], v197
	ds_read_b128 v[150:153], v197 offset:1024
	ds_read_b128 v[170:173], v197 offset:2048
	ds_read_b128 v[174:177], v197 offset:3072
	s_add_u32 s42, s40, 0xfffc0080
	s_addc_u32 s43, s41, -1
	s_cmp_eq_u32 s61, 12
	s_cselect_b32 s45, s19, s43
	s_cselect_b32 s44, s37, s42
	s_cselect_b32 s43, s17, s60
	s_cselect_b32 s42, s58, s59
	v_lshl_add_u64 v[186:187], s[40:41], 0, v[162:163]
	s_add_i32 m0, s39, 0xc000
	ds_read_b128 v[178:181], v198
	ds_read_b128 v[182:185], v198 offset:1024
	ds_read_b128 v[200:203], v198 offset:2048
	ds_read_b128 v[204:207], v198 offset:3072
	ds_read_b128 v[208:211], v198 offset:4096
	ds_read_b128 v[212:215], v198 offset:5120
	ds_read_b128 v[216:219], v198 offset:6144
	ds_read_b128 v[220:223], v198 offset:7168
	global_load_lds_dwordx4 v[186:187], off
	v_lshl_add_u64 v[186:187], s[40:41], 0, v[164:165]
	s_add_i32 m0, s39, 0xe000
	s_nop 0
	global_load_lds_dwordx4 v[186:187], off
	s_waitcnt vmcnt(8)
	s_waitcnt lgkmcnt(0)
	s_barrier
	s_setprio 3
	s_waitcnt lgkmcnt(0)
	v_mfma_f32_16x16x32_bf16 v[126:129], v[130:133], v[178:181], 0
	v_mfma_f32_16x16x32_bf16 v[122:125], v[138:141], v[178:181], 0
	v_mfma_f32_16x16x32_bf16 v[110:113], v[130:133], v[200:203], 0
	v_mfma_f32_16x16x32_bf16 v[106:109], v[138:141], v[200:203], 0
	v_mfma_f32_16x16x32_bf16 v[94:97], v[130:133], v[208:211], 0
	v_mfma_f32_16x16x32_bf16 v[90:93], v[138:141], v[208:211], 0
	v_mfma_f32_16x16x32_bf16 v[78:81], v[130:133], v[216:219], 0
	v_mfma_f32_16x16x32_bf16 v[74:77], v[138:141], v[216:219], 0
	v_mfma_f32_16x16x32_bf16 v[126:129], v[134:137], v[182:185], v[126:129]
	v_mfma_f32_16x16x32_bf16 v[122:125], v[142:145], v[182:185], v[122:125]
	v_mfma_f32_16x16x32_bf16 v[110:113], v[134:137], v[204:207], v[110:113]
	v_mfma_f32_16x16x32_bf16 v[106:109], v[142:145], v[204:207], v[106:109]
	v_mfma_f32_16x16x32_bf16 v[94:97], v[134:137], v[212:215], v[94:97]
	v_mfma_f32_16x16x32_bf16 v[90:93], v[142:145], v[212:215], v[90:93]
	v_mfma_f32_16x16x32_bf16 v[78:81], v[134:137], v[220:223], v[78:81]
	v_mfma_f32_16x16x32_bf16 v[74:77], v[142:145], v[220:223], v[74:77]
	s_setprio 0
	s_setprio 3
	v_mfma_f32_16x16x32_bf16 v[118:121], v[146:149], v[178:181], 0
	v_mfma_f32_16x16x32_bf16 v[114:117], v[170:173], v[178:181], 0
	v_mfma_f32_16x16x32_bf16 v[102:105], v[146:149], v[200:203], 0
	v_mfma_f32_16x16x32_bf16 v[98:101], v[170:173], v[200:203], 0
	v_mfma_f32_16x16x32_bf16 v[86:89], v[146:149], v[208:211], 0
	v_mfma_f32_16x16x32_bf16 v[82:85], v[170:173], v[208:211], 0
	v_mfma_f32_16x16x32_bf16 v[70:73], v[146:149], v[216:219], 0
	v_mfma_f32_16x16x32_bf16 v[66:69], v[170:173], v[216:219], 0
	v_mfma_f32_16x16x32_bf16 v[118:121], v[150:153], v[182:185], v[118:121]
	v_mfma_f32_16x16x32_bf16 v[114:117], v[174:177], v[182:185], v[114:117]
	v_mfma_f32_16x16x32_bf16 v[102:105], v[150:153], v[204:207], v[102:105]
	v_mfma_f32_16x16x32_bf16 v[98:101], v[174:177], v[204:207], v[98:101]
	v_mfma_f32_16x16x32_bf16 v[86:89], v[150:153], v[212:215], v[86:89]
	v_mfma_f32_16x16x32_bf16 v[82:85], v[174:177], v[212:215], v[82:85]
	v_mfma_f32_16x16x32_bf16 v[70:73], v[150:153], v[220:223], v[70:73]
	v_mfma_f32_16x16x32_bf16 v[66:69], v[174:177], v[220:223], v[66:69]
	s_setprio 0
	s_barrier
	s_add_i32 s62, s56, s47
	v_lshl_add_u64 v[186:187], s[42:43], 0, v[156:157]
	s_mov_b32 m0, s62
	ds_read_b128 v[178:181], v198 offset:16384
	ds_read_b128 v[182:185], v198 offset:17408
	ds_read_b128 v[200:203], v198 offset:18432
	ds_read_b128 v[204:207], v198 offset:19456
	ds_read_b128 v[208:211], v198 offset:20480
	ds_read_b128 v[212:215], v198 offset:21504
	ds_read_b128 v[216:219], v198 offset:22528
	ds_read_b128 v[220:223], v198 offset:23552
	global_load_lds_dwordx4 v[186:187], off
	s_add_i32 m0, s62, 0x2000
	s_add_u32 s62, s42, 0x40000
	v_lshl_add_u64 v[224:225], s[42:43], 0, v[160:161]
	s_addc_u32 s63, s43, 0
	s_add_i32 s64, s57, s47
	global_load_lds_dwordx4 v[224:225], off
	v_lshl_add_u64 v[226:227], s[62:63], 0, v[156:157]
	s_mov_b32 m0, s64
	v_lshl_add_u64 v[228:229], s[44:45], 0, v[158:159]
	global_load_lds_dwordx4 v[226:227], off
	v_lshl_add_u64 v[226:227], s[62:63], 0, v[160:161]
	s_add_i32 m0, s64, 0x2000
	s_nop 0
	global_load_lds_dwordx4 v[226:227], off
	v_lshl_add_u64 v[226:227], s[44:45], 0, v[154:155]
	s_mov_b32 m0, s39
	s_nop 0
	global_load_lds_dwordx4 v[226:227], off
	s_mov_b32 m0, s48
	s_nop 0
	global_load_lds_dwordx4 v[228:229], off
	s_waitcnt vmcnt(8)
	s_waitcnt lgkmcnt(0)
	s_barrier
; #define PG8_STAGE(bufoff, gbase, voff) do { _Pragma("unroll") for (int _i = 0; _i < 2; ++_i) \
;         __builtin_amdgcn_global_load_lds((const unsigned*)((const char*)(gbase) + (voff)[_i]), (LAS unsigned*)(lds + (bufoff) + ldsw + _i * 8192), 16, 0, 0); } while (0)
; #define PG8_LDA(dst, b, h) do { _Pragma("unroll") for (int m = 0; m < 4; ++m) _Pragma("unroll") for (int k = 0; k < 2; ++k) dst[m][k] = *(const LAS bf16x8*)(lds + PG8_SA(b, h) + aoff + m * 2048 + k * 1024); } while (0)
; #define PG8_LDB(dst, b, h) do { _Pragma("unroll") for (int n = 0; n < 2; ++n) _Pragma("unroll") for (int k = 0; k < 2; ++k) dst[n][k] = *(const LAS bf16x8*)(lds + PG8_SB(b, h) + boff + n * 2048 + k * 1024); } while (0)
; #define PG8_MMA(ai, bj, At, Bt) do { __builtin_amdgcn_s_setprio(3); _Pragma("unroll") for (int m = 0; m < 4; ++m) _Pragma("unroll") for (int n = 0; n < 2; ++n) _Pragma("unroll") for (int k = 0; k < 2; ++k) \
;         acc[ai][bj][m][n] = __builtin_amdgcn_mfma_f32_16x16x32_bf16(Bt[n][k], At[m][k], acc[ai][bj][m][n], 0, 0, 0); __builtin_amdgcn_s_setprio(0); } while (0)
; #define PG8_WAIT_V(n) asm volatile("s_waitcnt vmcnt(" #n ")" ::: "memory")
; #define PG8_WAIT_L(n) asm volatile("s_waitcnt lgkmcnt(" #n ")" ::: "memory")
; #define PG8_BAR __builtin_amdgcn_s_barrier()
; #define PG8_SCHED __builtin_amdgcn_sched_barrier(0)
; template <class Epi, bool ALIGN_EPI>
; __device__ __forceinline__ void gemm_phase(LAS unsigned char* lds, const Gemm g, const StaticOrder& S, const Epi& E) {
;     ...
;             PG8_WAIT_V(8); PG8_WAIT_L(0); PG8_BAR; PG8_MMA(1, 0, At, B0); PG8_MMA(1, 1, At, B1); PG8_BAR; PG8_SCHED;
;             PG8_LDB(B0, 1, 0); PG8_LDB(B1, 1, 1); PG8_SCHED; PG8_LDA(At, 1, 0); PG8_STAGE(PG8_SA(0, 1), a2 + hstep, voffA);
;             PG8_WAIT_V(8); PG8_WAIT_L(0); PG8_BAR; PG8_MMA(0, 0, At, B0); PG8_MMA(0, 1, At, B1); PG8_BAR; PG8_SCHED;
	s_setprio 3
	s_waitcnt lgkmcnt(0)
	v_mfma_f32_16x16x32_bf16 v[62:65], v[130:133], v[178:181], 0
	v_mfma_f32_16x16x32_bf16 v[58:61], v[138:141], v[178:181], 0
	v_mfma_f32_16x16x32_bf16 v[46:49], v[130:133], v[200:203], 0
	v_mfma_f32_16x16x32_bf16 v[42:45], v[138:141], v[200:203], 0
	v_mfma_f32_16x16x32_bf16 v[30:33], v[130:133], v[208:211], 0
	v_mfma_f32_16x16x32_bf16 v[26:29], v[138:141], v[208:211], 0
	v_mfma_f32_16x16x32_bf16 v[14:17], v[130:133], v[216:219], 0
	v_mfma_f32_16x16x32_bf16 v[10:13], v[138:141], v[216:219], 0
	v_mfma_f32_16x16x32_bf16 v[62:65], v[134:137], v[182:185], v[62:65]
	v_mfma_f32_16x16x32_bf16 v[58:61], v[142:145], v[182:185], v[58:61]
	v_mfma_f32_16x16x32_bf16 v[46:49], v[134:137], v[204:207], v[46:49]
	v_mfma_f32_16x16x32_bf16 v[42:45], v[142:145], v[204:207], v[42:45]
	v_mfma_f32_16x16x32_bf16 v[30:33], v[134:137], v[212:215], v[30:33]
	v_mfma_f32_16x16x32_bf16 v[26:29], v[142:145], v[212:215], v[26:29]
	v_mfma_f32_16x16x32_bf16 v[14:17], v[134:137], v[220:223], v[14:17]
	v_mfma_f32_16x16x32_bf16 v[10:13], v[142:145], v[220:223], v[10:13]
	s_setprio 0
	s_setprio 3
	v_mfma_f32_16x16x32_bf16 v[54:57], v[146:149], v[178:181], 0
	v_mfma_f32_16x16x32_bf16 v[50:53], v[170:173], v[178:181], 0
	v_mfma_f32_16x16x32_bf16 v[38:41], v[146:149], v[200:203], 0
	v_mfma_f32_16x16x32_bf16 v[34:37], v[170:173], v[200:203], 0
	v_mfma_f32_16x16x32_bf16 v[22:25], v[146:149], v[208:211], 0
	v_mfma_f32_16x16x32_bf16 v[18:21], v[170:173], v[208:211], 0
	v_mfma_f32_16x16x32_bf16 v[6:9], v[146:149], v[216:219], 0
	v_mfma_f32_16x16x32_bf16 v[2:5], v[170:173], v[216:219], 0
	v_mfma_f32_16x16x32_bf16 v[54:57], v[150:153], v[182:185], v[54:57]
	v_mfma_f32_16x16x32_bf16 v[50:53], v[174:177], v[182:185], v[50:53]
	v_mfma_f32_16x16x32_bf16 v[38:41], v[150:153], v[204:207], v[38:41]
	v_mfma_f32_16x16x32_bf16 v[34:37], v[174:177], v[204:207], v[34:37]
	v_mfma_f32_16x16x32_bf16 v[22:25], v[150:153], v[212:215], v[22:25]
	v_mfma_f32_16x16x32_bf16 v[18:21], v[174:177], v[212:215], v[18:21]
	v_mfma_f32_16x16x32_bf16 v[6:9], v[150:153], v[220:223], v[6:9]
	v_mfma_f32_16x16x32_bf16 v[2:5], v[174:177], v[220:223], v[2:5]
	s_setprio 0
	s_barrier
	s_add_i32 s62, 0, 0x18000
	s_add_i32 s63, 0, 0x1c000
	v_add_u32_e32 v142, s62, v194
	v_add_u32_e32 v174, s63, v194
	ds_read_b128 v[130:133], v142
	ds_read_b128 v[134:137], v142 offset:1024
	ds_read_b128 v[138:141], v142 offset:2048
	ds_read_b128 v[142:145], v142 offset:3072
	ds_read_b128 v[146:149], v174
	ds_read_b128 v[150:153], v174 offset:1024
	ds_read_b128 v[170:173], v174 offset:2048
	ds_read_b128 v[174:177], v174 offset:3072
	s_add_u32 s44, s44, 0x40000
	s_addc_u32 s45, s45, 0
	s_mov_b32 m0, s49
	v_lshl_add_u64 v[230:231], s[44:45], 0, v[154:155]
	ds_read_b128 v[178:181], v198 offset:32768
	ds_read_b128 v[182:185], v198 offset:33792
	ds_read_b128 v[200:203], v198 offset:34816
	ds_read_b128 v[204:207], v198 offset:35840
	ds_read_b128 v[208:211], v198 offset:36864
	ds_read_b128 v[212:215], v198 offset:37888
	ds_read_b128 v[216:219], v198 offset:38912
	ds_read_b128 v[220:223], v198 offset:39936
	global_load_lds_dwordx4 v[230:231], off
	v_lshl_add_u64 v[230:231], s[44:45], 0, v[158:159]
	s_mov_b32 m0, s50
	s_nop 0
	global_load_lds_dwordx4 v[230:231], off
	s_waitcnt vmcnt(8)
	s_waitcnt lgkmcnt(0)
	s_barrier
	s_setprio 3
	s_waitcnt lgkmcnt(0)
	v_mfma_f32_16x16x32_bf16 v[126:129], v[130:133], v[178:181], v[126:129]
	v_mfma_f32_16x16x32_bf16 v[122:125], v[138:141], v[178:181], v[122:125]
	v_mfma_f32_16x16x32_bf16 v[110:113], v[130:133], v[200:203], v[110:113]
	v_mfma_f32_16x16x32_bf16 v[106:109], v[138:141], v[200:203], v[106:109]
	v_mfma_f32_16x16x32_bf16 v[94:97], v[130:133], v[208:211], v[94:97]
	v_mfma_f32_16x16x32_bf16 v[90:93], v[138:141], v[208:211], v[90:93]
	v_mfma_f32_16x16x32_bf16 v[78:81], v[130:133], v[216:219], v[78:81]
	v_mfma_f32_16x16x32_bf16 v[74:77], v[138:141], v[216:219], v[74:77]
	v_mfma_f32_16x16x32_bf16 v[126:129], v[134:137], v[182:185], v[126:129]
	v_mfma_f32_16x16x32_bf16 v[122:125], v[142:145], v[182:185], v[122:125]
	v_mfma_f32_16x16x32_bf16 v[110:113], v[134:137], v[204:207], v[110:113]
	v_mfma_f32_16x16x32_bf16 v[106:109], v[142:145], v[204:207], v[106:109]
	v_mfma_f32_16x16x32_bf16 v[94:97], v[134:137], v[212:215], v[94:97]
	v_mfma_f32_16x16x32_bf16 v[90:93], v[142:145], v[212:215], v[90:93]
	v_mfma_f32_16x16x32_bf16 v[78:81], v[134:137], v[220:223], v[78:81]
	v_mfma_f32_16x16x32_bf16 v[74:77], v[142:145], v[220:223], v[74:77]
	s_setprio 0
	s_setprio 3
	v_mfma_f32_16x16x32_bf16 v[118:121], v[146:149], v[178:181], v[118:121]
	v_mfma_f32_16x16x32_bf16 v[114:117], v[170:173], v[178:181], v[114:117]
	v_mfma_f32_16x16x32_bf16 v[102:105], v[146:149], v[200:203], v[102:105]
	v_mfma_f32_16x16x32_bf16 v[98:101], v[170:173], v[200:203], v[98:101]
	v_mfma_f32_16x16x32_bf16 v[86:89], v[146:149], v[208:211], v[86:89]
	v_mfma_f32_16x16x32_bf16 v[82:85], v[170:173], v[208:211], v[82:85]
	v_mfma_f32_16x16x32_bf16 v[70:73], v[146:149], v[216:219], v[70:73]
	v_mfma_f32_16x16x32_bf16 v[66:69], v[170:173], v[216:219], v[66:69]
	v_mfma_f32_16x16x32_bf16 v[118:121], v[150:153], v[182:185], v[118:121]
	v_mfma_f32_16x16x32_bf16 v[114:117], v[174:177], v[182:185], v[114:117]
	v_mfma_f32_16x16x32_bf16 v[102:105], v[150:153], v[204:207], v[102:105]
	v_mfma_f32_16x16x32_bf16 v[98:101], v[174:177], v[204:207], v[98:101]
	v_mfma_f32_16x16x32_bf16 v[86:89], v[150:153], v[212:215], v[86:89]
	v_mfma_f32_16x16x32_bf16 v[82:85], v[174:177], v[212:215], v[82:85]
	v_mfma_f32_16x16x32_bf16 v[70:73], v[150:153], v[220:223], v[70:73]
	v_mfma_f32_16x16x32_bf16 v[66:69], v[174:177], v[220:223], v[66:69]
	s_setprio 0
	s_barrier
; #define PG8_STAGE(bufoff, gbase, voff) do { _Pragma("unroll") for (int _i = 0; _i < 2; ++_i) \
;         __builtin_amdgcn_global_load_lds((const unsigned*)((const char*)(gbase) + (voff)[_i]), (LAS unsigned*)(lds + (bufoff) + ldsw + _i * 8192), 16, 0, 0); } while (0)
; #define PG8_LDA(dst, b, h) do { _Pragma("unroll") for (int m = 0; m < 4; ++m) _Pragma("unroll") for (int k = 0; k < 2; ++k) dst[m][k] = *(const LAS bf16x8*)(lds + PG8_SA(b, h) + aoff + m * 2048 + k * 1024); } while (0)
; #define PG8_MMA(ai, bj, At, Bt) do { __builtin_amdgcn_s_setprio(3); _Pragma("unroll") for (int m = 0; m < 4; ++m) _Pragma("unroll") for (int n = 0; n < 2; ++n) _Pragma("unroll") for (int k = 0; k < 2; ++k) \
;         acc[ai][bj][m][n] = __builtin_amdgcn_mfma_f32_16x16x32_bf16(Bt[n][k], At[m][k], acc[ai][bj][m][n], 0, 0, 0); __builtin_amdgcn_s_setprio(0); } while (0)
; #define PG8_WAIT_V(n) asm volatile("s_waitcnt vmcnt(" #n ")" ::: "memory")
; #define PG8_WAIT_L(n) asm volatile("s_waitcnt lgkmcnt(" #n ")" ::: "memory")
; #define PG8_BAR __builtin_amdgcn_s_barrier()
; #define PG8_SCHED __builtin_amdgcn_sched_barrier(0)
; template <class Epi, bool ALIGN_EPI>
; __device__ __forceinline__ void gemm_phase(LAS unsigned char* lds, const Gemm g, const StaticOrder& S, const Epi& E) {
;     ...
;             PG8_LDA(At, 1, 1); PG8_STAGE(PG8_SB(1, 0), b3, voffB); PG8_STAGE(PG8_SB(1, 1), b3 + hstep, voffB); PG8_STAGE(PG8_SA(1, 0), a3, voffA);
;             PG8_WAIT_V(8); PG8_WAIT_L(0); PG8_BAR; PG8_MMA(1, 0, At, B0); PG8_MMA(1, 1, At, B1); PG8_BAR; PG8_SCHED;
	s_add_i32 s44, s62, s47
	v_lshl_add_u64 v[186:187], v[186:187], 0, s[12:13]
	s_mov_b32 m0, s44
	ds_read_b128 v[178:181], v198 offset:49152
	ds_read_b128 v[182:185], v198 offset:50176
	ds_read_b128 v[200:203], v198 offset:51200
	ds_read_b128 v[204:207], v198 offset:52224
	ds_read_b128 v[208:211], v198 offset:53248
	ds_read_b128 v[212:215], v198 offset:54272
	ds_read_b128 v[216:219], v198 offset:55296
	ds_read_b128 v[220:223], v198 offset:56320
	global_load_lds_dwordx4 v[186:187], off
	s_add_i32 m0, s44, 0x2000
	s_add_u32 s42, s42, 0x40080
	v_lshl_add_u64 v[186:187], v[224:225], 0, s[12:13]
	s_addc_u32 s43, s43, 0
	s_add_i32 s44, s63, s47
	global_load_lds_dwordx4 v[186:187], off
	v_lshl_add_u64 v[186:187], s[42:43], 0, v[156:157]
	s_mov_b32 m0, s44
	s_nop 0
	global_load_lds_dwordx4 v[186:187], off
	v_lshl_add_u64 v[186:187], s[42:43], 0, v[160:161]
	s_add_i32 m0, s44, 0x2000
	s_nop 0
	global_load_lds_dwordx4 v[186:187], off
	v_lshl_add_u64 v[186:187], v[226:227], 0, s[12:13]
	s_mov_b32 m0, s52
	s_nop 0
	global_load_lds_dwordx4 v[186:187], off
	v_lshl_add_u64 v[186:187], v[228:229], 0, s[12:13]
	s_mov_b32 m0, s53
	s_nop 0
	global_load_lds_dwordx4 v[186:187], off
	s_waitcnt vmcnt(8)
	s_waitcnt lgkmcnt(0)
	s_barrier
	s_setprio 3
	s_waitcnt lgkmcnt(0)
	v_mfma_f32_16x16x32_bf16 v[62:65], v[130:133], v[178:181], v[62:65]
	v_mfma_f32_16x16x32_bf16 v[58:61], v[138:141], v[178:181], v[58:61]
	v_mfma_f32_16x16x32_bf16 v[46:49], v[130:133], v[200:203], v[46:49]
	v_mfma_f32_16x16x32_bf16 v[42:45], v[138:141], v[200:203], v[42:45]
	v_mfma_f32_16x16x32_bf16 v[30:33], v[130:133], v[208:211], v[30:33]
	v_mfma_f32_16x16x32_bf16 v[26:29], v[138:141], v[208:211], v[26:29]
	v_mfma_f32_16x16x32_bf16 v[14:17], v[130:133], v[216:219], v[14:17]
	v_mfma_f32_16x16x32_bf16 v[10:13], v[138:141], v[216:219], v[10:13]
	v_mfma_f32_16x16x32_bf16 v[62:65], v[134:137], v[182:185], v[62:65]
	v_mfma_f32_16x16x32_bf16 v[58:61], v[142:145], v[182:185], v[58:61]
	v_mfma_f32_16x16x32_bf16 v[46:49], v[134:137], v[204:207], v[46:49]
	v_mfma_f32_16x16x32_bf16 v[42:45], v[142:145], v[204:207], v[42:45]
	v_mfma_f32_16x16x32_bf16 v[30:33], v[134:137], v[212:215], v[30:33]
	v_mfma_f32_16x16x32_bf16 v[26:29], v[142:145], v[212:215], v[26:29]
	v_mfma_f32_16x16x32_bf16 v[14:17], v[134:137], v[220:223], v[14:17]
	v_mfma_f32_16x16x32_bf16 v[10:13], v[142:145], v[220:223], v[10:13]
	s_setprio 0
	s_setprio 3
	v_mfma_f32_16x16x32_bf16 v[54:57], v[146:149], v[178:181], v[54:57]
	v_mfma_f32_16x16x32_bf16 v[50:53], v[170:173], v[178:181], v[50:53]
	v_mfma_f32_16x16x32_bf16 v[38:41], v[146:149], v[200:203], v[38:41]
	v_mfma_f32_16x16x32_bf16 v[34:37], v[170:173], v[200:203], v[34:37]
	v_mfma_f32_16x16x32_bf16 v[22:25], v[146:149], v[208:211], v[22:25]
	v_mfma_f32_16x16x32_bf16 v[18:21], v[170:173], v[208:211], v[18:21]
	v_mfma_f32_16x16x32_bf16 v[6:9], v[146:149], v[216:219], v[6:9]
	v_mfma_f32_16x16x32_bf16 v[2:5], v[170:173], v[216:219], v[2:5]
	v_mfma_f32_16x16x32_bf16 v[54:57], v[150:153], v[182:185], v[54:57]
	v_mfma_f32_16x16x32_bf16 v[50:53], v[174:177], v[182:185], v[50:53]
	v_mfma_f32_16x16x32_bf16 v[38:41], v[150:153], v[204:207], v[38:41]
	v_mfma_f32_16x16x32_bf16 v[34:37], v[174:177], v[204:207], v[34:37]
	v_mfma_f32_16x16x32_bf16 v[22:25], v[150:153], v[212:215], v[22:25]
	v_mfma_f32_16x16x32_bf16 v[18:21], v[174:177], v[212:215], v[18:21]
	v_mfma_f32_16x16x32_bf16 v[6:9], v[150:153], v[220:223], v[6:9]
	v_mfma_f32_16x16x32_bf16 v[2:5], v[174:177], v[220:223], v[2:5]
	s_setprio 0
	s_barrier
	s_add_i32 s61, s61, 2
	s_add_u32 s40, s40, 0x100
	s_addc_u32 s41, s41, 0
	s_add_u32 s59, s59, 0x100
	s_addc_u32 s60, s60, 0

; #define PG8_STAGE(bufoff, gbase, voff) do { _Pragma("unroll") for (int _i = 0; _i < 2; ++_i) \
;         __builtin_amdgcn_global_load_lds((const unsigned*)((const char*)(gbase) + (voff)[_i]), (LAS unsigned*)(lds + (bufoff) + ldsw + _i * 8192), 16, 0, 0); } while (0)
; #define PG8_LDA(dst, b, h) do { _Pragma("unroll") for (int m = 0; m < 4; ++m) _Pragma("unroll") for (int k = 0; k < 2; ++k) dst[m][k] = *(const LAS bf16x8*)(lds + PG8_SA(b, h) + aoff + m * 2048 + k * 1024); } while (0)
; #define PG8_LDB(dst, b, h) do { _Pragma("unroll") for (int n = 0; n < 2; ++n) _Pragma("unroll") for (int k = 0; k < 2; ++k) dst[n][k] = *(const LAS bf16x8*)(lds + PG8_SB(b, h) + boff + n * 2048 + k * 1024); } while (0)
; #define PG8_MMA(ai, bj, At, Bt) do { __builtin_amdgcn_s_setprio(3); _Pragma("unroll") for (int m = 0; m < 4; ++m) _Pragma("unroll") for (int n = 0; n < 2; ++n) _Pragma("unroll") for (int k = 0; k < 2; ++k) \
;         acc[ai][bj][m][n] = __builtin_amdgcn_mfma_f32_16x16x32_bf16(Bt[n][k], At[m][k], acc[ai][bj][m][n], 0, 0, 0); __builtin_amdgcn_s_setprio(0); } while (0)
; #define PG8_WAIT_V(n) asm volatile("s_waitcnt vmcnt(" #n ")" ::: "memory")
; #define PG8_WAIT_L(n) asm volatile("s_waitcnt lgkmcnt(" #n ")" ::: "memory")
; #define PG8_BAR __builtin_amdgcn_s_barrier()
; template <class Epi, bool ALIGN_EPI>
; __device__ __forceinline__ void gemm_phase(LAS unsigned char* lds, const Gemm g, const StaticOrder& S, const Epi& E) {
;     ...
;         const char* nA = has_next ? (const char*)g.A + (size_t)nxt.pm * tstep : cA; const char* nB = has_next ? (const char*)g.Bt + (size_t)nxt.pn * tstep : cB;
;         for (int t = 0; t < nt; t += 2) {
;             const bool last = (t == nt - 2);
;             const char* a1 = cA + (size_t)(t + 1) * kstep;
;             const char* a2 = last ? nA : cA + (size_t)(t + 2) * kstep; const char* b2 = last ? nB : cB + (size_t)(t + 2) * kstep;
;             const char* a3 = a2 + kstep; const char* b3 = b2 + kstep;
;             PG8_LDB(B0, 0, 0); PG8_LDB(B1, 0, 1); PG8_SCHED; PG8_LDA(At, 0, 0); PG8_STAGE(PG8_SA(1, 1), a1 + hstep, voffA);
;             PG8_WAIT_V(8); PG8_WAIT_L(0); PG8_BAR; PG8_MMA(0, 0, At, B0); PG8_MMA(0, 1, At, B1); PG8_BAR; PG8_SCHED;
;             PG8_LDA(At, 0, 1); PG8_STAGE(PG8_SB(0, 0), b2, voffB); PG8_STAGE(PG8_SB(0, 1), b2 + hstep, voffB); PG8_STAGE(PG8_SA(0, 0), a2, voffA);
.LBB0_1427:
	s_ashr_i32 s43, s42, 31
	s_lshl_b64 s[10:11], s[42:43], 19
	s_add_u32 s44, s34, s10
	s_addc_u32 s45, s35, s11
	s_and_b64 s[10:11], s[0:1], exec
	s_cselect_b32 s12, s45, s7
	s_cselect_b32 s13, s44, s6
	s_ashr_i32 s41, s40, 31
	s_lshl_b64 s[10:11], s[40:41], 19
	s_add_u32 s46, s22, s10
	s_addc_u32 s47, s23, s11
	s_and_b64 s[10:11], s[0:1], exec
	s_cselect_b32 s14, s47, s9
	s_cselect_b32 s15, s46, s8
	s_add_u32 s6, s6, 0x40080
	s_addc_u32 s7, s7, 0
	s_add_u32 s16, s8, 0x100
	s_addc_u32 s17, s9, 0
	s_mov_b32 s41, -2
	ds_read_b128 v[146:149], v168
	ds_read_b128 v[150:153], v168 offset:1024
	ds_read_b128 v[154:157], v168 offset:2048
	ds_read_b128 v[158:161], v168 offset:3072
	ds_read_b128 v[172:175], v169
	ds_read_b128 v[176:179], v169 offset:1024
	ds_read_b128 v[180:183], v169 offset:2048
	ds_read_b128 v[184:187], v169 offset:3072
	s_add_u32 s8, s6, 0xfffc0080
	s_addc_u32 s9, s7, -1
	s_cmp_eq_u32 s41, 12
	s_cselect_b32 s11, s12, s9
	s_cselect_b32 s10, s13, s8
	s_cselect_b32 s9, s14, s17
	s_cselect_b32 s8, s15, s16
	v_lshl_add_u64 v[220:221], s[6:7], 0, v[138:139]
	s_add_i32 m0, s50, 0xc000
	ds_read_b128 v[188:191], v170
	ds_read_b128 v[192:195], v170 offset:1024
	ds_read_b128 v[196:199], v170 offset:2048
	ds_read_b128 v[200:203], v170 offset:3072
	ds_read_b128 v[204:207], v170 offset:4096
	ds_read_b128 v[208:211], v170 offset:5120
	ds_read_b128 v[212:215], v170 offset:6144
	ds_read_b128 v[216:219], v170 offset:7168
	global_load_lds_dwordx4 v[220:221], off
	v_lshl_add_u64 v[220:221], s[6:7], 0, v[140:141]
	s_add_i32 m0, s50, 0xe000
	s_nop 0
	global_load_lds_dwordx4 v[220:221], off
	s_waitcnt vmcnt(8)
	s_waitcnt lgkmcnt(0)
	s_barrier
	s_setprio 3
	s_waitcnt lgkmcnt(0)
	v_mfma_f32_16x16x32_bf16 v[126:129], v[146:149], v[188:191], 0
	v_mfma_f32_16x16x32_bf16 v[118:121], v[154:157], v[188:191], 0
	v_mfma_f32_16x16x32_bf16 v[110:113], v[146:149], v[196:199], 0
	v_mfma_f32_16x16x32_bf16 v[102:105], v[154:157], v[196:199], 0
	v_mfma_f32_16x16x32_bf16 v[94:97], v[146:149], v[204:207], 0
	v_mfma_f32_16x16x32_bf16 v[86:89], v[154:157], v[204:207], 0
	v_mfma_f32_16x16x32_bf16 v[78:81], v[146:149], v[212:215], 0
	v_mfma_f32_16x16x32_bf16 v[70:73], v[154:157], v[212:215], 0
	v_mfma_f32_16x16x32_bf16 v[126:129], v[150:153], v[192:195], v[126:129]
	v_mfma_f32_16x16x32_bf16 v[118:121], v[158:161], v[192:195], v[118:121]
	v_mfma_f32_16x16x32_bf16 v[110:113], v[150:153], v[200:203], v[110:113]
	v_mfma_f32_16x16x32_bf16 v[102:105], v[158:161], v[200:203], v[102:105]
	v_mfma_f32_16x16x32_bf16 v[94:97], v[150:153], v[208:211], v[94:97]
	v_mfma_f32_16x16x32_bf16 v[86:89], v[158:161], v[208:211], v[86:89]
	v_mfma_f32_16x16x32_bf16 v[78:81], v[150:153], v[216:219], v[78:81]
	v_mfma_f32_16x16x32_bf16 v[70:73], v[158:161], v[216:219], v[70:73]
	s_setprio 0
	s_setprio 3
	v_mfma_f32_16x16x32_bf16 v[122:125], v[172:175], v[188:191], 0
	v_mfma_f32_16x16x32_bf16 v[114:117], v[180:183], v[188:191], 0
	v_mfma_f32_16x16x32_bf16 v[106:109], v[172:175], v[196:199], 0
	v_mfma_f32_16x16x32_bf16 v[98:101], v[180:183], v[196:199], 0
	v_mfma_f32_16x16x32_bf16 v[90:93], v[172:175], v[204:207], 0
	v_mfma_f32_16x16x32_bf16 v[82:85], v[180:183], v[204:207], 0
	v_mfma_f32_16x16x32_bf16 v[74:77], v[172:175], v[212:215], 0
	v_mfma_f32_16x16x32_bf16 v[66:69], v[180:183], v[212:215], 0
	v_mfma_f32_16x16x32_bf16 v[122:125], v[176:179], v[192:195], v[122:125]
	v_mfma_f32_16x16x32_bf16 v[114:117], v[184:187], v[192:195], v[114:117]
	v_mfma_f32_16x16x32_bf16 v[106:109], v[176:179], v[200:203], v[106:109]
	v_mfma_f32_16x16x32_bf16 v[98:101], v[184:187], v[200:203], v[98:101]
	v_mfma_f32_16x16x32_bf16 v[90:93], v[176:179], v[208:211], v[90:93]
	v_mfma_f32_16x16x32_bf16 v[82:85], v[184:187], v[208:211], v[82:85]
	v_mfma_f32_16x16x32_bf16 v[74:77], v[176:179], v[216:219], v[74:77]
	v_mfma_f32_16x16x32_bf16 v[66:69], v[184:187], v[216:219], v[66:69]
	s_setprio 0
	s_barrier
	s_add_i32 s43, s58, s33
	v_lshl_add_u64 v[220:221], s[8:9], 0, v[132:133]
	s_mov_b32 m0, s43
	ds_read_b128 v[188:191], v170 offset:16384
	ds_read_b128 v[192:195], v170 offset:17408
	ds_read_b128 v[196:199], v170 offset:18432
	ds_read_b128 v[200:203], v170 offset:19456
	ds_read_b128 v[204:207], v170 offset:20480
	ds_read_b128 v[208:211], v170 offset:21504
	ds_read_b128 v[212:215], v170 offset:22528
	ds_read_b128 v[216:219], v170 offset:23552
	global_load_lds_dwordx4 v[220:221], off
	s_add_i32 m0, s43, 0x2000
	s_add_u32 s62, s8, 0x40000
	v_lshl_add_u64 v[222:223], s[8:9], 0, v[136:137]
	s_addc_u32 s63, s9, 0
	s_add_i32 s43, s59, s33
	global_load_lds_dwordx4 v[222:223], off
	v_lshl_add_u64 v[224:225], s[62:63], 0, v[132:133]
	s_mov_b32 m0, s43
	v_lshl_add_u64 v[226:227], s[10:11], 0, v[134:135]
	global_load_lds_dwordx4 v[224:225], off
	v_lshl_add_u64 v[224:225], s[62:63], 0, v[136:137]
	s_add_i32 m0, s43, 0x2000
	s_nop 0
	global_load_lds_dwordx4 v[224:225], off
	v_lshl_add_u64 v[224:225], s[10:11], 0, v[130:131]
	s_mov_b32 m0, s50
	s_nop 0
	global_load_lds_dwordx4 v[224:225], off
	s_mov_b32 m0, s51
	s_nop 0
	global_load_lds_dwordx4 v[226:227], off
	s_waitcnt vmcnt(8)
	s_waitcnt lgkmcnt(0)
	s_barrier
; #define PG8_STAGE(bufoff, gbase, voff) do { _Pragma("unroll") for (int _i = 0; _i < 2; ++_i) \
;         __builtin_amdgcn_global_load_lds((const unsigned*)((const char*)(gbase) + (voff)[_i]), (LAS unsigned*)(lds + (bufoff) + ldsw + _i * 8192), 16, 0, 0); } while (0)
; #define PG8_LDA(dst, b, h) do { _Pragma("unroll") for (int m = 0; m < 4; ++m) _Pragma("unroll") for (int k = 0; k < 2; ++k) dst[m][k] = *(const LAS bf16x8*)(lds + PG8_SA(b, h) + aoff + m * 2048 + k * 1024); } while (0)
; #define PG8_LDB(dst, b, h) do { _Pragma("unroll") for (int n = 0; n < 2; ++n) _Pragma("unroll") for (int k = 0; k < 2; ++k) dst[n][k] = *(const LAS bf16x8*)(lds + PG8_SB(b, h) + boff + n * 2048 + k * 1024); } while (0)
; #define PG8_MMA(ai, bj, At, Bt) do { __builtin_amdgcn_s_setprio(3); _Pragma("unroll") for (int m = 0; m < 4; ++m) _Pragma("unroll") for (int n = 0; n < 2; ++n) _Pragma("unroll") for (int k = 0; k < 2; ++k) \
;         acc[ai][bj][m][n] = __builtin_amdgcn_mfma_f32_16x16x32_bf16(Bt[n][k], At[m][k], acc[ai][bj][m][n], 0, 0, 0); __builtin_amdgcn_s_setprio(0); } while (0)
; #define PG8_WAIT_V(n) asm volatile("s_waitcnt vmcnt(" #n ")" ::: "memory")
; #define PG8_WAIT_L(n) asm volatile("s_waitcnt lgkmcnt(" #n ")" ::: "memory")
; #define PG8_BAR __builtin_amdgcn_s_barrier()
; #define PG8_SCHED __builtin_amdgcn_sched_barrier(0)
; template <class Epi, bool ALIGN_EPI>
; __device__ __forceinline__ void gemm_phase(LAS unsigned char* lds, const Gemm g, const StaticOrder& S, const Epi& E) {
;     ...
;             PG8_WAIT_V(8); PG8_WAIT_L(0); PG8_BAR; PG8_MMA(1, 0, At, B0); PG8_MMA(1, 1, At, B1); PG8_BAR; PG8_SCHED;
;             PG8_LDB(B0, 1, 0); PG8_LDB(B1, 1, 1); PG8_SCHED; PG8_LDA(At, 1, 0); PG8_STAGE(PG8_SA(0, 1), a2 + hstep, voffA);
;             PG8_WAIT_V(8); PG8_WAIT_L(0); PG8_BAR; PG8_MMA(0, 0, At, B0); PG8_MMA(0, 1, At, B1); PG8_BAR; PG8_SCHED;
	s_setprio 3
	s_waitcnt lgkmcnt(0)
	v_mfma_f32_16x16x32_bf16 v[62:65], v[146:149], v[188:191], 0
	v_mfma_f32_16x16x32_bf16 v[54:57], v[154:157], v[188:191], 0
	v_mfma_f32_16x16x32_bf16 v[46:49], v[146:149], v[196:199], 0
	v_mfma_f32_16x16x32_bf16 v[38:41], v[154:157], v[196:199], 0
	v_mfma_f32_16x16x32_bf16 v[30:33], v[146:149], v[204:207], 0
	v_mfma_f32_16x16x32_bf16 v[22:25], v[154:157], v[204:207], 0
	v_mfma_f32_16x16x32_bf16 v[14:17], v[146:149], v[212:215], 0
	v_mfma_f32_16x16x32_bf16 v[6:9], v[154:157], v[212:215], 0
	v_mfma_f32_16x16x32_bf16 v[62:65], v[150:153], v[192:195], v[62:65]
	v_mfma_f32_16x16x32_bf16 v[54:57], v[158:161], v[192:195], v[54:57]
	v_mfma_f32_16x16x32_bf16 v[46:49], v[150:153], v[200:203], v[46:49]
	v_mfma_f32_16x16x32_bf16 v[38:41], v[158:161], v[200:203], v[38:41]
	v_mfma_f32_16x16x32_bf16 v[30:33], v[150:153], v[208:211], v[30:33]
	v_mfma_f32_16x16x32_bf16 v[22:25], v[158:161], v[208:211], v[22:25]
	v_mfma_f32_16x16x32_bf16 v[14:17], v[150:153], v[216:219], v[14:17]
	v_mfma_f32_16x16x32_bf16 v[6:9], v[158:161], v[216:219], v[6:9]
	s_setprio 0
	s_setprio 3
	v_mfma_f32_16x16x32_bf16 v[58:61], v[172:175], v[188:191], 0
	v_mfma_f32_16x16x32_bf16 v[50:53], v[180:183], v[188:191], 0
	v_mfma_f32_16x16x32_bf16 v[42:45], v[172:175], v[196:199], 0
	v_mfma_f32_16x16x32_bf16 v[34:37], v[180:183], v[196:199], 0
	v_mfma_f32_16x16x32_bf16 v[26:29], v[172:175], v[204:207], 0
	v_mfma_f32_16x16x32_bf16 v[18:21], v[180:183], v[204:207], 0
	v_mfma_f32_16x16x32_bf16 v[10:13], v[172:175], v[212:215], 0
	v_mfma_f32_16x16x32_bf16 v[2:5], v[180:183], v[212:215], 0
	v_mfma_f32_16x16x32_bf16 v[58:61], v[176:179], v[192:195], v[58:61]
	v_mfma_f32_16x16x32_bf16 v[50:53], v[184:187], v[192:195], v[50:53]
	v_mfma_f32_16x16x32_bf16 v[42:45], v[176:179], v[200:203], v[42:45]
	v_mfma_f32_16x16x32_bf16 v[34:37], v[184:187], v[200:203], v[34:37]
	v_mfma_f32_16x16x32_bf16 v[26:29], v[176:179], v[208:211], v[26:29]
	v_mfma_f32_16x16x32_bf16 v[18:21], v[184:187], v[208:211], v[18:21]
	v_mfma_f32_16x16x32_bf16 v[10:13], v[176:179], v[216:219], v[10:13]
	v_mfma_f32_16x16x32_bf16 v[2:5], v[184:187], v[216:219], v[2:5]
	s_setprio 0
	s_barrier
	s_add_i32 s43, 0, 0x18000
	s_add_i32 s62, 0, 0x1c000
	v_add_u32_e32 v158, s43, v166
	v_add_u32_e32 v184, s62, v166
	ds_read_b128 v[146:149], v158
	ds_read_b128 v[150:153], v158 offset:1024
	ds_read_b128 v[154:157], v158 offset:2048
	ds_read_b128 v[158:161], v158 offset:3072
	ds_read_b128 v[172:175], v184
	ds_read_b128 v[176:179], v184 offset:1024
	ds_read_b128 v[180:183], v184 offset:2048
	ds_read_b128 v[184:187], v184 offset:3072
	s_add_u32 s10, s10, 0x40000
	s_addc_u32 s11, s11, 0
	s_mov_b32 m0, s52
	v_lshl_add_u64 v[228:229], s[10:11], 0, v[130:131]
	ds_read_b128 v[188:191], v170 offset:32768
	ds_read_b128 v[192:195], v170 offset:33792
	ds_read_b128 v[196:199], v170 offset:34816
	ds_read_b128 v[200:203], v170 offset:35840
	ds_read_b128 v[204:207], v170 offset:36864
	ds_read_b128 v[208:211], v170 offset:37888
	ds_read_b128 v[212:215], v170 offset:38912
	ds_read_b128 v[216:219], v170 offset:39936
	global_load_lds_dwordx4 v[228:229], off
	v_lshl_add_u64 v[228:229], s[10:11], 0, v[134:135]
	s_mov_b32 m0, s53
	s_nop 0
	global_load_lds_dwordx4 v[228:229], off
	s_waitcnt vmcnt(8)
	s_waitcnt lgkmcnt(0)
	s_barrier
	s_setprio 3
	s_waitcnt lgkmcnt(0)
	v_mfma_f32_16x16x32_bf16 v[126:129], v[146:149], v[188:191], v[126:129]
	v_mfma_f32_16x16x32_bf16 v[118:121], v[154:157], v[188:191], v[118:121]
	v_mfma_f32_16x16x32_bf16 v[110:113], v[146:149], v[196:199], v[110:113]
	v_mfma_f32_16x16x32_bf16 v[102:105], v[154:157], v[196:199], v[102:105]
	v_mfma_f32_16x16x32_bf16 v[94:97], v[146:149], v[204:207], v[94:97]
	v_mfma_f32_16x16x32_bf16 v[86:89], v[154:157], v[204:207], v[86:89]
	v_mfma_f32_16x16x32_bf16 v[78:81], v[146:149], v[212:215], v[78:81]
	v_mfma_f32_16x16x32_bf16 v[70:73], v[154:157], v[212:215], v[70:73]
	v_mfma_f32_16x16x32_bf16 v[126:129], v[150:153], v[192:195], v[126:129]
	v_mfma_f32_16x16x32_bf16 v[118:121], v[158:161], v[192:195], v[118:121]
	v_mfma_f32_16x16x32_bf16 v[110:113], v[150:153], v[200:203], v[110:113]
	v_mfma_f32_16x16x32_bf16 v[102:105], v[158:161], v[200:203], v[102:105]
	v_mfma_f32_16x16x32_bf16 v[94:97], v[150:153], v[208:211], v[94:97]
	v_mfma_f32_16x16x32_bf16 v[86:89], v[158:161], v[208:211], v[86:89]
	v_mfma_f32_16x16x32_bf16 v[78:81], v[150:153], v[216:219], v[78:81]
	v_mfma_f32_16x16x32_bf16 v[70:73], v[158:161], v[216:219], v[70:73]
	s_setprio 0
	s_setprio 3
	v_mfma_f32_16x16x32_bf16 v[122:125], v[172:175], v[188:191], v[122:125]
	v_mfma_f32_16x16x32_bf16 v[114:117], v[180:183], v[188:191], v[114:117]
	v_mfma_f32_16x16x32_bf16 v[106:109], v[172:175], v[196:199], v[106:109]
	v_mfma_f32_16x16x32_bf16 v[98:101], v[180:183], v[196:199], v[98:101]
	v_mfma_f32_16x16x32_bf16 v[90:93], v[172:175], v[204:207], v[90:93]
	v_mfma_f32_16x16x32_bf16 v[82:85], v[180:183], v[204:207], v[82:85]
	v_mfma_f32_16x16x32_bf16 v[74:77], v[172:175], v[212:215], v[74:77]
	v_mfma_f32_16x16x32_bf16 v[66:69], v[180:183], v[212:215], v[66:69]
	v_mfma_f32_16x16x32_bf16 v[122:125], v[176:179], v[192:195], v[122:125]
	v_mfma_f32_16x16x32_bf16 v[114:117], v[184:187], v[192:195], v[114:117]
	v_mfma_f32_16x16x32_bf16 v[106:109], v[176:179], v[200:203], v[106:109]
	v_mfma_f32_16x16x32_bf16 v[98:101], v[184:187], v[200:203], v[98:101]
	v_mfma_f32_16x16x32_bf16 v[90:93], v[176:179], v[208:211], v[90:93]
	v_mfma_f32_16x16x32_bf16 v[82:85], v[184:187], v[208:211], v[82:85]
	v_mfma_f32_16x16x32_bf16 v[74:77], v[176:179], v[216:219], v[74:77]
	v_mfma_f32_16x16x32_bf16 v[66:69], v[184:187], v[216:219], v[66:69]
	s_setprio 0
	s_barrier
; #define PG8_STAGE(bufoff, gbase, voff) do { _Pragma("unroll") for (int _i = 0; _i < 2; ++_i) \
;         __builtin_amdgcn_global_load_lds((const unsigned*)((const char*)(gbase) + (voff)[_i]), (LAS unsigned*)(lds + (bufoff) + ldsw + _i * 8192), 16, 0, 0); } while (0)
; #define PG8_LDA(dst, b, h) do { _Pragma("unroll") for (int m = 0; m < 4; ++m) _Pragma("unroll") for (int k = 0; k < 2; ++k) dst[m][k] = *(const LAS bf16x8*)(lds + PG8_SA(b, h) + aoff + m * 2048 + k * 1024); } while (0)
; #define PG8_MMA(ai, bj, At, Bt) do { __builtin_amdgcn_s_setprio(3); _Pragma("unroll") for (int m = 0; m < 4; ++m) _Pragma("unroll") for (int n = 0; n < 2; ++n) _Pragma("unroll") for (int k = 0; k < 2; ++k) \
;         acc[ai][bj][m][n] = __builtin_amdgcn_mfma_f32_16x16x32_bf16(Bt[n][k], At[m][k], acc[ai][bj][m][n], 0, 0, 0); __builtin_amdgcn_s_setprio(0); } while (0)
; #define PG8_WAIT_V(n) asm volatile("s_waitcnt vmcnt(" #n ")" ::: "memory")
; #define PG8_WAIT_L(n) asm volatile("s_waitcnt lgkmcnt(" #n ")" ::: "memory")
; #define PG8_BAR __builtin_amdgcn_s_barrier()
; #define PG8_SCHED __builtin_amdgcn_sched_barrier(0)
; template <class Epi, bool ALIGN_EPI>
; __device__ __forceinline__ void gemm_phase(LAS unsigned char* lds, const Gemm g, const StaticOrder& S, const Epi& E) {
;     ...
;             PG8_LDA(At, 1, 1); PG8_STAGE(PG8_SB(1, 0), b3, voffB); PG8_STAGE(PG8_SB(1, 1), b3 + hstep, voffB); PG8_STAGE(PG8_SA(1, 0), a3, voffA);
;             PG8_WAIT_V(8); PG8_WAIT_L(0); PG8_BAR; PG8_MMA(1, 0, At, B0); PG8_MMA(1, 1, At, B1); PG8_BAR; PG8_SCHED;
	s_add_i32 s10, s43, s33
	v_lshl_add_u64 v[220:221], v[220:221], 0, s[36:37]
	s_mov_b32 m0, s10
	ds_read_b128 v[188:191], v170 offset:49152
	ds_read_b128 v[192:195], v170 offset:50176
	ds_read_b128 v[196:199], v170 offset:51200
	ds_read_b128 v[200:203], v170 offset:52224
	ds_read_b128 v[204:207], v170 offset:53248
	ds_read_b128 v[208:211], v170 offset:54272
	ds_read_b128 v[212:215], v170 offset:55296
	ds_read_b128 v[216:219], v170 offset:56320
	global_load_lds_dwordx4 v[220:221], off
	s_add_i32 m0, s10, 0x2000
	s_add_u32 s8, s8, 0x40080
	v_lshl_add_u64 v[220:221], v[222:223], 0, s[36:37]
	s_addc_u32 s9, s9, 0
	s_add_i32 s10, s62, s33
	global_load_lds_dwordx4 v[220:221], off
	v_lshl_add_u64 v[220:221], s[8:9], 0, v[132:133]
	s_mov_b32 m0, s10
	s_nop 0
	global_load_lds_dwordx4 v[220:221], off
	v_lshl_add_u64 v[220:221], s[8:9], 0, v[136:137]
	s_add_i32 m0, s10, 0x2000
	s_nop 0
	global_load_lds_dwordx4 v[220:221], off
	v_lshl_add_u64 v[220:221], v[224:225], 0, s[36:37]
	s_mov_b32 m0, s56
	s_nop 0
	global_load_lds_dwordx4 v[220:221], off
	v_lshl_add_u64 v[220:221], v[226:227], 0, s[36:37]
	s_mov_b32 m0, s57
	s_nop 0
	global_load_lds_dwordx4 v[220:221], off
	s_waitcnt vmcnt(8)
	s_waitcnt lgkmcnt(0)
	s_barrier
	s_setprio 3
	s_waitcnt lgkmcnt(0)
	v_mfma_f32_16x16x32_bf16 v[62:65], v[146:149], v[188:191], v[62:65]
	v_mfma_f32_16x16x32_bf16 v[54:57], v[154:157], v[188:191], v[54:57]
	v_mfma_f32_16x16x32_bf16 v[46:49], v[146:149], v[196:199], v[46:49]
	v_mfma_f32_16x16x32_bf16 v[38:41], v[154:157], v[196:199], v[38:41]
	v_mfma_f32_16x16x32_bf16 v[30:33], v[146:149], v[204:207], v[30:33]
	v_mfma_f32_16x16x32_bf16 v[22:25], v[154:157], v[204:207], v[22:25]
	v_mfma_f32_16x16x32_bf16 v[14:17], v[146:149], v[212:215], v[14:17]
	v_mfma_f32_16x16x32_bf16 v[6:9], v[154:157], v[212:215], v[6:9]
	v_mfma_f32_16x16x32_bf16 v[62:65], v[150:153], v[192:195], v[62:65]
	v_mfma_f32_16x16x32_bf16 v[54:57], v[158:161], v[192:195], v[54:57]
	v_mfma_f32_16x16x32_bf16 v[46:49], v[150:153], v[200:203], v[46:49]
	v_mfma_f32_16x16x32_bf16 v[38:41], v[158:161], v[200:203], v[38:41]
	v_mfma_f32_16x16x32_bf16 v[30:33], v[150:153], v[208:211], v[30:33]
	v_mfma_f32_16x16x32_bf16 v[22:25], v[158:161], v[208:211], v[22:25]
	v_mfma_f32_16x16x32_bf16 v[14:17], v[150:153], v[216:219], v[14:17]
	v_mfma_f32_16x16x32_bf16 v[6:9], v[158:161], v[216:219], v[6:9]
	s_setprio 0
	s_setprio 3
	v_mfma_f32_16x16x32_bf16 v[58:61], v[172:175], v[188:191], v[58:61]
	v_mfma_f32_16x16x32_bf16 v[50:53], v[180:183], v[188:191], v[50:53]
	v_mfma_f32_16x16x32_bf16 v[42:45], v[172:175], v[196:199], v[42:45]
	v_mfma_f32_16x16x32_bf16 v[34:37], v[180:183], v[196:199], v[34:37]
	v_mfma_f32_16x16x32_bf16 v[26:29], v[172:175], v[204:207], v[26:29]
	v_mfma_f32_16x16x32_bf16 v[18:21], v[180:183], v[204:207], v[18:21]
	v_mfma_f32_16x16x32_bf16 v[10:13], v[172:175], v[212:215], v[10:13]
	v_mfma_f32_16x16x32_bf16 v[2:5], v[180:183], v[212:215], v[2:5]
	v_mfma_f32_16x16x32_bf16 v[58:61], v[176:179], v[192:195], v[58:61]
	v_mfma_f32_16x16x32_bf16 v[50:53], v[184:187], v[192:195], v[50:53]
	v_mfma_f32_16x16x32_bf16 v[42:45], v[176:179], v[200:203], v[42:45]
	v_mfma_f32_16x16x32_bf16 v[34:37], v[184:187], v[200:203], v[34:37]
	v_mfma_f32_16x16x32_bf16 v[26:29], v[176:179], v[208:211], v[26:29]
	v_mfma_f32_16x16x32_bf16 v[18:21], v[184:187], v[208:211], v[18:21]
	v_mfma_f32_16x16x32_bf16 v[10:13], v[176:179], v[216:219], v[10:13]
	v_mfma_f32_16x16x32_bf16 v[2:5], v[184:187], v[216:219], v[2:5]
	s_setprio 0
	s_barrier
	s_add_i32 s41, s41, 2
	s_add_u32 s6, s6, 0x100
	s_addc_u32 s7, s7, 0
	s_add_u32 s16, s16, 0x100
	s_addc_u32 s17, s17, 0

; #define PG8_STAGE(bufoff, gbase, voff) do { _Pragma("unroll") for (int _i = 0; _i < 2; ++_i) \
;         __builtin_amdgcn_global_load_lds((const unsigned*)((const char*)(gbase) + (voff)[_i]), (LAS unsigned*)(lds + (bufoff) + ldsw + _i * 8192), 16, 0, 0); } while (0)
; #define PG8_LDA(dst, b, h) do { _Pragma("unroll") for (int m = 0; m < 4; ++m) _Pragma("unroll") for (int k = 0; k < 2; ++k) dst[m][k] = *(const LAS bf16x8*)(lds + PG8_SA(b, h) + aoff + m * 2048 + k * 1024); } while (0)
; #define PG8_LDB(dst, b, h) do { _Pragma("unroll") for (int n = 0; n < 2; ++n) _Pragma("unroll") for (int k = 0; k < 2; ++k) dst[n][k] = *(const LAS bf16x8*)(lds + PG8_SB(b, h) + boff + n * 2048 + k * 1024); } while (0)
; #define PG8_MMA(ai, bj, At, Bt) do { __builtin_amdgcn_s_setprio(3); _Pragma("unroll") for (int m = 0; m < 4; ++m) _Pragma("unroll") for (int n = 0; n < 2; ++n) _Pragma("unroll") for (int k = 0; k < 2; ++k) \
;         acc[ai][bj][m][n] = __builtin_amdgcn_mfma_f32_16x16x32_bf16(Bt[n][k], At[m][k], acc[ai][bj][m][n], 0, 0, 0); __builtin_amdgcn_s_setprio(0); } while (0)
; #define PG8_WAIT_V(n) asm volatile("s_waitcnt vmcnt(" #n ")" ::: "memory")
; #define PG8_WAIT_L(n) asm volatile("s_waitcnt lgkmcnt(" #n ")" ::: "memory")
; #define PG8_BAR __builtin_amdgcn_s_barrier()
; template <class Epi, bool ALIGN_EPI>
; __device__ __forceinline__ void gemm_phase(LAS unsigned char* lds, const Gemm g, const StaticOrder& S, const Epi& E) {
;     ...
;         const char* nA = has_next ? (const char*)g.A + (size_t)nxt.pm * tstep : cA; const char* nB = has_next ? (const char*)g.Bt + (size_t)nxt.pn * tstep : cB;
;         for (int t = 0; t < nt; t += 2) {
;             const bool last = (t == nt - 2);
;             const char* a1 = cA + (size_t)(t + 1) * kstep;
;             const char* a2 = last ? nA : cA + (size_t)(t + 2) * kstep; const char* b2 = last ? nB : cB + (size_t)(t + 2) * kstep;
;             const char* a3 = a2 + kstep; const char* b3 = b2 + kstep;
;             PG8_LDB(B0, 0, 0); PG8_LDB(B1, 0, 1); PG8_SCHED; PG8_LDA(At, 0, 0); PG8_STAGE(PG8_SA(1, 1), a1 + hstep, voffA);
;             PG8_WAIT_V(8); PG8_WAIT_L(0); PG8_BAR; PG8_MMA(0, 0, At, B0); PG8_MMA(0, 1, At, B1); PG8_BAR; PG8_SCHED;
;             PG8_LDA(At, 0, 1); PG8_STAGE(PG8_SB(0, 0), b2, voffB); PG8_STAGE(PG8_SB(0, 1), b2 + hstep, voffB); PG8_STAGE(PG8_SA(0, 0), a2, voffA);
.LBB0_1512:
	s_add_u32 s14, s14, 0xb0080
	s_addc_u32 s15, s15, 0
	s_add_u32 s43, s16, 0x100
	s_addc_u32 s44, s17, 0
	s_mov_b32 s45, -2
	ds_read_b128 v[144:147], v158
	ds_read_b128 v[148:151], v158 offset:1024
	ds_read_b128 v[162:165], v158 offset:2048
	ds_read_b128 v[166:169], v158 offset:3072
	ds_read_b128 v[170:173], v159
	ds_read_b128 v[174:177], v159 offset:1024
	ds_read_b128 v[178:181], v159 offset:2048
	ds_read_b128 v[182:185], v159 offset:3072
	s_add_u32 s16, s14, 0xfff50080
	s_addc_u32 s17, s15, -1
	s_cmp_eq_u32 s45, 40
	s_cselect_b32 s19, s5, s17
	s_cselect_b32 s18, s4, s16
	s_cselect_b32 s17, s13, s44
	s_cselect_b32 s16, s12, s43
	v_lshl_add_u64 v[218:219], s[14:15], 0, v[136:137]
	s_add_i32 m0, s26, 0xc000
	ds_read_b128 v[186:189], v160
	ds_read_b128 v[190:193], v160 offset:1024
	ds_read_b128 v[194:197], v160 offset:2048
	ds_read_b128 v[198:201], v160 offset:3072
	ds_read_b128 v[202:205], v160 offset:4096
	ds_read_b128 v[206:209], v160 offset:5120
	ds_read_b128 v[210:213], v160 offset:6144
	ds_read_b128 v[214:217], v160 offset:7168
	global_load_lds_dwordx4 v[218:219], off
	v_lshl_add_u64 v[218:219], s[14:15], 0, v[138:139]
	s_add_i32 m0, s26, 0xe000
	s_nop 0
	global_load_lds_dwordx4 v[218:219], off
	s_waitcnt vmcnt(8)
	s_waitcnt lgkmcnt(0)
	s_barrier
	s_setprio 3
	s_waitcnt lgkmcnt(0)
	v_mfma_f32_16x16x32_bf16 v[124:127], v[144:147], v[186:189], 0
	v_mfma_f32_16x16x32_bf16 v[120:123], v[162:165], v[186:189], 0
	v_mfma_f32_16x16x32_bf16 v[108:111], v[144:147], v[194:197], 0
	v_mfma_f32_16x16x32_bf16 v[104:107], v[162:165], v[194:197], 0
	v_mfma_f32_16x16x32_bf16 v[96:99], v[144:147], v[202:205], 0
	v_mfma_f32_16x16x32_bf16 v[88:91], v[162:165], v[202:205], 0
	v_mfma_f32_16x16x32_bf16 v[80:83], v[144:147], v[210:213], 0
	v_mfma_f32_16x16x32_bf16 v[72:75], v[162:165], v[210:213], 0
	v_mfma_f32_16x16x32_bf16 v[124:127], v[148:151], v[190:193], v[124:127]
	v_mfma_f32_16x16x32_bf16 v[120:123], v[166:169], v[190:193], v[120:123]
	v_mfma_f32_16x16x32_bf16 v[108:111], v[148:151], v[198:201], v[108:111]
	v_mfma_f32_16x16x32_bf16 v[104:107], v[166:169], v[198:201], v[104:107]
	v_mfma_f32_16x16x32_bf16 v[96:99], v[148:151], v[206:209], v[96:99]
	v_mfma_f32_16x16x32_bf16 v[88:91], v[166:169], v[206:209], v[88:91]
	v_mfma_f32_16x16x32_bf16 v[80:83], v[148:151], v[214:217], v[80:83]
	v_mfma_f32_16x16x32_bf16 v[72:75], v[166:169], v[214:217], v[72:75]
	s_setprio 0
	s_setprio 3
	v_mfma_f32_16x16x32_bf16 v[116:119], v[170:173], v[186:189], 0
	v_mfma_f32_16x16x32_bf16 v[112:115], v[178:181], v[186:189], 0
	v_mfma_f32_16x16x32_bf16 v[100:103], v[170:173], v[194:197], 0
	v_mfma_f32_16x16x32_bf16 v[92:95], v[178:181], v[194:197], 0
	v_mfma_f32_16x16x32_bf16 v[84:87], v[170:173], v[202:205], 0
	v_mfma_f32_16x16x32_bf16 v[76:79], v[178:181], v[202:205], 0
	v_mfma_f32_16x16x32_bf16 v[68:71], v[170:173], v[210:213], 0
	v_mfma_f32_16x16x32_bf16 v[64:67], v[178:181], v[210:213], 0
	v_mfma_f32_16x16x32_bf16 v[116:119], v[174:177], v[190:193], v[116:119]
	v_mfma_f32_16x16x32_bf16 v[112:115], v[182:185], v[190:193], v[112:115]
	v_mfma_f32_16x16x32_bf16 v[100:103], v[174:177], v[198:201], v[100:103]
	v_mfma_f32_16x16x32_bf16 v[92:95], v[182:185], v[198:201], v[92:95]
	v_mfma_f32_16x16x32_bf16 v[84:87], v[174:177], v[206:209], v[84:87]
	v_mfma_f32_16x16x32_bf16 v[76:79], v[182:185], v[206:209], v[76:79]
	v_mfma_f32_16x16x32_bf16 v[68:71], v[174:177], v[214:217], v[68:71]
	v_mfma_f32_16x16x32_bf16 v[64:67], v[182:185], v[214:217], v[64:67]
	s_setprio 0
	s_barrier
	s_add_i32 s46, s37, s23
	v_lshl_add_u64 v[218:219], s[16:17], 0, v[130:131]
	s_mov_b32 m0, s46
	ds_read_b128 v[186:189], v160 offset:16384
	ds_read_b128 v[190:193], v160 offset:17408
	ds_read_b128 v[194:197], v160 offset:18432
	ds_read_b128 v[198:201], v160 offset:19456
	ds_read_b128 v[202:205], v160 offset:20480
	ds_read_b128 v[206:209], v160 offset:21504
	ds_read_b128 v[210:213], v160 offset:22528
	ds_read_b128 v[214:217], v160 offset:23552
	global_load_lds_dwordx4 v[218:219], off
	s_add_i32 m0, s46, 0x2000
	s_add_u32 s46, s16, 0xb0000
	v_lshl_add_u64 v[220:221], s[16:17], 0, v[134:135]
	s_addc_u32 s47, s17, 0
	s_add_i32 s48, s38, s23
	global_load_lds_dwordx4 v[220:221], off
	v_lshl_add_u64 v[222:223], s[46:47], 0, v[130:131]
	s_mov_b32 m0, s48
	v_lshl_add_u64 v[224:225], s[18:19], 0, v[132:133]
	global_load_lds_dwordx4 v[222:223], off
	v_lshl_add_u64 v[222:223], s[46:47], 0, v[134:135]
	s_add_i32 m0, s48, 0x2000
	s_nop 0
	global_load_lds_dwordx4 v[222:223], off
	v_lshl_add_u64 v[222:223], s[18:19], 0, v[128:129]
	s_mov_b32 m0, s26
	s_nop 0
	global_load_lds_dwordx4 v[222:223], off
	s_mov_b32 m0, s27
	s_nop 0
	global_load_lds_dwordx4 v[224:225], off
	s_waitcnt vmcnt(8)
	s_waitcnt lgkmcnt(0)
	s_barrier
; #define PG8_STAGE(bufoff, gbase, voff) do { _Pragma("unroll") for (int _i = 0; _i < 2; ++_i) \
;         __builtin_amdgcn_global_load_lds((const unsigned*)((const char*)(gbase) + (voff)[_i]), (LAS unsigned*)(lds + (bufoff) + ldsw + _i * 8192), 16, 0, 0); } while (0)
; #define PG8_LDA(dst, b, h) do { _Pragma("unroll") for (int m = 0; m < 4; ++m) _Pragma("unroll") for (int k = 0; k < 2; ++k) dst[m][k] = *(const LAS bf16x8*)(lds + PG8_SA(b, h) + aoff + m * 2048 + k * 1024); } while (0)
; #define PG8_LDB(dst, b, h) do { _Pragma("unroll") for (int n = 0; n < 2; ++n) _Pragma("unroll") for (int k = 0; k < 2; ++k) dst[n][k] = *(const LAS bf16x8*)(lds + PG8_SB(b, h) + boff + n * 2048 + k * 1024); } while (0)
; #define PG8_MMA(ai, bj, At, Bt) do { __builtin_amdgcn_s_setprio(3); _Pragma("unroll") for (int m = 0; m < 4; ++m) _Pragma("unroll") for (int n = 0; n < 2; ++n) _Pragma("unroll") for (int k = 0; k < 2; ++k) \
;         acc[ai][bj][m][n] = __builtin_amdgcn_mfma_f32_16x16x32_bf16(Bt[n][k], At[m][k], acc[ai][bj][m][n], 0, 0, 0); __builtin_amdgcn_s_setprio(0); } while (0)
; #define PG8_WAIT_V(n) asm volatile("s_waitcnt vmcnt(" #n ")" ::: "memory")
; #define PG8_WAIT_L(n) asm volatile("s_waitcnt lgkmcnt(" #n ")" ::: "memory")
; #define PG8_BAR __builtin_amdgcn_s_barrier()
; #define PG8_SCHED __builtin_amdgcn_sched_barrier(0)
; template <class Epi, bool ALIGN_EPI>
; __device__ __forceinline__ void gemm_phase(LAS unsigned char* lds, const Gemm g, const StaticOrder& S, const Epi& E) {
;     ...
;             PG8_WAIT_V(8); PG8_WAIT_L(0); PG8_BAR; PG8_MMA(1, 0, At, B0); PG8_MMA(1, 1, At, B1); PG8_BAR; PG8_SCHED;
;             PG8_LDB(B0, 1, 0); PG8_LDB(B1, 1, 1); PG8_SCHED; PG8_LDA(At, 1, 0); PG8_STAGE(PG8_SA(0, 1), a2 + hstep, voffA);
;             PG8_WAIT_V(8); PG8_WAIT_L(0); PG8_BAR; PG8_MMA(0, 0, At, B0); PG8_MMA(0, 1, At, B1); PG8_BAR; PG8_SCHED;
	s_setprio 3
	s_waitcnt lgkmcnt(0)
	v_mfma_f32_16x16x32_bf16 v[60:63], v[144:147], v[186:189], 0
	v_mfma_f32_16x16x32_bf16 v[56:59], v[162:165], v[186:189], 0
	v_mfma_f32_16x16x32_bf16 v[48:51], v[144:147], v[194:197], 0
	v_mfma_f32_16x16x32_bf16 v[40:43], v[162:165], v[194:197], 0
	v_mfma_f32_16x16x32_bf16 v[32:35], v[144:147], v[202:205], 0
	v_mfma_f32_16x16x32_bf16 v[24:27], v[162:165], v[202:205], 0
	v_mfma_f32_16x16x32_bf16 v[16:19], v[144:147], v[210:213], 0
	v_mfma_f32_16x16x32_bf16 v[8:11], v[162:165], v[210:213], 0
	v_mfma_f32_16x16x32_bf16 v[60:63], v[148:151], v[190:193], v[60:63]
	v_mfma_f32_16x16x32_bf16 v[56:59], v[166:169], v[190:193], v[56:59]
	v_mfma_f32_16x16x32_bf16 v[48:51], v[148:151], v[198:201], v[48:51]
	v_mfma_f32_16x16x32_bf16 v[40:43], v[166:169], v[198:201], v[40:43]
	v_mfma_f32_16x16x32_bf16 v[32:35], v[148:151], v[206:209], v[32:35]
	v_mfma_f32_16x16x32_bf16 v[24:27], v[166:169], v[206:209], v[24:27]
	v_mfma_f32_16x16x32_bf16 v[16:19], v[148:151], v[214:217], v[16:19]
	v_mfma_f32_16x16x32_bf16 v[8:11], v[166:169], v[214:217], v[8:11]
	s_setprio 0
	s_setprio 3
	v_mfma_f32_16x16x32_bf16 v[52:55], v[170:173], v[186:189], 0
	v_mfma_f32_16x16x32_bf16 v[44:47], v[178:181], v[186:189], 0
	v_mfma_f32_16x16x32_bf16 v[36:39], v[170:173], v[194:197], 0
	v_mfma_f32_16x16x32_bf16 v[28:31], v[178:181], v[194:197], 0
	v_mfma_f32_16x16x32_bf16 v[20:23], v[170:173], v[202:205], 0
	v_mfma_f32_16x16x32_bf16 v[12:15], v[178:181], v[202:205], 0
	v_mfma_f32_16x16x32_bf16 v[4:7], v[170:173], v[210:213], 0
	v_mfma_f32_16x16x32_bf16 v[0:3], v[178:181], v[210:213], 0
	v_mfma_f32_16x16x32_bf16 v[52:55], v[174:177], v[190:193], v[52:55]
	v_mfma_f32_16x16x32_bf16 v[44:47], v[182:185], v[190:193], v[44:47]
	v_mfma_f32_16x16x32_bf16 v[36:39], v[174:177], v[198:201], v[36:39]
	v_mfma_f32_16x16x32_bf16 v[28:31], v[182:185], v[198:201], v[28:31]
	v_mfma_f32_16x16x32_bf16 v[20:23], v[174:177], v[206:209], v[20:23]
	v_mfma_f32_16x16x32_bf16 v[12:15], v[182:185], v[206:209], v[12:15]
	v_mfma_f32_16x16x32_bf16 v[4:7], v[174:177], v[214:217], v[4:7]
	v_mfma_f32_16x16x32_bf16 v[0:3], v[182:185], v[214:217], v[0:3]
	s_setprio 0
	s_barrier
	s_add_i32 s46, 0, 0x18000
	v_add_u32_e32 v161, s46, v156
	s_add_i32 s47, 0, 0x1c000
	ds_read_b128 v[144:147], v161
	ds_read_b128 v[148:151], v161 offset:1024
	ds_read_b128 v[162:165], v161 offset:2048
	ds_read_b128 v[166:169], v161 offset:3072
	v_add_u32_e32 v161, s47, v156
	ds_read_b128 v[170:173], v161
	ds_read_b128 v[174:177], v161 offset:1024
	ds_read_b128 v[178:181], v161 offset:2048
	ds_read_b128 v[182:185], v161 offset:3072
	s_add_u32 s18, s18, 0xb0000
	s_addc_u32 s19, s19, 0
	s_mov_b32 m0, s28
	v_lshl_add_u64 v[226:227], s[18:19], 0, v[128:129]
	ds_read_b128 v[186:189], v160 offset:32768
	ds_read_b128 v[190:193], v160 offset:33792
	ds_read_b128 v[194:197], v160 offset:34816
	ds_read_b128 v[198:201], v160 offset:35840
	ds_read_b128 v[202:205], v160 offset:36864
	ds_read_b128 v[206:209], v160 offset:37888
	ds_read_b128 v[210:213], v160 offset:38912
	ds_read_b128 v[214:217], v160 offset:39936
	global_load_lds_dwordx4 v[226:227], off
	v_lshl_add_u64 v[226:227], s[18:19], 0, v[132:133]
	s_mov_b32 m0, s29
	s_nop 0
	global_load_lds_dwordx4 v[226:227], off
	s_waitcnt vmcnt(8)
	s_waitcnt lgkmcnt(0)
	s_barrier
	s_setprio 3
	s_waitcnt lgkmcnt(0)
	v_mfma_f32_16x16x32_bf16 v[124:127], v[144:147], v[186:189], v[124:127]
	v_mfma_f32_16x16x32_bf16 v[120:123], v[162:165], v[186:189], v[120:123]
	v_mfma_f32_16x16x32_bf16 v[108:111], v[144:147], v[194:197], v[108:111]
	v_mfma_f32_16x16x32_bf16 v[104:107], v[162:165], v[194:197], v[104:107]
	v_mfma_f32_16x16x32_bf16 v[96:99], v[144:147], v[202:205], v[96:99]
	v_mfma_f32_16x16x32_bf16 v[88:91], v[162:165], v[202:205], v[88:91]
	v_mfma_f32_16x16x32_bf16 v[80:83], v[144:147], v[210:213], v[80:83]
	v_mfma_f32_16x16x32_bf16 v[72:75], v[162:165], v[210:213], v[72:75]
	v_mfma_f32_16x16x32_bf16 v[124:127], v[148:151], v[190:193], v[124:127]
	v_mfma_f32_16x16x32_bf16 v[120:123], v[166:169], v[190:193], v[120:123]
	v_mfma_f32_16x16x32_bf16 v[108:111], v[148:151], v[198:201], v[108:111]
	v_mfma_f32_16x16x32_bf16 v[104:107], v[166:169], v[198:201], v[104:107]
	v_mfma_f32_16x16x32_bf16 v[96:99], v[148:151], v[206:209], v[96:99]
	v_mfma_f32_16x16x32_bf16 v[88:91], v[166:169], v[206:209], v[88:91]
	v_mfma_f32_16x16x32_bf16 v[80:83], v[148:151], v[214:217], v[80:83]
	v_mfma_f32_16x16x32_bf16 v[72:75], v[166:169], v[214:217], v[72:75]
	s_setprio 0
	s_setprio 3
	v_mfma_f32_16x16x32_bf16 v[116:119], v[170:173], v[186:189], v[116:119]
	v_mfma_f32_16x16x32_bf16 v[112:115], v[178:181], v[186:189], v[112:115]
	v_mfma_f32_16x16x32_bf16 v[100:103], v[170:173], v[194:197], v[100:103]
	v_mfma_f32_16x16x32_bf16 v[92:95], v[178:181], v[194:197], v[92:95]
	v_mfma_f32_16x16x32_bf16 v[84:87], v[170:173], v[202:205], v[84:87]
	v_mfma_f32_16x16x32_bf16 v[76:79], v[178:181], v[202:205], v[76:79]
	v_mfma_f32_16x16x32_bf16 v[68:71], v[170:173], v[210:213], v[68:71]
	v_mfma_f32_16x16x32_bf16 v[64:67], v[178:181], v[210:213], v[64:67]
	v_mfma_f32_16x16x32_bf16 v[116:119], v[174:177], v[190:193], v[116:119]
	v_mfma_f32_16x16x32_bf16 v[112:115], v[182:185], v[190:193], v[112:115]
	v_mfma_f32_16x16x32_bf16 v[100:103], v[174:177], v[198:201], v[100:103]
	v_mfma_f32_16x16x32_bf16 v[92:95], v[182:185], v[198:201], v[92:95]
	v_mfma_f32_16x16x32_bf16 v[84:87], v[174:177], v[206:209], v[84:87]
	v_mfma_f32_16x16x32_bf16 v[76:79], v[182:185], v[206:209], v[76:79]
	v_mfma_f32_16x16x32_bf16 v[68:71], v[174:177], v[214:217], v[68:71]
	v_mfma_f32_16x16x32_bf16 v[64:67], v[182:185], v[214:217], v[64:67]
	s_setprio 0
	s_barrier
; #define PG8_STAGE(bufoff, gbase, voff) do { _Pragma("unroll") for (int _i = 0; _i < 2; ++_i) \
;         __builtin_amdgcn_global_load_lds((const unsigned*)((const char*)(gbase) + (voff)[_i]), (LAS unsigned*)(lds + (bufoff) + ldsw + _i * 8192), 16, 0, 0); } while (0)
; #define PG8_LDA(dst, b, h) do { _Pragma("unroll") for (int m = 0; m < 4; ++m) _Pragma("unroll") for (int k = 0; k < 2; ++k) dst[m][k] = *(const LAS bf16x8*)(lds + PG8_SA(b, h) + aoff + m * 2048 + k * 1024); } while (0)
; #define PG8_MMA(ai, bj, At, Bt) do { __builtin_amdgcn_s_setprio(3); _Pragma("unroll") for (int m = 0; m < 4; ++m) _Pragma("unroll") for (int n = 0; n < 2; ++n) _Pragma("unroll") for (int k = 0; k < 2; ++k) \
;         acc[ai][bj][m][n] = __builtin_amdgcn_mfma_f32_16x16x32_bf16(Bt[n][k], At[m][k], acc[ai][bj][m][n], 0, 0, 0); __builtin_amdgcn_s_setprio(0); } while (0)
; #define PG8_WAIT_V(n) asm volatile("s_waitcnt vmcnt(" #n ")" ::: "memory")
; #define PG8_WAIT_L(n) asm volatile("s_waitcnt lgkmcnt(" #n ")" ::: "memory")
; #define PG8_BAR __builtin_amdgcn_s_barrier()
; #define PG8_SCHED __builtin_amdgcn_sched_barrier(0)
; template <class Epi, bool ALIGN_EPI>
; __device__ __forceinline__ void gemm_phase(LAS unsigned char* lds, const Gemm g, const StaticOrder& S, const Epi& E) {
;     ...
;             PG8_LDA(At, 1, 1); PG8_STAGE(PG8_SB(1, 0), b3, voffB); PG8_STAGE(PG8_SB(1, 1), b3 + hstep, voffB); PG8_STAGE(PG8_SA(1, 0), a3, voffA);
;             PG8_WAIT_V(8); PG8_WAIT_L(0); PG8_BAR; PG8_MMA(1, 0, At, B0); PG8_MMA(1, 1, At, B1); PG8_BAR; PG8_SCHED;
	s_add_i32 s18, s46, s23
	v_lshl_add_u64 v[218:219], v[218:219], 0, s[8:9]
	s_mov_b32 m0, s18
	ds_read_b128 v[186:189], v160 offset:49152
	ds_read_b128 v[190:193], v160 offset:50176
	ds_read_b128 v[194:197], v160 offset:51200
	ds_read_b128 v[198:201], v160 offset:52224
	ds_read_b128 v[202:205], v160 offset:53248
	ds_read_b128 v[206:209], v160 offset:54272
	ds_read_b128 v[210:213], v160 offset:55296
	ds_read_b128 v[214:217], v160 offset:56320
	global_load_lds_dwordx4 v[218:219], off
	s_add_i32 m0, s18, 0x2000
	s_add_u32 s16, s16, 0xb0080
	v_lshl_add_u64 v[218:219], v[220:221], 0, s[8:9]
	s_addc_u32 s17, s17, 0
	s_add_i32 s18, s47, s23
	global_load_lds_dwordx4 v[218:219], off
	v_lshl_add_u64 v[218:219], s[16:17], 0, v[130:131]
	s_mov_b32 m0, s18
	s_nop 0
	global_load_lds_dwordx4 v[218:219], off
	v_lshl_add_u64 v[218:219], s[16:17], 0, v[134:135]
	s_add_i32 m0, s18, 0x2000
	s_nop 0
	global_load_lds_dwordx4 v[218:219], off
	v_lshl_add_u64 v[218:219], v[222:223], 0, s[8:9]
	s_mov_b32 m0, s31
	s_nop 0
	global_load_lds_dwordx4 v[218:219], off
	v_lshl_add_u64 v[218:219], v[224:225], 0, s[8:9]
	s_mov_b32 m0, s33
	s_nop 0
	global_load_lds_dwordx4 v[218:219], off
	s_waitcnt vmcnt(8)
	s_waitcnt lgkmcnt(0)
	s_barrier
	s_setprio 3
	s_waitcnt lgkmcnt(0)
	v_mfma_f32_16x16x32_bf16 v[60:63], v[144:147], v[186:189], v[60:63]
	v_mfma_f32_16x16x32_bf16 v[56:59], v[162:165], v[186:189], v[56:59]
	v_mfma_f32_16x16x32_bf16 v[48:51], v[144:147], v[194:197], v[48:51]
	v_mfma_f32_16x16x32_bf16 v[40:43], v[162:165], v[194:197], v[40:43]
	v_mfma_f32_16x16x32_bf16 v[32:35], v[144:147], v[202:205], v[32:35]
	v_mfma_f32_16x16x32_bf16 v[24:27], v[162:165], v[202:205], v[24:27]
	v_mfma_f32_16x16x32_bf16 v[16:19], v[144:147], v[210:213], v[16:19]
	v_mfma_f32_16x16x32_bf16 v[8:11], v[162:165], v[210:213], v[8:11]
	v_mfma_f32_16x16x32_bf16 v[60:63], v[148:151], v[190:193], v[60:63]
	v_mfma_f32_16x16x32_bf16 v[56:59], v[166:169], v[190:193], v[56:59]
	v_mfma_f32_16x16x32_bf16 v[48:51], v[148:151], v[198:201], v[48:51]
	v_mfma_f32_16x16x32_bf16 v[40:43], v[166:169], v[198:201], v[40:43]
	v_mfma_f32_16x16x32_bf16 v[32:35], v[148:151], v[206:209], v[32:35]
	v_mfma_f32_16x16x32_bf16 v[24:27], v[166:169], v[206:209], v[24:27]
	v_mfma_f32_16x16x32_bf16 v[16:19], v[148:151], v[214:217], v[16:19]
	v_mfma_f32_16x16x32_bf16 v[8:11], v[166:169], v[214:217], v[8:11]
	s_setprio 0
	s_setprio 3
	v_mfma_f32_16x16x32_bf16 v[52:55], v[170:173], v[186:189], v[52:55]
	v_mfma_f32_16x16x32_bf16 v[44:47], v[178:181], v[186:189], v[44:47]
	v_mfma_f32_16x16x32_bf16 v[36:39], v[170:173], v[194:197], v[36:39]
	v_mfma_f32_16x16x32_bf16 v[28:31], v[178:181], v[194:197], v[28:31]
	v_mfma_f32_16x16x32_bf16 v[20:23], v[170:173], v[202:205], v[20:23]
	v_mfma_f32_16x16x32_bf16 v[12:15], v[178:181], v[202:205], v[12:15]
	v_mfma_f32_16x16x32_bf16 v[4:7], v[170:173], v[210:213], v[4:7]
	v_mfma_f32_16x16x32_bf16 v[0:3], v[178:181], v[210:213], v[0:3]
	v_mfma_f32_16x16x32_bf16 v[52:55], v[174:177], v[190:193], v[52:55]
	v_mfma_f32_16x16x32_bf16 v[44:47], v[182:185], v[190:193], v[44:47]
	v_mfma_f32_16x16x32_bf16 v[36:39], v[174:177], v[198:201], v[36:39]
	v_mfma_f32_16x16x32_bf16 v[28:31], v[182:185], v[198:201], v[28:31]
	v_mfma_f32_16x16x32_bf16 v[20:23], v[174:177], v[206:209], v[20:23]
	v_mfma_f32_16x16x32_bf16 v[12:15], v[182:185], v[206:209], v[12:15]
	v_mfma_f32_16x16x32_bf16 v[4:7], v[174:177], v[214:217], v[4:7]
	v_mfma_f32_16x16x32_bf16 v[0:3], v[182:185], v[214:217], v[0:3]
	s_setprio 0
	s_barrier
	s_add_i32 s45, s45, 2
	s_add_u32 s14, s14, 0x100
	s_addc_u32 s15, s15, 0
	s_add_u32 s43, s43, 0x100
	s_addc_u32 s44, s44, 0

; #define LAS __attribute__((address_space(3)))
; __global__ void __launch_bounds__(512, 2) fwd_kernel(Params p) {
;     extern __shared__ __attribute__((aligned(16))) unsigned char lds_raw[];
;     LAS unsigned char* lds = (LAS unsigned char*)lds_raw;
	.amdhsa_kernel _Z10fwd_kernel6Params
		.amdhsa_group_segment_fixed_size 0
		.amdhsa_private_segment_fixed_size 0
		.amdhsa_kernarg_size 496
		.amdhsa_user_sgpr_count 2
		.amdhsa_user_sgpr_dispatch_ptr 0
		.amdhsa_user_sgpr_queue_ptr 0
		.amdhsa_user_sgpr_kernarg_segment_ptr 1
		.amdhsa_user_sgpr_dispatch_id 0
		.amdhsa_user_sgpr_kernarg_preload_length 0
		.amdhsa_user_sgpr_kernarg_preload_offset 0
		.amdhsa_user_sgpr_private_segment_size 0
		.amdhsa_uses_dynamic_stack 0
		.amdhsa_enable_private_segment 0
		.amdhsa_system_sgpr_workgroup_id_x 1
		.amdhsa_system_sgpr_workgroup_id_y 0
		.amdhsa_system_sgpr_workgroup_id_z 0
		.amdhsa_system_sgpr_workgroup_info 0
		.amdhsa_system_vgpr_workitem_id 2
		.amdhsa_next_free_vgpr 256
		.amdhsa_next_free_sgpr 102
		.amdhsa_accum_offset 256
		.amdhsa_reserve_vcc 1
		.amdhsa_float_round_mode_32 0
		.amdhsa_float_round_mode_16_64 0
		.amdhsa_float_denorm_mode_32 3
		.amdhsa_float_denorm_mode_16_64 3
		.amdhsa_dx10_clamp 1
		.amdhsa_ieee_mode 1
		.amdhsa_fp16_overflow 0
		.amdhsa_tg_split 0
		.amdhsa_exception_fp_ieee_invalid_op 0
		.amdhsa_exception_fp_denorm_src 0
		.amdhsa_exception_fp_ieee_div_zero 0
		.amdhsa_exception_fp_ieee_overflow 0
		.amdhsa_exception_fp_ieee_underflow 0
		.amdhsa_exception_fp_ieee_inexact 0
		.amdhsa_exception_int_div_zero 0
	.end_amdhsa_kernel

amdhsa.kernels:
  - .agpr_count:     0
    .args:
      - .offset:         0
        .size:           240
        .value_kind:     by_value
      - .offset:         240
        .size:           4
        .value_kind:     hidden_block_count_x
      - .offset:         244
        .size:           4
        .value_kind:     hidden_block_count_y
      - .offset:         248
        .size:           4
        .value_kind:     hidden_block_count_z
      - .offset:         252
        .size:           2
        .value_kind:     hidden_group_size_x
      - .offset:         254
        .size:           2
        .value_kind:     hidden_group_size_y
      - .offset:         256
        .size:           2
        .value_kind:     hidden_group_size_z
      - .offset:         258
        .size:           2
        .value_kind:     hidden_remainder_x
      - .offset:         260
        .size:           2
        .value_kind:     hidden_remainder_y
      - .offset:         262
        .size:           2
        .value_kind:     hidden_remainder_z
      - .offset:         280
        .size:           8
        .value_kind:     hidden_global_offset_x
      - .offset:         288
        .size:           8
        .value_kind:     hidden_global_offset_y
      - .offset:         296
        .size:           8
        .value_kind:     hidden_global_offset_z
      - .offset:         304
        .size:           2
        .value_kind:     hidden_grid_dims
      - .offset:         328
        .size:           8
        .value_kind:     hidden_multigrid_sync_arg
      - .offset:         360
        .size:           4
        .value_kind:     hidden_dynamic_lds_size
    .group_segment_fixed_size: 0
    .kernarg_segment_align: 8
    .kernarg_segment_size: 496
    .language:       OpenCL C
    .language_version:
      - 2
      - 0
    .max_flat_workgroup_size: 512
    .name:           _Z10fwd_kernel6Params
    .private_segment_fixed_size: 0
    .sgpr_count:     108
    .sgpr_spill_count: 28
    .symbol:         _Z10fwd_kernel6Params.kd
    .uniform_work_group_size: 1
    .uses_dynamic_stack: false
    .vgpr_count:     256
    .vgpr_spill_count: 0
    .wavefront_size: 64
